# FFN-up epilogue: rare sequence-boundary fix-up blocks moved out of line (common path falls through)
# baseline (speedup 1.0000x reference)
;     __device__ __forceinline__ void operator()(f32x4 (&acc)[2][2][4][2], const Unit& u, int wr, int wc, int fr, int fq) const {
;     ...
;         for (int i = 0; i < 8; ++i) { const int tok = u.pm * 248 + 62 * (2 * (i >> 2) + wr) - 1 + 16 * (i & 3) + fr; int tc = tok < 0 ? 0 : tok; tc = tc > ntok - 1 ? ntok - 1 : tc;
;             qs[i] = *(const f32x4*)(ss + (size_t)tc * 4); }
;         asm volatile("" : "+v"(qs[0]), "+v"(qs[1]), "+v"(qs[2]), "+v"(qs[3]), "+v"(qs[4]), "+v"(qs[5]), "+v"(qs[6]), "+v"(qs[7]));
; #pragma unroll
;         for (int ai = 0; ai < 2; ++ai) {
; #pragma unroll
;             for (int m = 0; m < 4; ++m) {
;                 const f32x4 q = qs[ai * 4 + m];
;                 const float rs = rsqrtf(((q[0] + q[1]) + (q[2] + q[3])) * (1.f / DM) + EPS);
; #pragma unroll
;                 for (int bj = 0; bj < 2; ++bj)
; #pragma unroll
;                     for (int n = 0; n < 2; ++n) acc[ai][bj][m][n] *= rs;
;             }
;         }
;         __builtin_amdgcn_sched_barrier(0); asm volatile("s_nop 1");
;         const bool f15 = fr == 15, f0 = fr == 0;
;         f32x2 wq[2][2][4];
;     ...
;         CONV_WLOAD(0, 0, 0);
; #pragma unroll
;         for (int n = 0; n < 2; ++n) {
;             unsigned stash[2][4];
; #pragma unroll
;             for (int jh = 0; jh < 2; ++jh) {
;                 const int g_ = 2 * n + jh, cb_ = g_ & 1;
;                 if (g_ + 1 < 4) CONV_WLOAD(cb_ ^ 1, (g_ + 1) >> 1, (g_ + 1) & 1);
;                 f32x2 w0[2], w1[2], w2[2], bb[2], w0f[2], w2l[2];
; #pragma unroll
;                 for (int bj = 0; bj < 2; ++bj) { w0[bj] = wq[cb_][bj][0]; w1[bj] = wq[cb_][bj][1]; w2[bj] = wq[cb_][bj][2]; bb[bj] = wq[cb_][bj][3];
;                     w0f[bj] = f0 ? w0[bj] : (f32x2){0.f, 0.f}; w2l[bj] = f15 ? w2[bj] : (f32x2){0.f, 0.f}; }
; #pragma unroll
;                 for (int ai = 0; ai < 2; ++ai) {
;                     const int tokbase = u.pm * 248 + 62 * (2 * ai + wr) - 1;
; #pragma unroll
;                     for (int m = 0; m < 4; ++m) {
;                         const int rr = 16 * m + fr, tok = tokbase + rr, pos = tok & Tmask;
;                         const bool lbad = pos == 0, rbad = pos == Tmask;
;                         float uu[2][2];
; #pragma unroll
;                         for (int bj = 0; bj < 2; ++bj) {
.LBB0_789:
	s_mul_i32 s15, s31, 0xf8
	s_add_i32 s15, s15, -1
	v_add_u32_e32 v102, s15, v17
	v_add_u32_e32 v104, 16, v102
	v_add_u32_e32 v105, s1, v104
	v_med3_i32 v105, v105, 0, v242
	v_add_u32_e32 v104, s38, v104
	v_lshlrev_b32_e32 v106, 4, v105
	v_add_u32_e32 v105, 32, v102
	v_med3_i32 v104, v104, 0, v242
	v_lshlrev_b32_e32 v110, 4, v104
	v_add_u32_e32 v104, s38, v105
	s_ashr_i32 s21, s20, 31
	v_add_u32_e32 v108, 48, v102
	v_med3_i32 v104, v104, 0, v242
	s_lshl_b64 s[6:7], s[20:21], 12
	v_add_u32_e32 v103, s1, v102
	v_add_u32_e32 v107, s1, v105
	v_add_u32_e32 v109, s1, v108
	v_add_u32_e32 v102, s38, v102
	v_lshlrev_b32_e32 v111, 4, v104
	v_add_u32_e32 v104, s38, v108
	v_med3_i32 v103, v103, 0, v242
	v_med3_i32 v107, v107, 0, v242
	v_med3_i32 v109, v109, 0, v242
	v_med3_i32 v102, v102, 0, v242
	v_med3_i32 v104, v104, 0, v242
	v_lshl_add_u64 v[214:215], v[194:195], 0, s[6:7]
	v_readlane_b32 s6, v253, 24
	v_lshlrev_b32_e32 v103, 4, v103
	v_lshlrev_b32_e32 v107, 4, v107
	v_lshlrev_b32_e32 v109, 4, v109
	v_lshlrev_b32_e32 v102, 4, v102
	v_lshlrev_b32_e32 v108, 4, v104
	v_readlane_b32 s7, v253, 25
	s_nop 4
	global_load_dwordx4 v[174:177], v102, s[6:7]
	s_nop 0
	global_load_dwordx4 v[216:219], v103, s[6:7]
	s_nop 0
	global_load_dwordx4 v[166:169], v108, s[6:7]
	global_load_dwordx4 v[170:173], v111, s[6:7]
	global_load_dwordx4 v[178:181], v110, s[6:7]
	global_load_dwordx4 v[182:185], v109, s[6:7]
	global_load_dwordx4 v[186:189], v107, s[6:7]
	s_nop 0
	global_load_dwordx4 v[220:223], v106, s[6:7]
	global_load_dwordx4 v[114:117], v[214:215], off offset:1024
	global_load_dwordx4 v[110:113], v[214:215], off offset:3072
	global_load_dwordx4 v[130:133], v[214:215], off offset:512
	global_load_dwordx4 v[102:105], v[214:215], off offset:1536
	global_load_dwordx4 v[126:129], v[214:215], off offset:2560
	global_load_dwordx4 v[106:109], v[214:215], off offset:3584
	global_load_dwordx4 v[122:125], v[214:215], off
	global_load_dwordx4 v[118:121], v[214:215], off offset:2048
	s_waitcnt vmcnt(8)
	s_nop 0
	v_mov_b32_e32 v208, v217
	v_mov_b32_e32 v209, v218
	v_mov_b32_e32 v217, v219
	v_mov_b32_e32 v218, v221
	v_mov_b32_e32 v219, v222
	v_mov_b32_e32 v221, v223
	v_pk_add_f32 v[216:217], v[208:209], v[216:217]
	v_pk_add_f32 v[218:219], v[218:219], v[220:221]
	v_mov_b32_e32 v221, v216
	v_mov_b32_e32 v220, v218
	v_mov_b32_e32 v216, v219
	v_pk_add_f32 v[216:217], v[220:221], v[216:217]
	s_nop 0
	v_pk_fma_f32 v[216:217], v[216:217], s[60:61], v[202:203] op_sel_hi:[1,0,0]
	s_nop 0
	v_mul_f32_e32 v218, 0x4b800000, v217
	v_cmp_gt_f32_e64 s[6:7], s59, v217
	v_cmp_gt_f32_e32 vcc, s59, v216
	s_nop 0
	v_cndmask_b32_e64 v217, v217, v218, s[6:7]
	v_rsq_f32_e32 v217, v217
	s_nop 0
	v_mul_f32_e32 v218, 0x45800000, v217
	v_cndmask_b32_e64 v212, v217, v218, s[6:7]
	v_mul_f32_e32 v217, 0x4b800000, v216
	v_cndmask_b32_e32 v216, v216, v217, vcc
	v_rsq_f32_e32 v216, v216
	v_pk_mul_f32 v[224:225], v[154:155], v[212:213] op_sel_hi:[1,0]
	v_pk_mul_f32 v[228:229], v[162:163], v[212:213] op_sel_hi:[1,0]
	v_mul_f32_e32 v217, 0x45800000, v216
	v_cndmask_b32_e32 v154, v216, v217, vcc
	v_pk_mul_f32 v[162:163], v[158:159], v[154:155] op_sel_hi:[1,0]
	v_pk_mul_f32 v[158:159], v[150:151], v[154:155] op_sel_hi:[1,0]
	s_nop 1
	s_add_i32 s21, s15, s1
	v_add_u32_e32 v249, s21, v17
	v_and_b32_e32 v150, s35, v249
	v_cmp_eq_u32_e64 s[80:81], s35, v150
	v_cmp_eq_u32_e64 s[82:83], 0, v150
	s_or_b64 s[6:7], s[82:83], s[80:81]
	s_mov_b64 vcc, s[6:7]
	s_waitcnt vmcnt(7)
	v_cndmask_b32_e64 v251, 0, v115, s[42:43]
	v_cndmask_b32_e64 v234, 0, v114, s[42:43]
	s_waitcnt vmcnt(6)
	v_cndmask_b32_e64 v151, 0, v111, s[42:43]
	s_waitcnt vmcnt(4)
	v_fma_f32 v220, v130, v228, v102
	v_fma_f32 v221, v131, v229, v103
	s_waitcnt vmcnt(2)
	v_fma_f32 v222, v126, v224, v106
	v_fma_f32 v223, v127, v225, v107
	s_waitcnt vmcnt(1)
	v_fmac_f32_dpp v220, v228, v122 row_shr:1 row_mask:0xf bank_mask:0xf bound_ctrl:0
	v_fmac_f32_dpp v221, v229, v123 row_shr:1 row_mask:0xf bank_mask:0xf bound_ctrl:0
	s_waitcnt vmcnt(0)
	v_fmac_f32_dpp v222, v224, v118 row_shr:1 row_mask:0xf bank_mask:0xf bound_ctrl:0
	v_fmac_f32_dpp v223, v225, v119 row_shr:1 row_mask:0xf bank_mask:0xf bound_ctrl:0
	v_cndmask_b32_e64 v213, 0, v110, s[42:43]
	v_fmac_f32_dpp v220, v228, v114 row_shl:1 row_mask:0xf bank_mask:0xf bound_ctrl:0
	v_fmac_f32_dpp v221, v229, v115 row_shl:1 row_mask:0xf bank_mask:0xf bound_ctrl:0
	v_fmac_f32_dpp v222, v224, v110 row_shl:1 row_mask:0xf bank_mask:0xf bound_ctrl:0
	v_fmac_f32_dpp v223, v225, v111 row_shl:1 row_mask:0xf bank_mask:0xf bound_ctrl:0
	s_nop 0
	v_fmac_f32_dpp v220, v162, v234 row_ror:15 row_mask:0xf bank_mask:0xf bound_ctrl:0
	v_fmac_f32_dpp v221, v163, v251 row_ror:15 row_mask:0xf bank_mask:0xf bound_ctrl:0
	v_fmac_f32_dpp v222, v158, v213 row_ror:15 row_mask:0xf bank_mask:0xf bound_ctrl:0
	v_fmac_f32_dpp v223, v159, v151 row_ror:15 row_mask:0xf bank_mask:0xf bound_ctrl:0
	s_cbranch_vccnz .Lconvgate_fix_1
;     __device__ __forceinline__ void operator()(f32x4 (&acc)[2][2][4][2], const Unit& u, int wr, int wc, int fr, int fq) const {
;     ...
;         for (int ai = 0; ai < 2; ++ai) {
; #pragma unroll
;             for (int m = 0; m < 4; ++m) {
;                 const f32x4 q = qs[ai * 4 + m];
;                 const float rs = rsqrtf(((q[0] + q[1]) + (q[2] + q[3])) * (1.f / DM) + EPS);
; #pragma unroll
;                 for (int bj = 0; bj < 2; ++bj)
; #pragma unroll
;                     for (int n = 0; n < 2; ++n) acc[ai][bj][m][n] *= rs;
;             }
;         }
;         __builtin_amdgcn_sched_barrier(0); asm volatile("s_nop 1");
;         const bool f15 = fr == 15, f0 = fr == 0;
;         f32x2 wq[2][2][4];
;     ...
;         CONV_WLOAD(0, 0, 0);
; #pragma unroll
;         for (int n = 0; n < 2; ++n) {
;             unsigned stash[2][4];
; #pragma unroll
;             for (int jh = 0; jh < 2; ++jh) {
;                 const int g_ = 2 * n + jh, cb_ = g_ & 1;
;                 if (g_ + 1 < 4) CONV_WLOAD(cb_ ^ 1, (g_ + 1) >> 1, (g_ + 1) & 1);
;                 f32x2 w0[2], w1[2], w2[2], bb[2], w0f[2], w2l[2];
; #pragma unroll
;                 for (int bj = 0; bj < 2; ++bj) { w0[bj] = wq[cb_][bj][0]; w1[bj] = wq[cb_][bj][1]; w2[bj] = wq[cb_][bj][2]; bb[bj] = wq[cb_][bj][3];
;                     w0f[bj] = f0 ? w0[bj] : (f32x2){0.f, 0.f}; w2l[bj] = f15 ? w2[bj] : (f32x2){0.f, 0.f}; }
; #pragma unroll
;                 for (int ai = 0; ai < 2; ++ai) {
;                     const int tokbase = u.pm * 248 + 62 * (2 * ai + wr) - 1;
; #pragma unroll
;                     for (int m = 0; m < 4; ++m) {
;                         const int rr = 16 * m + fr, tok = tokbase + rr, pos = tok & Tmask;
;                         const bool lbad = pos == 0, rbad = pos == Tmask;
;                         float uu[2][2];
; #pragma unroll
;                         for (int bj = 0; bj < 2; ++bj) {
;                             const f32x4 c = acc[ai][bj][m][n], cm = acc[ai][bj][m > 0 ? m - 1 : m][n], cp = acc[ai][bj][m < 3 ? m + 1 : m][n];
; #pragma unroll
;                             for (int jj = 0; jj < 2; ++jj) {
;                                 const int j = 2 * jh + jj;
;                                 float t = bb[bj][jj] + w1[bj][jj] * c[j];
;                                 fmac_shr1(t, c[j], w0[bj][jj]);
;                                 fmac_shl1(t, c[j], w2[bj][jj]);
.LBB0_791:
	v_mov_b32_e32 v208, v187
	v_mov_b32_e32 v209, v188
	v_mov_b32_e32 v187, v189
	v_mov_b32_e32 v188, v183
	v_mov_b32_e32 v189, v184
	v_mov_b32_e32 v183, v185
	v_pk_add_f32 v[186:187], v[208:209], v[186:187]
	v_pk_add_f32 v[182:183], v[188:189], v[182:183]
	v_mov_b32_e32 v185, v186
	v_mov_b32_e32 v184, v182
	v_mov_b32_e32 v186, v183
	v_pk_add_f32 v[182:183], v[184:185], v[186:187]
	s_mov_b32 s31, 0x10000
	v_pk_fma_f32 v[182:183], v[182:183], s[60:61], v[202:203] op_sel_hi:[1,0,0]
	v_cndmask_b32_e64 v250, 0, v123, s[44:45]
	v_mul_f32_e32 v150, 0x4b800000, v183
	v_cmp_gt_f32_e32 vcc, s59, v183
	v_cmp_gt_f32_e64 s[52:53], s59, v182
	v_cndmask_b32_e64 v233, 0, v122, s[44:45]
	v_cndmask_b32_e32 v150, v183, v150, vcc
	v_rsq_f32_e32 v150, v150
	s_nop 0
	v_mul_f32_e32 v155, 0x45800000, v150
	v_cndmask_b32_e32 v150, v150, v155, vcc
	v_pk_mul_f32 v[226:227], v[146:147], v[150:151] op_sel_hi:[1,0]
	v_pk_mul_f32 v[146:147], v[142:143], v[150:151] op_sel_hi:[1,0]
	v_cndmask_b32_e64 v143, 0, v119, s[44:45]
	v_cndmask_b32_e64 v155, 0, v118, s[44:45]
	v_add_u32_e32 v248, s21, v244
	v_and_b32_e32 v142, s35, v248
	v_fma_f32 v216, v130, v162, v102
	v_fma_f32 v217, v131, v163, v103
	v_fma_f32 v218, v126, v158, v106
	v_fma_f32 v219, v127, v159, v107
	v_fmac_f32_dpp v216, v162, v122 row_shr:1 row_mask:0xf bank_mask:0xf bound_ctrl:0
	v_fmac_f32_dpp v217, v163, v123 row_shr:1 row_mask:0xf bank_mask:0xf bound_ctrl:0
	v_fmac_f32_dpp v218, v158, v118 row_shr:1 row_mask:0xf bank_mask:0xf bound_ctrl:0
	v_fmac_f32_dpp v219, v159, v119 row_shr:1 row_mask:0xf bank_mask:0xf bound_ctrl:0
	v_cmp_eq_u32_e64 s[76:77], s35, v142
	v_cmp_eq_u32_e64 s[78:79], 0, v142
	v_fmac_f32_dpp v216, v162, v114 row_shl:1 row_mask:0xf bank_mask:0xf bound_ctrl:0
	v_fmac_f32_dpp v217, v163, v115 row_shl:1 row_mask:0xf bank_mask:0xf bound_ctrl:0
	v_fmac_f32_dpp v218, v158, v110 row_shl:1 row_mask:0xf bank_mask:0xf bound_ctrl:0
	v_fmac_f32_dpp v219, v159, v111 row_shl:1 row_mask:0xf bank_mask:0xf bound_ctrl:0
	s_or_b64 s[90:91], s[78:79], s[76:77]
	v_fmac_f32_dpp v216, v228, v233 row_ror:1 row_mask:0xf bank_mask:0xf bound_ctrl:0
	v_fmac_f32_dpp v217, v229, v250 row_ror:1 row_mask:0xf bank_mask:0xf bound_ctrl:0
	v_fmac_f32_dpp v218, v224, v155 row_ror:1 row_mask:0xf bank_mask:0xf bound_ctrl:0
	v_fmac_f32_dpp v219, v225, v143 row_ror:1 row_mask:0xf bank_mask:0xf bound_ctrl:0
	s_mov_b64 vcc, s[90:91]
	v_fmac_f32_dpp v216, v226, v234 row_ror:15 row_mask:0xf bank_mask:0xf bound_ctrl:0
	v_fmac_f32_dpp v217, v227, v251 row_ror:15 row_mask:0xf bank_mask:0xf bound_ctrl:0
	v_fmac_f32_dpp v218, v146, v213 row_ror:15 row_mask:0xf bank_mask:0xf bound_ctrl:0
	v_fmac_f32_dpp v219, v147, v151 row_ror:15 row_mask:0xf bank_mask:0xf bound_ctrl:0
	s_cbranch_vccnz .Lconvgate_fix_2
.LBB0_793:
	v_mul_f32_e32 v142, 0x4b800000, v182
	v_cndmask_b32_e64 v142, v182, v142, s[52:53]
	v_rsq_f32_e32 v142, v142
	s_nop 0
	v_mul_f32_e32 v182, 0x45800000, v142
	v_cndmask_b32_e64 v142, v142, v182, s[52:53]
	v_pk_mul_f32 v[138:139], v[138:139], v[142:143] op_sel_hi:[1,0]
	v_pk_mul_f32 v[134:135], v[134:135], v[142:143] op_sel_hi:[1,0]
	v_add_u32_e32 v225, s21, v245
	v_and_b32_e32 v182, s35, v225
	v_fma_f32 v186, v130, v226, v102
	v_fma_f32 v187, v131, v227, v103
	v_fma_f32 v188, v126, v146, v106
	v_fma_f32 v189, v127, v147, v107
	v_fmac_f32_dpp v186, v226, v122 row_shr:1 row_mask:0xf bank_mask:0xf bound_ctrl:0
	v_fmac_f32_dpp v187, v227, v123 row_shr:1 row_mask:0xf bank_mask:0xf bound_ctrl:0
	v_fmac_f32_dpp v188, v146, v118 row_shr:1 row_mask:0xf bank_mask:0xf bound_ctrl:0
	v_fmac_f32_dpp v189, v147, v119 row_shr:1 row_mask:0xf bank_mask:0xf bound_ctrl:0
	v_cmp_eq_u32_e64 s[72:73], s35, v182
	v_cmp_eq_u32_e64 s[74:75], 0, v182
	v_fmac_f32_dpp v186, v226, v114 row_shl:1 row_mask:0xf bank_mask:0xf bound_ctrl:0
	v_fmac_f32_dpp v187, v227, v115 row_shl:1 row_mask:0xf bank_mask:0xf bound_ctrl:0
	v_fmac_f32_dpp v188, v146, v110 row_shl:1 row_mask:0xf bank_mask:0xf bound_ctrl:0
	v_fmac_f32_dpp v189, v147, v111 row_shl:1 row_mask:0xf bank_mask:0xf bound_ctrl:0
	s_or_b64 s[88:89], s[74:75], s[72:73]
	v_fmac_f32_dpp v186, v162, v233 row_ror:1 row_mask:0xf bank_mask:0xf bound_ctrl:0
	v_fmac_f32_dpp v187, v163, v250 row_ror:1 row_mask:0xf bank_mask:0xf bound_ctrl:0
	v_fmac_f32_dpp v188, v158, v155 row_ror:1 row_mask:0xf bank_mask:0xf bound_ctrl:0
	v_fmac_f32_dpp v189, v159, v143 row_ror:1 row_mask:0xf bank_mask:0xf bound_ctrl:0
	s_mov_b64 vcc, s[88:89]
	v_fmac_f32_dpp v186, v138, v234 row_ror:15 row_mask:0xf bank_mask:0xf bound_ctrl:0
	v_fmac_f32_dpp v187, v139, v251 row_ror:15 row_mask:0xf bank_mask:0xf bound_ctrl:0
	v_fmac_f32_dpp v188, v134, v213 row_ror:15 row_mask:0xf bank_mask:0xf bound_ctrl:0
	v_fmac_f32_dpp v189, v135, v151 row_ror:15 row_mask:0xf bank_mask:0xf bound_ctrl:0
	s_cbranch_vccnz .Lconvgate_fix_3
.LBB0_795:
	v_add_u32_e32 v224, s21, v246
	v_and_b32_e32 v158, s35, v224
	v_fma_f32 v182, v130, v138, v102
	v_fma_f32 v183, v131, v139, v103
	v_fma_f32 v184, v126, v134, v106
	v_fma_f32 v185, v127, v135, v107
	v_cmp_eq_u32_e64 s[68:69], s35, v158
	v_cmp_eq_u32_e64 s[70:71], 0, v158
	v_fmac_f32_dpp v182, v138, v122 row_shr:1 row_mask:0xf bank_mask:0xf bound_ctrl:0
	v_fmac_f32_dpp v183, v139, v123 row_shr:1 row_mask:0xf bank_mask:0xf bound_ctrl:0
	v_fmac_f32_dpp v184, v134, v118 row_shr:1 row_mask:0xf bank_mask:0xf bound_ctrl:0
	v_fmac_f32_dpp v185, v135, v119 row_shr:1 row_mask:0xf bank_mask:0xf bound_ctrl:0
	s_or_b64 s[96:97], s[70:71], s[68:69]
	v_fmac_f32_dpp v182, v138, v114 row_shl:1 row_mask:0xf bank_mask:0xf bound_ctrl:0
	v_fmac_f32_dpp v183, v139, v115 row_shl:1 row_mask:0xf bank_mask:0xf bound_ctrl:0
	v_fmac_f32_dpp v184, v134, v110 row_shl:1 row_mask:0xf bank_mask:0xf bound_ctrl:0
	v_fmac_f32_dpp v185, v135, v111 row_shl:1 row_mask:0xf bank_mask:0xf bound_ctrl:0
	s_mov_b64 vcc, s[96:97]
	v_fmac_f32_dpp v182, v226, v233 row_ror:1 row_mask:0xf bank_mask:0xf bound_ctrl:0
	v_fmac_f32_dpp v183, v227, v250 row_ror:1 row_mask:0xf bank_mask:0xf bound_ctrl:0
	v_fmac_f32_dpp v184, v146, v155 row_ror:1 row_mask:0xf bank_mask:0xf bound_ctrl:0
	v_fmac_f32_dpp v185, v147, v143 row_ror:1 row_mask:0xf bank_mask:0xf bound_ctrl:0
	s_cbranch_vccnz .Lconvgate_fix_4
;     __device__ __forceinline__ void operator()(f32x4 (&acc)[2][2][4][2], const Unit& u, int wr, int wc, int fr, int fq) const {
;     ...
;         for (int ai = 0; ai < 2; ++ai) {
; #pragma unroll
;             for (int m = 0; m < 4; ++m) {
;                 const f32x4 q = qs[ai * 4 + m];
;                 const float rs = rsqrtf(((q[0] + q[1]) + (q[2] + q[3])) * (1.f / DM) + EPS);
; #pragma unroll
;                 for (int bj = 0; bj < 2; ++bj)
; #pragma unroll
;                     for (int n = 0; n < 2; ++n) acc[ai][bj][m][n] *= rs;
;             }
;         }
;         __builtin_amdgcn_sched_barrier(0); asm volatile("s_nop 1");
;         const bool f15 = fr == 15, f0 = fr == 0;
;         f32x2 wq[2][2][4];
;     ...
;         CONV_WLOAD(0, 0, 0);
; #pragma unroll
;         for (int n = 0; n < 2; ++n) {
;             unsigned stash[2][4];
; #pragma unroll
;             for (int jh = 0; jh < 2; ++jh) {
;                 const int g_ = 2 * n + jh, cb_ = g_ & 1;
;                 if (g_ + 1 < 4) CONV_WLOAD(cb_ ^ 1, (g_ + 1) >> 1, (g_ + 1) & 1);
;                 f32x2 w0[2], w1[2], w2[2], bb[2], w0f[2], w2l[2];
; #pragma unroll
;                 for (int bj = 0; bj < 2; ++bj) { w0[bj] = wq[cb_][bj][0]; w1[bj] = wq[cb_][bj][1]; w2[bj] = wq[cb_][bj][2]; bb[bj] = wq[cb_][bj][3];
;                     w0f[bj] = f0 ? w0[bj] : (f32x2){0.f, 0.f}; w2l[bj] = f15 ? w2[bj] : (f32x2){0.f, 0.f}; }
; #pragma unroll
;                 for (int ai = 0; ai < 2; ++ai) {
;                     const int tokbase = u.pm * 248 + 62 * (2 * ai + wr) - 1;
; #pragma unroll
;                     for (int m = 0; m < 4; ++m) {
;                         const int rr = 16 * m + fr, tok = tokbase + rr, pos = tok & Tmask;
;                         const bool lbad = pos == 0, rbad = pos == Tmask;
;                         float uu[2][2];
; #pragma unroll
;                         for (int bj = 0; bj < 2; ++bj) {
;                             const f32x4 c = acc[ai][bj][m][n], cm = acc[ai][bj][m > 0 ? m - 1 : m][n], cp = acc[ai][bj][m < 3 ? m + 1 : m][n];
; #pragma unroll
;                             for (int jj = 0; jj < 2; ++jj) {
;                                 const int j = 2 * jh + jj;
;                                 float t = bb[bj][jj] + w1[bj][jj] * c[j];
;                                 fmac_shr1(t, c[j], w0[bj][jj]);
;                                 fmac_shl1(t, c[j], w2[bj][jj]);
.LBB0_797:
	v_mov_b32_e32 v134, v175
	v_mov_b32_e32 v135, v176
	v_mov_b32_e32 v175, v177
	v_mov_b32_e32 v138, v179
	v_mov_b32_e32 v139, v180
	v_mov_b32_e32 v179, v181
	v_pk_add_f32 v[134:135], v[134:135], v[174:175]
	v_pk_add_f32 v[138:139], v[138:139], v[178:179]
	v_mov_b32_e32 v147, v134
	v_mov_b32_e32 v146, v138
	v_mov_b32_e32 v134, v139
	v_pk_add_f32 v[134:135], v[146:147], v[134:135]
	s_nop 0
	v_pk_fma_f32 v[134:135], v[134:135], s[60:61], v[202:203] op_sel_hi:[1,0,0]
	s_nop 0
	v_mul_f32_e32 v138, 0x4b800000, v135
	v_cmp_gt_f32_e32 vcc, s59, v135
	v_mul_f32_e32 v139, 0x4b800000, v134
	v_cmp_gt_f32_e64 s[52:53], s59, v134
	v_cndmask_b32_e32 v135, v135, v138, vcc
	v_rsq_f32_e32 v135, v135
	v_cndmask_b32_e64 v134, v134, v139, s[52:53]
	v_rsq_f32_e32 v158, v134
	v_mul_f32_e32 v138, 0x45800000, v135
	v_cndmask_b32_e32 v134, v135, v138, vcc
	v_pk_mul_f32 v[138:139], v[90:91], v[134:135] op_sel_hi:[1,0]
	v_mul_f32_e32 v90, 0x45800000, v158
	v_cndmask_b32_e64 v90, v158, v90, s[52:53]
	v_pk_mul_f32 v[146:147], v[98:99], v[134:135] op_sel_hi:[1,0]
	v_pk_mul_f32 v[98:99], v[94:95], v[90:91] op_sel_hi:[1,0]
	v_pk_mul_f32 v[94:95], v[86:87], v[90:91] op_sel_hi:[1,0]
	s_add_i32 s15, s15, s38
	v_add_u32_e32 v178, s15, v17
	v_and_b32_e32 v86, s35, v178
	v_fma_f32 v174, v130, v146, v102
	v_fma_f32 v175, v131, v147, v103
	v_fma_f32 v176, v126, v138, v106
	v_fma_f32 v177, v127, v139, v107
	v_cmp_eq_u32_e64 s[64:65], s35, v86
	v_cmp_eq_u32_e64 s[66:67], 0, v86
	v_fmac_f32_dpp v174, v146, v122 row_shr:1 row_mask:0xf bank_mask:0xf bound_ctrl:0
	v_fmac_f32_dpp v175, v147, v123 row_shr:1 row_mask:0xf bank_mask:0xf bound_ctrl:0
	v_fmac_f32_dpp v176, v138, v118 row_shr:1 row_mask:0xf bank_mask:0xf bound_ctrl:0
	v_fmac_f32_dpp v177, v139, v119 row_shr:1 row_mask:0xf bank_mask:0xf bound_ctrl:0
	s_or_b64 s[94:95], s[66:67], s[64:65]
	v_fmac_f32_dpp v174, v146, v114 row_shl:1 row_mask:0xf bank_mask:0xf bound_ctrl:0
	v_fmac_f32_dpp v175, v147, v115 row_shl:1 row_mask:0xf bank_mask:0xf bound_ctrl:0
	v_fmac_f32_dpp v176, v138, v110 row_shl:1 row_mask:0xf bank_mask:0xf bound_ctrl:0
	v_fmac_f32_dpp v177, v139, v111 row_shl:1 row_mask:0xf bank_mask:0xf bound_ctrl:0
	s_mov_b64 vcc, s[94:95]
	v_fmac_f32_dpp v174, v98, v234 row_ror:15 row_mask:0xf bank_mask:0xf bound_ctrl:0
	v_fmac_f32_dpp v175, v99, v251 row_ror:15 row_mask:0xf bank_mask:0xf bound_ctrl:0
	v_fmac_f32_dpp v176, v94, v213 row_ror:15 row_mask:0xf bank_mask:0xf bound_ctrl:0
	v_fmac_f32_dpp v177, v95, v151 row_ror:15 row_mask:0xf bank_mask:0xf bound_ctrl:0
	s_cbranch_vccnz .Lconvgate_fix_5
.LBB0_799:
	v_mov_b32_e32 v86, v171
	v_mov_b32_e32 v87, v172
	v_mov_b32_e32 v171, v173
	v_mov_b32_e32 v158, v167
	v_mov_b32_e32 v159, v168
	v_mov_b32_e32 v167, v169
	v_pk_add_f32 v[86:87], v[86:87], v[170:171]
	v_pk_add_f32 v[158:159], v[158:159], v[166:167]
	v_mov_b32_e32 v163, v86
	v_mov_b32_e32 v162, v158
	v_mov_b32_e32 v86, v159
	v_pk_add_f32 v[86:87], v[162:163], v[86:87]
	s_nop 0
	v_pk_fma_f32 v[168:169], v[86:87], s[60:61], v[202:203] op_sel_hi:[1,0,0]
	s_nop 0
	v_mul_f32_e32 v86, 0x4b800000, v169
	v_cmp_gt_f32_e32 vcc, s59, v169
	v_cmp_gt_f32_e64 s[52:53], s59, v168
	s_nop 0
	v_cndmask_b32_e32 v86, v169, v86, vcc
	v_rsq_f32_e32 v86, v86
	s_nop 0
	v_mul_f32_e32 v87, 0x45800000, v86
	v_cndmask_b32_e32 v86, v86, v87, vcc
	v_pk_mul_f32 v[166:167], v[82:83], v[86:87] op_sel_hi:[1,0]
	v_pk_mul_f32 v[78:79], v[78:79], v[86:87] op_sel_hi:[1,0]
	v_add_u32_e32 v170, s15, v244
	v_and_b32_e32 v82, s35, v170
	v_fma_f32 v158, v130, v98, v102
	v_fma_f32 v159, v131, v99, v103
	v_fma_f32 v162, v126, v94, v106
	v_fma_f32 v163, v127, v95, v107
	v_fmac_f32_dpp v158, v98, v122 row_shr:1 row_mask:0xf bank_mask:0xf bound_ctrl:0
	v_fmac_f32_dpp v159, v99, v123 row_shr:1 row_mask:0xf bank_mask:0xf bound_ctrl:0
	v_fmac_f32_dpp v162, v94, v118 row_shr:1 row_mask:0xf bank_mask:0xf bound_ctrl:0
	v_fmac_f32_dpp v163, v95, v119 row_shr:1 row_mask:0xf bank_mask:0xf bound_ctrl:0
	v_cmp_eq_u32_e64 s[60:61], s35, v82
	v_cmp_eq_u32_e64 s[62:63], 0, v82
	v_fmac_f32_dpp v158, v98, v114 row_shl:1 row_mask:0xf bank_mask:0xf bound_ctrl:0
	v_fmac_f32_dpp v159, v99, v115 row_shl:1 row_mask:0xf bank_mask:0xf bound_ctrl:0
	v_fmac_f32_dpp v162, v94, v110 row_shl:1 row_mask:0xf bank_mask:0xf bound_ctrl:0
	v_fmac_f32_dpp v163, v95, v111 row_shl:1 row_mask:0xf bank_mask:0xf bound_ctrl:0
	s_or_b64 s[86:87], s[62:63], s[60:61]
	v_fmac_f32_dpp v158, v146, v233 row_ror:1 row_mask:0xf bank_mask:0xf bound_ctrl:0
	v_fmac_f32_dpp v159, v147, v250 row_ror:1 row_mask:0xf bank_mask:0xf bound_ctrl:0
	v_fmac_f32_dpp v162, v138, v155 row_ror:1 row_mask:0xf bank_mask:0xf bound_ctrl:0
	v_fmac_f32_dpp v163, v139, v143 row_ror:1 row_mask:0xf bank_mask:0xf bound_ctrl:0
	s_mov_b64 vcc, s[86:87]
	v_fmac_f32_dpp v158, v166, v234 row_ror:15 row_mask:0xf bank_mask:0xf bound_ctrl:0
	v_fmac_f32_dpp v159, v167, v251 row_ror:15 row_mask:0xf bank_mask:0xf bound_ctrl:0
	v_fmac_f32_dpp v162, v78, v213 row_ror:15 row_mask:0xf bank_mask:0xf bound_ctrl:0
	v_fmac_f32_dpp v163, v79, v151 row_ror:15 row_mask:0xf bank_mask:0xf bound_ctrl:0
	s_cbranch_vccnz .Lconvgate_fix_6
;     __device__ __forceinline__ void operator()(f32x4 (&acc)[2][2][4][2], const Unit& u, int wr, int wc, int fr, int fq) const {
;     ...
;         CONV_WLOAD(0, 0, 0);
; #pragma unroll
;         for (int n = 0; n < 2; ++n) {
;             unsigned stash[2][4];
; #pragma unroll
;             for (int jh = 0; jh < 2; ++jh) {
;                 const int g_ = 2 * n + jh, cb_ = g_ & 1;
;                 if (g_ + 1 < 4) CONV_WLOAD(cb_ ^ 1, (g_ + 1) >> 1, (g_ + 1) & 1);
;                 f32x2 w0[2], w1[2], w2[2], bb[2], w0f[2], w2l[2];
; #pragma unroll
;                 for (int bj = 0; bj < 2; ++bj) { w0[bj] = wq[cb_][bj][0]; w1[bj] = wq[cb_][bj][1]; w2[bj] = wq[cb_][bj][2]; bb[bj] = wq[cb_][bj][3];
;                     w0f[bj] = f0 ? w0[bj] : (f32x2){0.f, 0.f}; w2l[bj] = f15 ? w2[bj] : (f32x2){0.f, 0.f}; }
; #pragma unroll
;                 for (int ai = 0; ai < 2; ++ai) {
;                     const int tokbase = u.pm * 248 + 62 * (2 * ai + wr) - 1;
; #pragma unroll
;                     for (int m = 0; m < 4; ++m) {
;                         const int rr = 16 * m + fr, tok = tokbase + rr, pos = tok & Tmask;
;                         const bool lbad = pos == 0, rbad = pos == Tmask;
;                         float uu[2][2];
; #pragma unroll
;                         for (int bj = 0; bj < 2; ++bj) {
;                             const f32x4 c = acc[ai][bj][m][n], cm = acc[ai][bj][m > 0 ? m - 1 : m][n], cp = acc[ai][bj][m < 3 ? m + 1 : m][n];
; #pragma unroll
;                             for (int jj = 0; jj < 2; ++jj) {
;                                 const int j = 2 * jh + jj;
;                                 float t = bb[bj][jj] + w1[bj][jj] * c[j];
;                                 fmac_shr1(t, c[j], w0[bj][jj]);
;                                 fmac_shl1(t, c[j], w2[bj][jj]);
;                                 if (m > 0) fmac_ror1(t, cm[j], w0f[bj][jj]);
;                                 if (m < 3) fmac_ror15(t, cp[j], w2l[bj][jj]);
;                                 uu[bj][jj] = t;
;                             }
;                         }
;                         if (__any(lbad | rbad)) {
.LBB0_801:
	v_mul_f32_e32 v82, 0x4b800000, v168
	v_cndmask_b32_e64 v82, v168, v82, s[52:53]
	v_rsq_f32_e32 v82, v82
	s_nop 0
	v_mul_f32_e32 v83, 0x45800000, v82
	v_cndmask_b32_e64 v82, v82, v83, s[52:53]
	v_pk_mul_f32 v[74:75], v[74:75], v[82:83] op_sel_hi:[1,0]
	v_pk_mul_f32 v[70:71], v[70:71], v[82:83] op_sel_hi:[1,0]
	v_add_u32_e32 v169, s15, v245
	v_and_b32_e32 v83, s35, v169
	v_fma_f32 v138, v130, v166, v102
	v_fma_f32 v139, v131, v167, v103
	v_fma_f32 v146, v126, v78, v106
	v_fma_f32 v147, v127, v79, v107
	v_fmac_f32_dpp v138, v166, v122 row_shr:1 row_mask:0xf bank_mask:0xf bound_ctrl:0
	v_fmac_f32_dpp v139, v167, v123 row_shr:1 row_mask:0xf bank_mask:0xf bound_ctrl:0
	v_fmac_f32_dpp v146, v78, v118 row_shr:1 row_mask:0xf bank_mask:0xf bound_ctrl:0
	v_fmac_f32_dpp v147, v79, v119 row_shr:1 row_mask:0xf bank_mask:0xf bound_ctrl:0
	v_cmp_eq_u32_e64 s[56:57], s35, v83
	v_cmp_eq_u32_e64 s[58:59], 0, v83
	v_fmac_f32_dpp v138, v166, v114 row_shl:1 row_mask:0xf bank_mask:0xf bound_ctrl:0
	v_fmac_f32_dpp v139, v167, v115 row_shl:1 row_mask:0xf bank_mask:0xf bound_ctrl:0
	v_fmac_f32_dpp v146, v78, v110 row_shl:1 row_mask:0xf bank_mask:0xf bound_ctrl:0
	v_fmac_f32_dpp v147, v79, v111 row_shl:1 row_mask:0xf bank_mask:0xf bound_ctrl:0
	s_or_b64 s[84:85], s[58:59], s[56:57]
	v_fmac_f32_dpp v138, v98, v233 row_ror:1 row_mask:0xf bank_mask:0xf bound_ctrl:0
	v_fmac_f32_dpp v139, v99, v250 row_ror:1 row_mask:0xf bank_mask:0xf bound_ctrl:0
	v_fmac_f32_dpp v146, v94, v155 row_ror:1 row_mask:0xf bank_mask:0xf bound_ctrl:0
	v_fmac_f32_dpp v147, v95, v143 row_ror:1 row_mask:0xf bank_mask:0xf bound_ctrl:0
	s_mov_b64 vcc, s[84:85]
	v_fmac_f32_dpp v138, v74, v234 row_ror:15 row_mask:0xf bank_mask:0xf bound_ctrl:0
	v_fmac_f32_dpp v139, v75, v251 row_ror:15 row_mask:0xf bank_mask:0xf bound_ctrl:0
	v_fmac_f32_dpp v146, v70, v213 row_ror:15 row_mask:0xf bank_mask:0xf bound_ctrl:0
	v_fmac_f32_dpp v147, v71, v151 row_ror:15 row_mask:0xf bank_mask:0xf bound_ctrl:0
	s_cbranch_vccnz .Lconvgate_fix_7
.LBB0_803:
	v_add_u32_e32 v168, s15, v246
	v_and_b32_e32 v83, s35, v168
	v_fma_f32 v130, v130, v74, v102
	v_fma_f32 v131, v131, v75, v103
	v_fma_f32 v126, v126, v70, v106
	v_fma_f32 v127, v127, v71, v107
	v_cmp_eq_u32_e64 s[52:53], s35, v83
	v_cmp_eq_u32_e64 s[54:55], 0, v83
	v_fmac_f32_dpp v130, v74, v122 row_shr:1 row_mask:0xf bank_mask:0xf bound_ctrl:0
	v_fmac_f32_dpp v131, v75, v123 row_shr:1 row_mask:0xf bank_mask:0xf bound_ctrl:0
	v_fmac_f32_dpp v126, v70, v118 row_shr:1 row_mask:0xf bank_mask:0xf bound_ctrl:0
	v_fmac_f32_dpp v127, v71, v119 row_shr:1 row_mask:0xf bank_mask:0xf bound_ctrl:0
	s_or_b64 s[92:93], s[54:55], s[52:53]
	v_fmac_f32_dpp v130, v74, v114 row_shl:1 row_mask:0xf bank_mask:0xf bound_ctrl:0
	v_fmac_f32_dpp v131, v75, v115 row_shl:1 row_mask:0xf bank_mask:0xf bound_ctrl:0
	v_fmac_f32_dpp v126, v70, v110 row_shl:1 row_mask:0xf bank_mask:0xf bound_ctrl:0
	v_fmac_f32_dpp v127, v71, v111 row_shl:1 row_mask:0xf bank_mask:0xf bound_ctrl:0
	s_mov_b64 vcc, s[92:93]
	v_fmac_f32_dpp v130, v166, v233 row_ror:1 row_mask:0xf bank_mask:0xf bound_ctrl:0
	v_fmac_f32_dpp v131, v167, v250 row_ror:1 row_mask:0xf bank_mask:0xf bound_ctrl:0
	v_fmac_f32_dpp v126, v78, v155 row_ror:1 row_mask:0xf bank_mask:0xf bound_ctrl:0
	v_fmac_f32_dpp v127, v79, v143 row_ror:1 row_mask:0xf bank_mask:0xf bound_ctrl:0
	s_cbranch_vccnz .Lconvgate_fix_8
.LBB0_805:
	v_pk_mul_f32 v[164:165], v[164:165], v[212:213] op_sel_hi:[1,0]
	v_pk_mul_f32 v[156:157], v[156:157], v[212:213] op_sel_hi:[1,0]
	v_pk_mul_f32 v[122:123], v[160:161], v[154:155] op_sel_hi:[1,0]
	v_pk_mul_f32 v[118:119], v[152:153], v[154:155] op_sel_hi:[1,0]
	global_load_dwordx2 v[102:103], v[214:215], off offset:16
	global_load_dwordx2 v[114:115], v[214:215], off offset:528
	global_load_dwordx2 v[106:107], v[214:215], off offset:1040
	global_load_dwordx2 v[70:71], v[214:215], off offset:1552
	global_load_dwordx2 v[94:95], v[214:215], off offset:2064
	global_load_dwordx2 v[110:111], v[214:215], off offset:2576
	global_load_dwordx2 v[98:99], v[214:215], off offset:3088
	global_load_dwordx2 v[74:75], v[214:215], off offset:3600
	v_fma_f32 v152, v132, v164, v104
	v_fma_f32 v153, v133, v165, v105
	v_fma_f32 v160, v156, v128, v108
	v_fma_f32 v161, v157, v129, v109
	v_fmac_f32_dpp v152, v164, v124 row_shr:1 row_mask:0xf bank_mask:0xf bound_ctrl:0
	v_fmac_f32_dpp v153, v165, v125 row_shr:1 row_mask:0xf bank_mask:0xf bound_ctrl:0
	v_fmac_f32_dpp v160, v156, v120 row_shr:1 row_mask:0xf bank_mask:0xf bound_ctrl:0
	v_fmac_f32_dpp v161, v157, v121 row_shr:1 row_mask:0xf bank_mask:0xf bound_ctrl:0
	v_cndmask_b32_e64 v167, 0, 1, s[6:7]
	v_cndmask_b32_e64 v151, 0, v117, s[42:43]
	v_cndmask_b32_e64 v171, 0, v116, s[42:43]
	v_cndmask_b32_e64 v83, 0, v113, s[42:43]
	v_cndmask_b32_e64 v91, 0, v112, s[42:43]
	v_fmac_f32_dpp v152, v164, v116 row_shl:1 row_mask:0xf bank_mask:0xf bound_ctrl:0
	v_fmac_f32_dpp v153, v165, v117 row_shl:1 row_mask:0xf bank_mask:0xf bound_ctrl:0
	v_fmac_f32_dpp v160, v156, v112 row_shl:1 row_mask:0xf bank_mask:0xf bound_ctrl:0
	v_fmac_f32_dpp v161, v157, v113 row_shl:1 row_mask:0xf bank_mask:0xf bound_ctrl:0
	v_cmp_ne_u32_e32 vcc, 0, v167
	v_fmac_f32_dpp v152, v122, v171 row_ror:15 row_mask:0xf bank_mask:0xf bound_ctrl:0
	v_fmac_f32_dpp v153, v123, v151 row_ror:15 row_mask:0xf bank_mask:0xf bound_ctrl:0
	v_fmac_f32_dpp v160, v118, v91 row_ror:15 row_mask:0xf bank_mask:0xf bound_ctrl:0
	v_fmac_f32_dpp v161, v119, v83 row_ror:15 row_mask:0xf bank_mask:0xf bound_ctrl:0
	s_cbranch_vccnz .Lconvgate_fix_9

;     __device__ __forceinline__ void operator()(f32x4 (&acc)[2][2][4][2], const Unit& u, int wr, int wc, int fr, int fq) const {
;     ...
;                 for (int ai = 0; ai < 2; ++ai) {
;                     const int tokbase = u.pm * 248 + 62 * (2 * ai + wr) - 1;
; #pragma unroll
;                     for (int m = 0; m < 4; ++m) {
;                         const int rr = 16 * m + fr, tok = tokbase + rr, pos = tok & Tmask;
;                         const bool lbad = pos == 0, rbad = pos == Tmask;
;                         float uu[2][2];
; #pragma unroll
;                         for (int bj = 0; bj < 2; ++bj) {
;                             const f32x4 c = acc[ai][bj][m][n], cm = acc[ai][bj][m > 0 ? m - 1 : m][n], cp = acc[ai][bj][m < 3 ? m + 1 : m][n];
; #pragma unroll
;                             for (int jj = 0; jj < 2; ++jj) {
;                                 const int j = 2 * jh + jj;
;                                 float t = bb[bj][jj] + w1[bj][jj] * c[j];
;                                 fmac_shr1(t, c[j], w0[bj][jj]);
;                                 fmac_shl1(t, c[j], w2[bj][jj]);
;                                 if (m > 0) fmac_ror1(t, cm[j], w0f[bj][jj]);
;                                 if (m < 3) fmac_ror15(t, cp[j], w2l[bj][jj]);
;                                 uu[bj][jj] = t;
;                             }
;                         }
;                         if (__any(lbad | rbad)) {
.LBB0_809:
	s_or_b64 exec, exec, s[6:7]
	v_pk_mul_f32 v[148:149], v[148:149], v[150:151] op_sel_hi:[1,0]
	v_pk_mul_f32 v[144:145], v[144:145], v[150:151] op_sel_hi:[1,0]
	v_cndmask_b32_e64 v143, 0, v125, s[44:45]
	v_cndmask_b32_e64 v155, 0, v124, s[44:45]
	v_cndmask_b32_e64 v87, 0, v121, s[44:45]
	v_cndmask_b32_e64 v135, 0, v120, s[44:45]
	v_fma_f32 v152, v132, v122, v104
	v_fma_f32 v153, v133, v123, v105
	v_fma_f32 v160, v118, v128, v108
	v_fma_f32 v161, v119, v129, v109
	v_fmac_f32_dpp v152, v122, v124 row_shr:1 row_mask:0xf bank_mask:0xf bound_ctrl:0
	v_fmac_f32_dpp v153, v123, v125 row_shr:1 row_mask:0xf bank_mask:0xf bound_ctrl:0
	v_fmac_f32_dpp v160, v118, v120 row_shr:1 row_mask:0xf bank_mask:0xf bound_ctrl:0
	v_fmac_f32_dpp v161, v119, v121 row_shr:1 row_mask:0xf bank_mask:0xf bound_ctrl:0
	v_cndmask_b32_e64 v166, 0, 1, s[90:91]
	v_fmac_f32_dpp v152, v122, v116 row_shl:1 row_mask:0xf bank_mask:0xf bound_ctrl:0
	v_fmac_f32_dpp v153, v123, v117 row_shl:1 row_mask:0xf bank_mask:0xf bound_ctrl:0
	v_fmac_f32_dpp v160, v118, v112 row_shl:1 row_mask:0xf bank_mask:0xf bound_ctrl:0
	v_fmac_f32_dpp v161, v119, v113 row_shl:1 row_mask:0xf bank_mask:0xf bound_ctrl:0
	v_cmp_ne_u32_e32 vcc, 0, v166
	v_fmac_f32_dpp v152, v164, v155 row_ror:1 row_mask:0xf bank_mask:0xf bound_ctrl:0
	v_fmac_f32_dpp v153, v165, v143 row_ror:1 row_mask:0xf bank_mask:0xf bound_ctrl:0
	v_fmac_f32_dpp v160, v156, v135 row_ror:1 row_mask:0xf bank_mask:0xf bound_ctrl:0
	v_fmac_f32_dpp v161, v157, v87 row_ror:1 row_mask:0xf bank_mask:0xf bound_ctrl:0
	s_nop 0
	v_fmac_f32_dpp v152, v148, v171 row_ror:15 row_mask:0xf bank_mask:0xf bound_ctrl:0
	v_fmac_f32_dpp v153, v149, v151 row_ror:15 row_mask:0xf bank_mask:0xf bound_ctrl:0
	v_fmac_f32_dpp v160, v144, v91 row_ror:15 row_mask:0xf bank_mask:0xf bound_ctrl:0
	v_fmac_f32_dpp v161, v145, v83 row_ror:15 row_mask:0xf bank_mask:0xf bound_ctrl:0
	s_cbranch_vccnz .Lconvgate_fix_10

;     __device__ __forceinline__ void operator()(f32x4 (&acc)[2][2][4][2], const Unit& u, int wr, int wc, int fr, int fq) const {
;     ...
;                 for (int ai = 0; ai < 2; ++ai) {
;                     const int tokbase = u.pm * 248 + 62 * (2 * ai + wr) - 1;
; #pragma unroll
;                     for (int m = 0; m < 4; ++m) {
;                         const int rr = 16 * m + fr, tok = tokbase + rr, pos = tok & Tmask;
;                         const bool lbad = pos == 0, rbad = pos == Tmask;
;                         float uu[2][2];
; #pragma unroll
;                         for (int bj = 0; bj < 2; ++bj) {
;                             const f32x4 c = acc[ai][bj][m][n], cm = acc[ai][bj][m > 0 ? m - 1 : m][n], cp = acc[ai][bj][m < 3 ? m + 1 : m][n];
; #pragma unroll
;                             for (int jj = 0; jj < 2; ++jj) {
;                                 const int j = 2 * jh + jj;
;                                 float t = bb[bj][jj] + w1[bj][jj] * c[j];
;                                 fmac_shr1(t, c[j], w0[bj][jj]);
;                                 fmac_shl1(t, c[j], w2[bj][jj]);
;                                 if (m > 0) fmac_ror1(t, cm[j], w0f[bj][jj]);
;                                 if (m < 3) fmac_ror15(t, cp[j], w2l[bj][jj]);
;                                 uu[bj][jj] = t;
;                             }
;                         }
;                         if (__any(lbad | rbad)) {
.LBB0_813:
	s_or_b64 exec, exec, s[6:7]
	v_pk_mul_f32 v[140:141], v[140:141], v[142:143] op_sel_hi:[1,0]
	v_pk_mul_f32 v[136:137], v[136:137], v[142:143] op_sel_hi:[1,0]
	v_fma_f32 v152, v132, v148, v104
	v_fma_f32 v153, v133, v149, v105
	v_fma_f32 v156, v144, v128, v108
	v_fma_f32 v157, v145, v129, v109
	v_fmac_f32_dpp v152, v148, v124 row_shr:1 row_mask:0xf bank_mask:0xf bound_ctrl:0
	v_fmac_f32_dpp v153, v149, v125 row_shr:1 row_mask:0xf bank_mask:0xf bound_ctrl:0
	v_fmac_f32_dpp v156, v144, v120 row_shr:1 row_mask:0xf bank_mask:0xf bound_ctrl:0
	v_fmac_f32_dpp v157, v145, v121 row_shr:1 row_mask:0xf bank_mask:0xf bound_ctrl:0
	v_cndmask_b32_e64 v160, 0, 1, s[88:89]
	v_fmac_f32_dpp v152, v148, v116 row_shl:1 row_mask:0xf bank_mask:0xf bound_ctrl:0
	v_fmac_f32_dpp v153, v149, v117 row_shl:1 row_mask:0xf bank_mask:0xf bound_ctrl:0
	v_fmac_f32_dpp v156, v144, v112 row_shl:1 row_mask:0xf bank_mask:0xf bound_ctrl:0
	v_fmac_f32_dpp v157, v145, v113 row_shl:1 row_mask:0xf bank_mask:0xf bound_ctrl:0
	v_cmp_ne_u32_e32 vcc, 0, v160
	v_fmac_f32_dpp v152, v122, v155 row_ror:1 row_mask:0xf bank_mask:0xf bound_ctrl:0
	v_fmac_f32_dpp v153, v123, v143 row_ror:1 row_mask:0xf bank_mask:0xf bound_ctrl:0
	v_fmac_f32_dpp v156, v118, v135 row_ror:1 row_mask:0xf bank_mask:0xf bound_ctrl:0
	v_fmac_f32_dpp v157, v119, v87 row_ror:1 row_mask:0xf bank_mask:0xf bound_ctrl:0
	s_nop 0
	v_fmac_f32_dpp v152, v140, v171 row_ror:15 row_mask:0xf bank_mask:0xf bound_ctrl:0
	v_fmac_f32_dpp v153, v141, v151 row_ror:15 row_mask:0xf bank_mask:0xf bound_ctrl:0
	v_fmac_f32_dpp v156, v136, v91 row_ror:15 row_mask:0xf bank_mask:0xf bound_ctrl:0
	v_fmac_f32_dpp v157, v137, v83 row_ror:15 row_mask:0xf bank_mask:0xf bound_ctrl:0
	s_cbranch_vccnz .Lconvgate_fix_11

;     __device__ __forceinline__ void operator()(f32x4 (&acc)[2][2][4][2], const Unit& u, int wr, int wc, int fr, int fq) const {
;     ...
;                 for (int ai = 0; ai < 2; ++ai) {
;                     const int tokbase = u.pm * 248 + 62 * (2 * ai + wr) - 1;
; #pragma unroll
;                     for (int m = 0; m < 4; ++m) {
;                         const int rr = 16 * m + fr, tok = tokbase + rr, pos = tok & Tmask;
;                         const bool lbad = pos == 0, rbad = pos == Tmask;
;                         float uu[2][2];
; #pragma unroll
;                         for (int bj = 0; bj < 2; ++bj) {
;                             const f32x4 c = acc[ai][bj][m][n], cm = acc[ai][bj][m > 0 ? m - 1 : m][n], cp = acc[ai][bj][m < 3 ? m + 1 : m][n];
; #pragma unroll
;                             for (int jj = 0; jj < 2; ++jj) {
;                                 const int j = 2 * jh + jj;
;                                 float t = bb[bj][jj] + w1[bj][jj] * c[j];
;                                 fmac_shr1(t, c[j], w0[bj][jj]);
;                                 fmac_shl1(t, c[j], w2[bj][jj]);
;                                 if (m > 0) fmac_ror1(t, cm[j], w0f[bj][jj]);
;                                 if (m < 3) fmac_ror15(t, cp[j], w2l[bj][jj]);
;                                 uu[bj][jj] = t;
;                             }
;                         }
;                         if (__any(lbad | rbad)) {
.LBB0_817:
	s_or_b64 exec, exec, s[6:7]
	v_fma_f32 v118, v132, v140, v104
	v_fma_f32 v119, v133, v141, v105
	v_fma_f32 v122, v136, v128, v108
	v_fma_f32 v123, v137, v129, v109
	v_fmac_f32_dpp v118, v140, v124 row_shr:1 row_mask:0xf bank_mask:0xf bound_ctrl:0
	v_fmac_f32_dpp v119, v141, v125 row_shr:1 row_mask:0xf bank_mask:0xf bound_ctrl:0
	v_fmac_f32_dpp v122, v136, v120 row_shr:1 row_mask:0xf bank_mask:0xf bound_ctrl:0
	v_fmac_f32_dpp v123, v137, v121 row_shr:1 row_mask:0xf bank_mask:0xf bound_ctrl:0
	v_cndmask_b32_e64 v152, 0, 1, s[96:97]
	v_fmac_f32_dpp v118, v140, v116 row_shl:1 row_mask:0xf bank_mask:0xf bound_ctrl:0
	v_fmac_f32_dpp v119, v141, v117 row_shl:1 row_mask:0xf bank_mask:0xf bound_ctrl:0
	v_fmac_f32_dpp v122, v136, v112 row_shl:1 row_mask:0xf bank_mask:0xf bound_ctrl:0
	v_fmac_f32_dpp v123, v137, v113 row_shl:1 row_mask:0xf bank_mask:0xf bound_ctrl:0
	v_cmp_ne_u32_e32 vcc, 0, v152
	v_fmac_f32_dpp v118, v148, v155 row_ror:1 row_mask:0xf bank_mask:0xf bound_ctrl:0
	v_fmac_f32_dpp v119, v149, v143 row_ror:1 row_mask:0xf bank_mask:0xf bound_ctrl:0
	v_fmac_f32_dpp v122, v144, v135 row_ror:1 row_mask:0xf bank_mask:0xf bound_ctrl:0
	v_fmac_f32_dpp v123, v145, v87 row_ror:1 row_mask:0xf bank_mask:0xf bound_ctrl:0
	s_cbranch_vccnz .Lconvgate_fix_12

;     __device__ __forceinline__ void operator()(f32x4 (&acc)[2][2][4][2], const Unit& u, int wr, int wc, int fr, int fq) const {
;     ...
;                 for (int ai = 0; ai < 2; ++ai) {
;                     const int tokbase = u.pm * 248 + 62 * (2 * ai + wr) - 1;
; #pragma unroll
;                     for (int m = 0; m < 4; ++m) {
;                         const int rr = 16 * m + fr, tok = tokbase + rr, pos = tok & Tmask;
;                         const bool lbad = pos == 0, rbad = pos == Tmask;
;                         float uu[2][2];
; #pragma unroll
;                         for (int bj = 0; bj < 2; ++bj) {
;                             const f32x4 c = acc[ai][bj][m][n], cm = acc[ai][bj][m > 0 ? m - 1 : m][n], cp = acc[ai][bj][m < 3 ? m + 1 : m][n];
; #pragma unroll
;                             for (int jj = 0; jj < 2; ++jj) {
;                                 const int j = 2 * jh + jj;
;                                 float t = bb[bj][jj] + w1[bj][jj] * c[j];
;                                 fmac_shr1(t, c[j], w0[bj][jj]);
;                                 fmac_shl1(t, c[j], w2[bj][jj]);
;                                 if (m > 0) fmac_ror1(t, cm[j], w0f[bj][jj]);
;                                 if (m < 3) fmac_ror15(t, cp[j], w2l[bj][jj]);
;                                 uu[bj][jj] = t;
;                             }
;                         }
;                         if (__any(lbad | rbad)) {
.LBB0_821:
	s_or_b64 exec, exec, s[6:7]
	v_pk_mul_f32 v[118:119], v[100:101], v[134:135] op_sel_hi:[1,0]
	v_pk_mul_f32 v[100:101], v[92:93], v[134:135] op_sel_hi:[1,0]
	v_pk_mul_f32 v[92:93], v[96:97], v[90:91] op_sel_hi:[1,0]
	v_pk_mul_f32 v[88:89], v[88:89], v[90:91] op_sel_hi:[1,0]
	v_fma_f32 v96, v132, v118, v104
	v_fma_f32 v97, v133, v119, v105
	v_fma_f32 v122, v100, v128, v108
	v_fma_f32 v123, v101, v129, v109
	v_fmac_f32_dpp v96, v118, v124 row_shr:1 row_mask:0xf bank_mask:0xf bound_ctrl:0
	v_fmac_f32_dpp v97, v119, v125 row_shr:1 row_mask:0xf bank_mask:0xf bound_ctrl:0
	v_fmac_f32_dpp v122, v100, v120 row_shr:1 row_mask:0xf bank_mask:0xf bound_ctrl:0
	v_fmac_f32_dpp v123, v101, v121 row_shr:1 row_mask:0xf bank_mask:0xf bound_ctrl:0
	v_cndmask_b32_e64 v137, 0, 1, s[94:95]
	v_fmac_f32_dpp v96, v118, v116 row_shl:1 row_mask:0xf bank_mask:0xf bound_ctrl:0
	v_fmac_f32_dpp v97, v119, v117 row_shl:1 row_mask:0xf bank_mask:0xf bound_ctrl:0
	v_fmac_f32_dpp v122, v100, v112 row_shl:1 row_mask:0xf bank_mask:0xf bound_ctrl:0
	v_fmac_f32_dpp v123, v101, v113 row_shl:1 row_mask:0xf bank_mask:0xf bound_ctrl:0
	v_cmp_ne_u32_e32 vcc, 0, v137
	v_fmac_f32_dpp v96, v92, v171 row_ror:15 row_mask:0xf bank_mask:0xf bound_ctrl:0
	v_fmac_f32_dpp v97, v93, v151 row_ror:15 row_mask:0xf bank_mask:0xf bound_ctrl:0
	v_fmac_f32_dpp v122, v88, v91 row_ror:15 row_mask:0xf bank_mask:0xf bound_ctrl:0
	v_fmac_f32_dpp v123, v89, v83 row_ror:15 row_mask:0xf bank_mask:0xf bound_ctrl:0
	s_cbranch_vccnz .Lconvgate_fix_13

;     __device__ __forceinline__ void operator()(f32x4 (&acc)[2][2][4][2], const Unit& u, int wr, int wc, int fr, int fq) const {
;     ...
;                 for (int ai = 0; ai < 2; ++ai) {
;                     const int tokbase = u.pm * 248 + 62 * (2 * ai + wr) - 1;
; #pragma unroll
;                     for (int m = 0; m < 4; ++m) {
;                         const int rr = 16 * m + fr, tok = tokbase + rr, pos = tok & Tmask;
;                         const bool lbad = pos == 0, rbad = pos == Tmask;
;                         float uu[2][2];
; #pragma unroll
;                         for (int bj = 0; bj < 2; ++bj) {
;                             const f32x4 c = acc[ai][bj][m][n], cm = acc[ai][bj][m > 0 ? m - 1 : m][n], cp = acc[ai][bj][m < 3 ? m + 1 : m][n];
; #pragma unroll
;                             for (int jj = 0; jj < 2; ++jj) {
;                                 const int j = 2 * jh + jj;
;                                 float t = bb[bj][jj] + w1[bj][jj] * c[j];
;                                 fmac_shr1(t, c[j], w0[bj][jj]);
;                                 fmac_shl1(t, c[j], w2[bj][jj]);
;                                 if (m > 0) fmac_ror1(t, cm[j], w0f[bj][jj]);
;                                 if (m < 3) fmac_ror15(t, cp[j], w2l[bj][jj]);
;                                 uu[bj][jj] = t;
;                             }
;                         }
;                         if (__any(lbad | rbad)) {
.LBB0_825:
	s_or_b64 exec, exec, s[6:7]
	v_pk_mul_f32 v[84:85], v[84:85], v[86:87] op_sel_hi:[1,0]
	v_pk_mul_f32 v[80:81], v[80:81], v[86:87] op_sel_hi:[1,0]
	v_fma_f32 v96, v132, v92, v104
	v_fma_f32 v97, v133, v93, v105
	v_fma_f32 v122, v88, v128, v108
	v_fma_f32 v123, v89, v129, v109
	v_fmac_f32_dpp v96, v92, v124 row_shr:1 row_mask:0xf bank_mask:0xf bound_ctrl:0
	v_fmac_f32_dpp v97, v93, v125 row_shr:1 row_mask:0xf bank_mask:0xf bound_ctrl:0
	v_fmac_f32_dpp v122, v88, v120 row_shr:1 row_mask:0xf bank_mask:0xf bound_ctrl:0
	v_fmac_f32_dpp v123, v89, v121 row_shr:1 row_mask:0xf bank_mask:0xf bound_ctrl:0
	v_cndmask_b32_e64 v136, 0, 1, s[86:87]
	v_fmac_f32_dpp v96, v92, v116 row_shl:1 row_mask:0xf bank_mask:0xf bound_ctrl:0
	v_fmac_f32_dpp v97, v93, v117 row_shl:1 row_mask:0xf bank_mask:0xf bound_ctrl:0
	v_fmac_f32_dpp v122, v88, v112 row_shl:1 row_mask:0xf bank_mask:0xf bound_ctrl:0
	v_fmac_f32_dpp v123, v89, v113 row_shl:1 row_mask:0xf bank_mask:0xf bound_ctrl:0
	v_cmp_ne_u32_e32 vcc, 0, v136
	v_fmac_f32_dpp v96, v118, v155 row_ror:1 row_mask:0xf bank_mask:0xf bound_ctrl:0
	v_fmac_f32_dpp v97, v119, v143 row_ror:1 row_mask:0xf bank_mask:0xf bound_ctrl:0
	v_fmac_f32_dpp v122, v100, v135 row_ror:1 row_mask:0xf bank_mask:0xf bound_ctrl:0
	v_fmac_f32_dpp v123, v101, v87 row_ror:1 row_mask:0xf bank_mask:0xf bound_ctrl:0
	s_nop 0
	v_fmac_f32_dpp v96, v84, v171 row_ror:15 row_mask:0xf bank_mask:0xf bound_ctrl:0
	v_fmac_f32_dpp v97, v85, v151 row_ror:15 row_mask:0xf bank_mask:0xf bound_ctrl:0
	v_fmac_f32_dpp v122, v80, v91 row_ror:15 row_mask:0xf bank_mask:0xf bound_ctrl:0
	v_fmac_f32_dpp v123, v81, v83 row_ror:15 row_mask:0xf bank_mask:0xf bound_ctrl:0
	s_cbranch_vccnz .Lconvgate_fix_14

;     __device__ __forceinline__ void operator()(f32x4 (&acc)[2][2][4][2], const Unit& u, int wr, int wc, int fr, int fq) const {
;     ...
;                 for (int ai = 0; ai < 2; ++ai) {
;                     const int tokbase = u.pm * 248 + 62 * (2 * ai + wr) - 1;
; #pragma unroll
;                     for (int m = 0; m < 4; ++m) {
;                         const int rr = 16 * m + fr, tok = tokbase + rr, pos = tok & Tmask;
;                         const bool lbad = pos == 0, rbad = pos == Tmask;
;                         float uu[2][2];
; #pragma unroll
;                         for (int bj = 0; bj < 2; ++bj) {
;                             const f32x4 c = acc[ai][bj][m][n], cm = acc[ai][bj][m > 0 ? m - 1 : m][n], cp = acc[ai][bj][m < 3 ? m + 1 : m][n];
; #pragma unroll
;                             for (int jj = 0; jj < 2; ++jj) {
;                                 const int j = 2 * jh + jj;
;                                 float t = bb[bj][jj] + w1[bj][jj] * c[j];
;                                 fmac_shr1(t, c[j], w0[bj][jj]);
;                                 fmac_shl1(t, c[j], w2[bj][jj]);
;                                 if (m > 0) fmac_ror1(t, cm[j], w0f[bj][jj]);
;                                 if (m < 3) fmac_ror15(t, cp[j], w2l[bj][jj]);
;                                 uu[bj][jj] = t;
;                             }
;                         }
;                         if (__any(lbad | rbad)) {
.LBB0_829:
	s_or_b64 exec, exec, s[6:7]
	v_pk_mul_f32 v[76:77], v[76:77], v[82:83] op_sel_hi:[1,0]
	v_pk_mul_f32 v[72:73], v[72:73], v[82:83] op_sel_hi:[1,0]
	v_fma_f32 v96, v132, v84, v104
	v_fma_f32 v97, v133, v85, v105
	v_fma_f32 v100, v80, v128, v108
	v_fma_f32 v101, v81, v129, v109
	v_fmac_f32_dpp v96, v84, v124 row_shr:1 row_mask:0xf bank_mask:0xf bound_ctrl:0
	v_fmac_f32_dpp v97, v85, v125 row_shr:1 row_mask:0xf bank_mask:0xf bound_ctrl:0
	v_fmac_f32_dpp v100, v80, v120 row_shr:1 row_mask:0xf bank_mask:0xf bound_ctrl:0
	v_fmac_f32_dpp v101, v81, v121 row_shr:1 row_mask:0xf bank_mask:0xf bound_ctrl:0
	v_cndmask_b32_e64 v123, 0, 1, s[84:85]
	v_fmac_f32_dpp v96, v84, v116 row_shl:1 row_mask:0xf bank_mask:0xf bound_ctrl:0
	v_fmac_f32_dpp v97, v85, v117 row_shl:1 row_mask:0xf bank_mask:0xf bound_ctrl:0
	v_fmac_f32_dpp v100, v80, v112 row_shl:1 row_mask:0xf bank_mask:0xf bound_ctrl:0
	v_fmac_f32_dpp v101, v81, v113 row_shl:1 row_mask:0xf bank_mask:0xf bound_ctrl:0
	v_cmp_ne_u32_e32 vcc, 0, v123
	v_fmac_f32_dpp v96, v92, v155 row_ror:1 row_mask:0xf bank_mask:0xf bound_ctrl:0
	v_fmac_f32_dpp v97, v93, v143 row_ror:1 row_mask:0xf bank_mask:0xf bound_ctrl:0
	v_fmac_f32_dpp v100, v88, v135 row_ror:1 row_mask:0xf bank_mask:0xf bound_ctrl:0
	v_fmac_f32_dpp v101, v89, v87 row_ror:1 row_mask:0xf bank_mask:0xf bound_ctrl:0
	s_nop 0
	v_fmac_f32_dpp v96, v76, v171 row_ror:15 row_mask:0xf bank_mask:0xf bound_ctrl:0
	v_fmac_f32_dpp v97, v77, v151 row_ror:15 row_mask:0xf bank_mask:0xf bound_ctrl:0
	v_fmac_f32_dpp v100, v72, v91 row_ror:15 row_mask:0xf bank_mask:0xf bound_ctrl:0
	v_fmac_f32_dpp v101, v73, v83 row_ror:15 row_mask:0xf bank_mask:0xf bound_ctrl:0
	s_cbranch_vccnz .Lconvgate_fix_15

;     __device__ __forceinline__ void operator()(f32x4 (&acc)[2][2][4][2], const Unit& u, int wr, int wc, int fr, int fq) const {
;     ...
;                 for (int ai = 0; ai < 2; ++ai) {
;                     const int tokbase = u.pm * 248 + 62 * (2 * ai + wr) - 1;
; #pragma unroll
;                     for (int m = 0; m < 4; ++m) {
;                         const int rr = 16 * m + fr, tok = tokbase + rr, pos = tok & Tmask;
;                         const bool lbad = pos == 0, rbad = pos == Tmask;
;                         float uu[2][2];
; #pragma unroll
;                         for (int bj = 0; bj < 2; ++bj) {
;                             const f32x4 c = acc[ai][bj][m][n], cm = acc[ai][bj][m > 0 ? m - 1 : m][n], cp = acc[ai][bj][m < 3 ? m + 1 : m][n];
; #pragma unroll
;                             for (int jj = 0; jj < 2; ++jj) {
;                                 const int j = 2 * jh + jj;
;                                 float t = bb[bj][jj] + w1[bj][jj] * c[j];
;                                 fmac_shr1(t, c[j], w0[bj][jj]);
;                                 fmac_shl1(t, c[j], w2[bj][jj]);
;                                 if (m > 0) fmac_ror1(t, cm[j], w0f[bj][jj]);
;                                 if (m < 3) fmac_ror15(t, cp[j], w2l[bj][jj]);
;                                 uu[bj][jj] = t;
;                             }
;                         }
;                         if (__any(lbad | rbad)) {
.LBB0_833:
	s_or_b64 exec, exec, s[6:7]
	v_fma_f32 v104, v132, v76, v104
	v_fmac_f32_e32 v105, v133, v77
	v_fma_f32 v108, v72, v128, v108
	v_fmac_f32_e32 v109, v73, v129
	v_fmac_f32_dpp v104, v76, v124 row_shr:1 row_mask:0xf bank_mask:0xf bound_ctrl:0
	v_fmac_f32_dpp v105, v77, v125 row_shr:1 row_mask:0xf bank_mask:0xf bound_ctrl:0
	v_fmac_f32_dpp v108, v72, v120 row_shr:1 row_mask:0xf bank_mask:0xf bound_ctrl:0
	v_fmac_f32_dpp v109, v73, v121 row_shr:1 row_mask:0xf bank_mask:0xf bound_ctrl:0
	v_cndmask_b32_e64 v122, 0, 1, s[92:93]
	v_fmac_f32_dpp v104, v76, v116 row_shl:1 row_mask:0xf bank_mask:0xf bound_ctrl:0
	v_fmac_f32_dpp v105, v77, v117 row_shl:1 row_mask:0xf bank_mask:0xf bound_ctrl:0
	v_fmac_f32_dpp v108, v72, v112 row_shl:1 row_mask:0xf bank_mask:0xf bound_ctrl:0
	v_fmac_f32_dpp v109, v73, v113 row_shl:1 row_mask:0xf bank_mask:0xf bound_ctrl:0
	v_cmp_ne_u32_e32 vcc, 0, v122
	v_fmac_f32_dpp v104, v84, v155 row_ror:1 row_mask:0xf bank_mask:0xf bound_ctrl:0
	v_fmac_f32_dpp v105, v85, v143 row_ror:1 row_mask:0xf bank_mask:0xf bound_ctrl:0
	v_fmac_f32_dpp v108, v80, v135 row_ror:1 row_mask:0xf bank_mask:0xf bound_ctrl:0
	v_fmac_f32_dpp v109, v81, v87 row_ror:1 row_mask:0xf bank_mask:0xf bound_ctrl:0
	s_cbranch_vccnz .Lconvgate_fix_16

;     __device__ __forceinline__ void operator()(f32x4 (&acc)[2][2][4][2], const Unit& u, int wr, int wc, int fr, int fq) const {
;     ...
;         CONV_WLOAD(0, 0, 0);
; #pragma unroll
;         for (int n = 0; n < 2; ++n) {
;             unsigned stash[2][4];
; #pragma unroll
;             for (int jh = 0; jh < 2; ++jh) {
;                 const int g_ = 2 * n + jh, cb_ = g_ & 1;
;                 if (g_ + 1 < 4) CONV_WLOAD(cb_ ^ 1, (g_ + 1) >> 1, (g_ + 1) & 1);
;                 f32x2 w0[2], w1[2], w2[2], bb[2], w0f[2], w2l[2];
; #pragma unroll
;                 for (int bj = 0; bj < 2; ++bj) { w0[bj] = wq[cb_][bj][0]; w1[bj] = wq[cb_][bj][1]; w2[bj] = wq[cb_][bj][2]; bb[bj] = wq[cb_][bj][3];
;                     w0f[bj] = f0 ? w0[bj] : (f32x2){0.f, 0.f}; w2l[bj] = f15 ? w2[bj] : (f32x2){0.f, 0.f}; }
; #pragma unroll
;                 for (int ai = 0; ai < 2; ++ai) {
;                     const int tokbase = u.pm * 248 + 62 * (2 * ai + wr) - 1;
; #pragma unroll
;                     for (int m = 0; m < 4; ++m) {
;                         const int rr = 16 * m + fr, tok = tokbase + rr, pos = tok & Tmask;
;                         const bool lbad = pos == 0, rbad = pos == Tmask;
;                         float uu[2][2];
; #pragma unroll
;                         for (int bj = 0; bj < 2; ++bj) {
;                             const f32x4 c = acc[ai][bj][m][n], cm = acc[ai][bj][m > 0 ? m - 1 : m][n], cp = acc[ai][bj][m < 3 ? m + 1 : m][n];
; #pragma unroll
;                             for (int jj = 0; jj < 2; ++jj) {
;                                 const int j = 2 * jh + jj;
;                                 float t = bb[bj][jj] + w1[bj][jj] * c[j];
;                                 fmac_shr1(t, c[j], w0[bj][jj]);
;                                 fmac_shl1(t, c[j], w2[bj][jj]);
;                                 if (m > 0) fmac_ror1(t, cm[j], w0f[bj][jj]);
;                                 if (m < 3) fmac_ror15(t, cp[j], w2l[bj][jj]);
;                                 uu[bj][jj] = t;
;                             }
;                         }
;                         if (__any(lbad | rbad)) {
.LBB0_837:
	s_or_b64 exec, exec, s[92:93]
	v_mov_b32_e32 v213, v212
	v_mov_b32_e32 v155, v154
	v_pk_mul_f32 v[120:121], v[66:67], v[212:213]
	v_pk_mul_f32 v[118:119], v[58:59], v[212:213]
	v_pk_mul_f32 v[112:113], v[62:63], v[154:155]
	v_pk_mul_f32 v[104:105], v[54:55], v[154:155]
	global_load_dwordx2 v[76:77], v[214:215], off offset:24
	global_load_dwordx2 v[84:85], v[214:215], off offset:536
	global_load_dwordx2 v[72:73], v[214:215], off offset:1048
	global_load_dwordx2 v[54:55], v[214:215], off offset:1560
	global_load_dwordx2 v[66:67], v[214:215], off offset:2072
	global_load_dwordx2 v[80:81], v[214:215], off offset:2584
	global_load_dwordx2 v[62:63], v[214:215], off offset:3096
	global_load_dwordx2 v[58:59], v[214:215], off offset:3608
	v_fma_f32 v96, v120, v114, v70
	v_fma_f32 v97, v121, v115, v71
	v_fma_f32 v100, v118, v110, v74
	v_fma_f32 v101, v119, v111, v75
	v_fmac_f32_dpp v96, v120, v102 row_shr:1 row_mask:0xf bank_mask:0xf bound_ctrl:0
	v_fmac_f32_dpp v97, v121, v103 row_shr:1 row_mask:0xf bank_mask:0xf bound_ctrl:0
	v_fmac_f32_dpp v100, v118, v94 row_shr:1 row_mask:0xf bank_mask:0xf bound_ctrl:0
	v_fmac_f32_dpp v101, v119, v95 row_shr:1 row_mask:0xf bank_mask:0xf bound_ctrl:0
	v_cndmask_b32_e64 v129, 0, v107, s[42:43]
	v_cndmask_b32_e64 v131, 0, v106, s[42:43]
	v_cndmask_b32_e64 v125, 0, v99, s[42:43]
	v_cndmask_b32_e64 v128, 0, v98, s[42:43]
	v_fmac_f32_dpp v96, v120, v106 row_shl:1 row_mask:0xf bank_mask:0xf bound_ctrl:0
	v_fmac_f32_dpp v97, v121, v107 row_shl:1 row_mask:0xf bank_mask:0xf bound_ctrl:0
	v_fmac_f32_dpp v100, v118, v98 row_shl:1 row_mask:0xf bank_mask:0xf bound_ctrl:0
	v_fmac_f32_dpp v101, v119, v99 row_shl:1 row_mask:0xf bank_mask:0xf bound_ctrl:0
	v_cmp_ne_u32_e32 vcc, 0, v167
	v_fmac_f32_dpp v96, v112, v131 row_ror:15 row_mask:0xf bank_mask:0xf bound_ctrl:0
	v_fmac_f32_dpp v97, v113, v129 row_ror:15 row_mask:0xf bank_mask:0xf bound_ctrl:0
	v_fmac_f32_dpp v100, v104, v128 row_ror:15 row_mask:0xf bank_mask:0xf bound_ctrl:0
	v_fmac_f32_dpp v101, v105, v125 row_ror:15 row_mask:0xf bank_mask:0xf bound_ctrl:0
	s_cbranch_vccnz .Lconvgate_fix_17
.LBB0_839:
	v_readlane_b32 s92, v254, 57
	v_readlane_b32 s94, v254, 59
	v_mov_b32_e32 v151, v150
	v_readlane_b32 s93, v254, 58
	v_readlane_b32 s95, v254, 60
	v_cndmask_b32_e64 v127, 0, v103, s[44:45]
	v_cndmask_b32_e64 v130, 0, v102, s[44:45]
	v_cndmask_b32_e64 v124, 0, v95, s[44:45]
	v_cndmask_b32_e64 v126, 0, v94, s[44:45]
	v_pk_mul_f32 v[116:117], v[50:51], v[150:151]
	v_pk_mul_f32 v[108:109], v[46:47], v[150:151]
	v_fma_f32 v88, v112, v114, v70
	v_fma_f32 v89, v113, v115, v71
	v_fma_f32 v92, v104, v110, v74
	v_fma_f32 v93, v105, v111, v75
	v_fmac_f32_dpp v88, v112, v102 row_shr:1 row_mask:0xf bank_mask:0xf bound_ctrl:0
	v_fmac_f32_dpp v89, v113, v103 row_shr:1 row_mask:0xf bank_mask:0xf bound_ctrl:0
	v_fmac_f32_dpp v92, v104, v94 row_shr:1 row_mask:0xf bank_mask:0xf bound_ctrl:0
	v_fmac_f32_dpp v93, v105, v95 row_shr:1 row_mask:0xf bank_mask:0xf bound_ctrl:0
	v_cmp_ne_u32_e32 vcc, 0, v166
	v_fmac_f32_dpp v88, v112, v106 row_shl:1 row_mask:0xf bank_mask:0xf bound_ctrl:0
	v_fmac_f32_dpp v89, v113, v107 row_shl:1 row_mask:0xf bank_mask:0xf bound_ctrl:0
	v_fmac_f32_dpp v92, v104, v98 row_shl:1 row_mask:0xf bank_mask:0xf bound_ctrl:0
	v_fmac_f32_dpp v93, v105, v99 row_shl:1 row_mask:0xf bank_mask:0xf bound_ctrl:0
	s_nop 0
	v_fmac_f32_dpp v88, v120, v130 row_ror:1 row_mask:0xf bank_mask:0xf bound_ctrl:0
	v_fmac_f32_dpp v89, v121, v127 row_ror:1 row_mask:0xf bank_mask:0xf bound_ctrl:0
	v_fmac_f32_dpp v92, v118, v126 row_ror:1 row_mask:0xf bank_mask:0xf bound_ctrl:0
	v_fmac_f32_dpp v93, v119, v124 row_ror:1 row_mask:0xf bank_mask:0xf bound_ctrl:0
	s_nop 0
	v_fmac_f32_dpp v88, v116, v131 row_ror:15 row_mask:0xf bank_mask:0xf bound_ctrl:0
	v_fmac_f32_dpp v89, v117, v129 row_ror:15 row_mask:0xf bank_mask:0xf bound_ctrl:0
	v_fmac_f32_dpp v92, v108, v128 row_ror:15 row_mask:0xf bank_mask:0xf bound_ctrl:0
	v_fmac_f32_dpp v93, v109, v125 row_ror:15 row_mask:0xf bank_mask:0xf bound_ctrl:0
	s_cbranch_vccnz .Lconvgate_fix_18
.LBB0_841:
	v_mov_b32_e32 v143, v142
	v_pk_mul_f32 v[120:121], v[42:43], v[142:143]
	v_pk_mul_f32 v[118:119], v[38:39], v[142:143]
	v_fma_f32 v46, v116, v114, v70
	v_fma_f32 v47, v117, v115, v71
	v_fma_f32 v50, v108, v110, v74
	v_fma_f32 v51, v109, v111, v75
	v_fmac_f32_dpp v46, v116, v102 row_shr:1 row_mask:0xf bank_mask:0xf bound_ctrl:0
	v_fmac_f32_dpp v47, v117, v103 row_shr:1 row_mask:0xf bank_mask:0xf bound_ctrl:0
	v_fmac_f32_dpp v50, v108, v94 row_shr:1 row_mask:0xf bank_mask:0xf bound_ctrl:0
	v_fmac_f32_dpp v51, v109, v95 row_shr:1 row_mask:0xf bank_mask:0xf bound_ctrl:0
	v_cmp_ne_u32_e32 vcc, 0, v160
	v_fmac_f32_dpp v46, v116, v106 row_shl:1 row_mask:0xf bank_mask:0xf bound_ctrl:0
	v_fmac_f32_dpp v47, v117, v107 row_shl:1 row_mask:0xf bank_mask:0xf bound_ctrl:0
	v_fmac_f32_dpp v50, v108, v98 row_shl:1 row_mask:0xf bank_mask:0xf bound_ctrl:0
	v_fmac_f32_dpp v51, v109, v99 row_shl:1 row_mask:0xf bank_mask:0xf bound_ctrl:0
	s_nop 0
	v_fmac_f32_dpp v46, v112, v130 row_ror:1 row_mask:0xf bank_mask:0xf bound_ctrl:0
	v_fmac_f32_dpp v47, v113, v127 row_ror:1 row_mask:0xf bank_mask:0xf bound_ctrl:0
	v_fmac_f32_dpp v50, v104, v126 row_ror:1 row_mask:0xf bank_mask:0xf bound_ctrl:0
	v_fmac_f32_dpp v51, v105, v124 row_ror:1 row_mask:0xf bank_mask:0xf bound_ctrl:0
	s_nop 0
	v_fmac_f32_dpp v46, v120, v131 row_ror:15 row_mask:0xf bank_mask:0xf bound_ctrl:0
	v_fmac_f32_dpp v47, v121, v129 row_ror:15 row_mask:0xf bank_mask:0xf bound_ctrl:0
	v_fmac_f32_dpp v50, v118, v128 row_ror:15 row_mask:0xf bank_mask:0xf bound_ctrl:0
	v_fmac_f32_dpp v51, v119, v125 row_ror:15 row_mask:0xf bank_mask:0xf bound_ctrl:0
	s_cbranch_vccnz .Lconvgate_fix_19
;     __device__ __forceinline__ void operator()(f32x4 (&acc)[2][2][4][2], const Unit& u, int wr, int wc, int fr, int fq) const {
;     ...
;                 for (int ai = 0; ai < 2; ++ai) {
;                     const int tokbase = u.pm * 248 + 62 * (2 * ai + wr) - 1;
; #pragma unroll
;                     for (int m = 0; m < 4; ++m) {
;                         const int rr = 16 * m + fr, tok = tokbase + rr, pos = tok & Tmask;
;                         const bool lbad = pos == 0, rbad = pos == Tmask;
;                         float uu[2][2];
; #pragma unroll
;                         for (int bj = 0; bj < 2; ++bj) {
;                             const f32x4 c = acc[ai][bj][m][n], cm = acc[ai][bj][m > 0 ? m - 1 : m][n], cp = acc[ai][bj][m < 3 ? m + 1 : m][n];
; #pragma unroll
;                             for (int jj = 0; jj < 2; ++jj) {
;                                 const int j = 2 * jh + jj;
;                                 float t = bb[bj][jj] + w1[bj][jj] * c[j];
;                                 fmac_shr1(t, c[j], w0[bj][jj]);
;                                 fmac_shl1(t, c[j], w2[bj][jj]);
;                                 if (m > 0) fmac_ror1(t, cm[j], w0f[bj][jj]);
;                                 if (m < 3) fmac_ror15(t, cp[j], w2l[bj][jj]);
;                                 uu[bj][jj] = t;
;                             }
;                         }
;                         if (__any(lbad | rbad)) {
.LBB0_843:
	v_fma_f32 v38, v120, v114, v70
	v_fma_f32 v39, v121, v115, v71
	v_fma_f32 v42, v118, v110, v74
	v_fma_f32 v43, v119, v111, v75
	v_fmac_f32_dpp v38, v120, v102 row_shr:1 row_mask:0xf bank_mask:0xf bound_ctrl:0
	v_fmac_f32_dpp v39, v121, v103 row_shr:1 row_mask:0xf bank_mask:0xf bound_ctrl:0
	v_fmac_f32_dpp v42, v118, v94 row_shr:1 row_mask:0xf bank_mask:0xf bound_ctrl:0
	v_fmac_f32_dpp v43, v119, v95 row_shr:1 row_mask:0xf bank_mask:0xf bound_ctrl:0
	v_cmp_ne_u32_e32 vcc, 0, v152
	v_fmac_f32_dpp v38, v120, v106 row_shl:1 row_mask:0xf bank_mask:0xf bound_ctrl:0
	v_fmac_f32_dpp v39, v121, v107 row_shl:1 row_mask:0xf bank_mask:0xf bound_ctrl:0
	v_fmac_f32_dpp v42, v118, v98 row_shl:1 row_mask:0xf bank_mask:0xf bound_ctrl:0
	v_fmac_f32_dpp v43, v119, v99 row_shl:1 row_mask:0xf bank_mask:0xf bound_ctrl:0
	s_nop 0
	v_fmac_f32_dpp v38, v116, v130 row_ror:1 row_mask:0xf bank_mask:0xf bound_ctrl:0
	v_fmac_f32_dpp v39, v117, v127 row_ror:1 row_mask:0xf bank_mask:0xf bound_ctrl:0
	v_fmac_f32_dpp v42, v108, v126 row_ror:1 row_mask:0xf bank_mask:0xf bound_ctrl:0
	v_fmac_f32_dpp v43, v109, v124 row_ror:1 row_mask:0xf bank_mask:0xf bound_ctrl:0
	s_cbranch_vccnz .Lconvgate_fix_20
.LBB0_845:
	v_mov_b32_e32 v135, v134
	v_mov_b32_e32 v91, v90
	v_pk_mul_f32 v[116:117], v[34:35], v[134:135]
	v_pk_mul_f32 v[112:113], v[26:27], v[134:135]
	v_pk_mul_f32 v[108:109], v[30:31], v[90:91]
	v_pk_mul_f32 v[34:35], v[22:23], v[90:91]
	v_fma_f32 v22, v116, v114, v70
	v_fma_f32 v23, v117, v115, v71
	v_fma_f32 v26, v112, v110, v74
	v_fma_f32 v27, v113, v111, v75
	v_fmac_f32_dpp v22, v116, v102 row_shr:1 row_mask:0xf bank_mask:0xf bound_ctrl:0
	v_fmac_f32_dpp v23, v117, v103 row_shr:1 row_mask:0xf bank_mask:0xf bound_ctrl:0
	v_fmac_f32_dpp v26, v112, v94 row_shr:1 row_mask:0xf bank_mask:0xf bound_ctrl:0
	v_fmac_f32_dpp v27, v113, v95 row_shr:1 row_mask:0xf bank_mask:0xf bound_ctrl:0
	v_cmp_ne_u32_e32 vcc, 0, v137
	v_fmac_f32_dpp v22, v116, v106 row_shl:1 row_mask:0xf bank_mask:0xf bound_ctrl:0
	v_fmac_f32_dpp v23, v117, v107 row_shl:1 row_mask:0xf bank_mask:0xf bound_ctrl:0
	v_fmac_f32_dpp v26, v112, v98 row_shl:1 row_mask:0xf bank_mask:0xf bound_ctrl:0
	v_fmac_f32_dpp v27, v113, v99 row_shl:1 row_mask:0xf bank_mask:0xf bound_ctrl:0
	s_nop 0
	v_fmac_f32_dpp v22, v108, v131 row_ror:15 row_mask:0xf bank_mask:0xf bound_ctrl:0
	v_fmac_f32_dpp v23, v109, v129 row_ror:15 row_mask:0xf bank_mask:0xf bound_ctrl:0
	v_fmac_f32_dpp v26, v34, v128 row_ror:15 row_mask:0xf bank_mask:0xf bound_ctrl:0
	v_fmac_f32_dpp v27, v35, v125 row_ror:15 row_mask:0xf bank_mask:0xf bound_ctrl:0
	s_cbranch_vccnz .Lconvgate_fix_21
.LBB0_847:
	v_mov_b32_e32 v87, v86
	v_pk_mul_f32 v[104:105], v[18:19], v[86:87]
	v_pk_mul_f32 v[30:31], v[10:11], v[86:87]
	v_fma_f32 v10, v108, v114, v70
	v_fma_f32 v11, v109, v115, v71
	v_fma_f32 v18, v34, v110, v74
	v_fma_f32 v19, v35, v111, v75
	v_fmac_f32_dpp v10, v108, v102 row_shr:1 row_mask:0xf bank_mask:0xf bound_ctrl:0
	v_fmac_f32_dpp v11, v109, v103 row_shr:1 row_mask:0xf bank_mask:0xf bound_ctrl:0
	v_fmac_f32_dpp v18, v34, v94 row_shr:1 row_mask:0xf bank_mask:0xf bound_ctrl:0
	v_fmac_f32_dpp v19, v35, v95 row_shr:1 row_mask:0xf bank_mask:0xf bound_ctrl:0
	v_cmp_ne_u32_e32 vcc, 0, v136
	v_fmac_f32_dpp v10, v108, v106 row_shl:1 row_mask:0xf bank_mask:0xf bound_ctrl:0
	v_fmac_f32_dpp v11, v109, v107 row_shl:1 row_mask:0xf bank_mask:0xf bound_ctrl:0
	v_fmac_f32_dpp v18, v34, v98 row_shl:1 row_mask:0xf bank_mask:0xf bound_ctrl:0
	v_fmac_f32_dpp v19, v35, v99 row_shl:1 row_mask:0xf bank_mask:0xf bound_ctrl:0
	s_nop 0
	v_fmac_f32_dpp v10, v116, v130 row_ror:1 row_mask:0xf bank_mask:0xf bound_ctrl:0
	v_fmac_f32_dpp v11, v117, v127 row_ror:1 row_mask:0xf bank_mask:0xf bound_ctrl:0
	v_fmac_f32_dpp v18, v112, v126 row_ror:1 row_mask:0xf bank_mask:0xf bound_ctrl:0
	v_fmac_f32_dpp v19, v113, v124 row_ror:1 row_mask:0xf bank_mask:0xf bound_ctrl:0
	s_nop 0
	v_fmac_f32_dpp v10, v104, v131 row_ror:15 row_mask:0xf bank_mask:0xf bound_ctrl:0
	v_fmac_f32_dpp v11, v105, v129 row_ror:15 row_mask:0xf bank_mask:0xf bound_ctrl:0
	v_fmac_f32_dpp v18, v30, v128 row_ror:15 row_mask:0xf bank_mask:0xf bound_ctrl:0
	v_fmac_f32_dpp v19, v31, v125 row_ror:15 row_mask:0xf bank_mask:0xf bound_ctrl:0
	s_cbranch_vccnz .Lconvgate_fix_22
;     __device__ __forceinline__ void operator()(f32x4 (&acc)[2][2][4][2], const Unit& u, int wr, int wc, int fr, int fq) const {
;     ...
;         CONV_WLOAD(0, 0, 0);
; #pragma unroll
;         for (int n = 0; n < 2; ++n) {
;             unsigned stash[2][4];
; #pragma unroll
;             for (int jh = 0; jh < 2; ++jh) {
;                 const int g_ = 2 * n + jh, cb_ = g_ & 1;
;                 if (g_ + 1 < 4) CONV_WLOAD(cb_ ^ 1, (g_ + 1) >> 1, (g_ + 1) & 1);
;                 f32x2 w0[2], w1[2], w2[2], bb[2], w0f[2], w2l[2];
; #pragma unroll
;                 for (int bj = 0; bj < 2; ++bj) { w0[bj] = wq[cb_][bj][0]; w1[bj] = wq[cb_][bj][1]; w2[bj] = wq[cb_][bj][2]; bb[bj] = wq[cb_][bj][3];
;                     w0f[bj] = f0 ? w0[bj] : (f32x2){0.f, 0.f}; w2l[bj] = f15 ? w2[bj] : (f32x2){0.f, 0.f}; }
; #pragma unroll
;                 for (int ai = 0; ai < 2; ++ai) {
;                     const int tokbase = u.pm * 248 + 62 * (2 * ai + wr) - 1;
; #pragma unroll
;                     for (int m = 0; m < 4; ++m) {
;                         const int rr = 16 * m + fr, tok = tokbase + rr, pos = tok & Tmask;
;                         const bool lbad = pos == 0, rbad = pos == Tmask;
;                         float uu[2][2];
; #pragma unroll
;                         for (int bj = 0; bj < 2; ++bj) {
;                             const f32x4 c = acc[ai][bj][m][n], cm = acc[ai][bj][m > 0 ? m - 1 : m][n], cp = acc[ai][bj][m < 3 ? m + 1 : m][n];
; #pragma unroll
;                             for (int jj = 0; jj < 2; ++jj) {
;                                 const int j = 2 * jh + jj;
;                                 float t = bb[bj][jj] + w1[bj][jj] * c[j];
;                                 fmac_shr1(t, c[j], w0[bj][jj]);
;                                 fmac_shl1(t, c[j], w2[bj][jj]);
;                                 if (m > 0) fmac_ror1(t, cm[j], w0f[bj][jj]);
;                                 if (m < 3) fmac_ror15(t, cp[j], w2l[bj][jj]);
;                                 uu[bj][jj] = t;
;                             }
;                         }
;                         if (__any(lbad | rbad)) {
.LBB0_849:
	v_mov_b32_e32 v83, v82
	v_pk_mul_f32 v[116:117], v[6:7], v[82:83]
	v_pk_mul_f32 v[112:113], v[2:3], v[82:83]
	v_fma_f32 v2, v104, v114, v70
	v_fma_f32 v3, v105, v115, v71
	v_fma_f32 v6, v30, v110, v74
	v_fma_f32 v7, v31, v111, v75
	v_fmac_f32_dpp v2, v104, v102 row_shr:1 row_mask:0xf bank_mask:0xf bound_ctrl:0
	v_fmac_f32_dpp v3, v105, v103 row_shr:1 row_mask:0xf bank_mask:0xf bound_ctrl:0
	v_fmac_f32_dpp v6, v30, v94 row_shr:1 row_mask:0xf bank_mask:0xf bound_ctrl:0
	v_fmac_f32_dpp v7, v31, v95 row_shr:1 row_mask:0xf bank_mask:0xf bound_ctrl:0
	v_cmp_ne_u32_e32 vcc, 0, v123
	v_fmac_f32_dpp v2, v104, v106 row_shl:1 row_mask:0xf bank_mask:0xf bound_ctrl:0
	v_fmac_f32_dpp v3, v105, v107 row_shl:1 row_mask:0xf bank_mask:0xf bound_ctrl:0
	v_fmac_f32_dpp v6, v30, v98 row_shl:1 row_mask:0xf bank_mask:0xf bound_ctrl:0
	v_fmac_f32_dpp v7, v31, v99 row_shl:1 row_mask:0xf bank_mask:0xf bound_ctrl:0
	s_nop 0
	v_fmac_f32_dpp v2, v108, v130 row_ror:1 row_mask:0xf bank_mask:0xf bound_ctrl:0
	v_fmac_f32_dpp v3, v109, v127 row_ror:1 row_mask:0xf bank_mask:0xf bound_ctrl:0
	v_fmac_f32_dpp v6, v34, v126 row_ror:1 row_mask:0xf bank_mask:0xf bound_ctrl:0
	v_fmac_f32_dpp v7, v35, v124 row_ror:1 row_mask:0xf bank_mask:0xf bound_ctrl:0
	s_nop 0
	v_fmac_f32_dpp v2, v116, v131 row_ror:15 row_mask:0xf bank_mask:0xf bound_ctrl:0
	v_fmac_f32_dpp v3, v117, v129 row_ror:15 row_mask:0xf bank_mask:0xf bound_ctrl:0
	v_fmac_f32_dpp v6, v112, v128 row_ror:15 row_mask:0xf bank_mask:0xf bound_ctrl:0
	v_fmac_f32_dpp v7, v113, v125 row_ror:15 row_mask:0xf bank_mask:0xf bound_ctrl:0
	s_cbranch_vccnz .Lconvgate_fix_23
.LBB0_851:
	v_fma_f32 v70, v116, v114, v70
	v_fmac_f32_e32 v71, v117, v115
	v_fma_f32 v74, v112, v110, v74
	v_fmac_f32_e32 v75, v113, v111
	v_fmac_f32_dpp v70, v116, v102 row_shr:1 row_mask:0xf bank_mask:0xf bound_ctrl:0
	v_fmac_f32_dpp v71, v117, v103 row_shr:1 row_mask:0xf bank_mask:0xf bound_ctrl:0
	v_fmac_f32_dpp v74, v112, v94 row_shr:1 row_mask:0xf bank_mask:0xf bound_ctrl:0
	v_fmac_f32_dpp v75, v113, v95 row_shr:1 row_mask:0xf bank_mask:0xf bound_ctrl:0
	v_cmp_ne_u32_e32 vcc, 0, v122
	v_fmac_f32_dpp v70, v116, v106 row_shl:1 row_mask:0xf bank_mask:0xf bound_ctrl:0
	v_fmac_f32_dpp v71, v117, v107 row_shl:1 row_mask:0xf bank_mask:0xf bound_ctrl:0
	v_fmac_f32_dpp v74, v112, v98 row_shl:1 row_mask:0xf bank_mask:0xf bound_ctrl:0
	v_fmac_f32_dpp v75, v113, v99 row_shl:1 row_mask:0xf bank_mask:0xf bound_ctrl:0
	s_nop 0
	v_fmac_f32_dpp v70, v104, v130 row_ror:1 row_mask:0xf bank_mask:0xf bound_ctrl:0
	v_fmac_f32_dpp v71, v105, v127 row_ror:1 row_mask:0xf bank_mask:0xf bound_ctrl:0
	v_fmac_f32_dpp v74, v30, v126 row_ror:1 row_mask:0xf bank_mask:0xf bound_ctrl:0
	v_fmac_f32_dpp v75, v31, v124 row_ror:1 row_mask:0xf bank_mask:0xf bound_ctrl:0
	s_cbranch_vccnz .Lconvgate_fix_24
.LBB0_853:
	v_mov_b32_e32 v213, v212
	v_mov_b32_e32 v155, v154
	v_pk_mul_f32 v[68:69], v[68:69], v[212:213]
	v_pk_mul_f32 v[60:61], v[60:61], v[212:213]
	v_pk_mul_f32 v[34:35], v[64:65], v[154:155]
	v_pk_mul_f32 v[30:31], v[56:57], v[154:155]
	s_waitcnt vmcnt(4)
	v_fma_f32 v56, v68, v84, v54
	v_fma_f32 v57, v69, v85, v55
	s_waitcnt vmcnt(0)
	v_fma_f32 v64, v60, v80, v58
	v_fma_f32 v65, v61, v81, v59
	v_fmac_f32_dpp v56, v68, v76 row_shr:1 row_mask:0xf bank_mask:0xf bound_ctrl:0
	v_fmac_f32_dpp v57, v69, v77 row_shr:1 row_mask:0xf bank_mask:0xf bound_ctrl:0
	v_fmac_f32_dpp v64, v60, v66 row_shr:1 row_mask:0xf bank_mask:0xf bound_ctrl:0
	v_fmac_f32_dpp v65, v61, v67 row_shr:1 row_mask:0xf bank_mask:0xf bound_ctrl:0
	v_cndmask_b32_e64 v99, 0, v73, s[42:43]
	v_cndmask_b32_e64 v102, 0, v72, s[42:43]
	v_cndmask_b32_e64 v95, 0, v63, s[42:43]
	v_cndmask_b32_e64 v98, 0, v62, s[42:43]
	v_fmac_f32_dpp v56, v68, v72 row_shl:1 row_mask:0xf bank_mask:0xf bound_ctrl:0
	v_fmac_f32_dpp v57, v69, v73 row_shl:1 row_mask:0xf bank_mask:0xf bound_ctrl:0
	v_fmac_f32_dpp v64, v60, v62 row_shl:1 row_mask:0xf bank_mask:0xf bound_ctrl:0
	v_fmac_f32_dpp v65, v61, v63 row_shl:1 row_mask:0xf bank_mask:0xf bound_ctrl:0
	v_cmp_ne_u32_e32 vcc, 0, v167
	v_fmac_f32_dpp v56, v34, v102 row_ror:15 row_mask:0xf bank_mask:0xf bound_ctrl:0
	v_fmac_f32_dpp v57, v35, v99 row_ror:15 row_mask:0xf bank_mask:0xf bound_ctrl:0
	v_fmac_f32_dpp v64, v30, v98 row_ror:15 row_mask:0xf bank_mask:0xf bound_ctrl:0
	v_fmac_f32_dpp v65, v31, v95 row_ror:15 row_mask:0xf bank_mask:0xf bound_ctrl:0
	s_cbranch_vccnz .Lconvgate_fix_25

;     __device__ __forceinline__ void operator()(f32x4 (&acc)[2][2][4][2], const Unit& u, int wr, int wc, int fr, int fq) const {
;     ...
;                 for (int ai = 0; ai < 2; ++ai) {
;                     const int tokbase = u.pm * 248 + 62 * (2 * ai + wr) - 1;
; #pragma unroll
;                     for (int m = 0; m < 4; ++m) {
;                         const int rr = 16 * m + fr, tok = tokbase + rr, pos = tok & Tmask;
;                         const bool lbad = pos == 0, rbad = pos == Tmask;
;                         float uu[2][2];
; #pragma unroll
;                         for (int bj = 0; bj < 2; ++bj) {
;                             const f32x4 c = acc[ai][bj][m][n], cm = acc[ai][bj][m > 0 ? m - 1 : m][n], cp = acc[ai][bj][m < 3 ? m + 1 : m][n];
; #pragma unroll
;                             for (int jj = 0; jj < 2; ++jj) {
;                                 const int j = 2 * jh + jj;
;                                 float t = bb[bj][jj] + w1[bj][jj] * c[j];
;                                 fmac_shr1(t, c[j], w0[bj][jj]);
;                                 fmac_shl1(t, c[j], w2[bj][jj]);
;                                 if (m > 0) fmac_ror1(t, cm[j], w0f[bj][jj]);
;                                 if (m < 3) fmac_ror15(t, cp[j], w2l[bj][jj]);
;                                 uu[bj][jj] = t;
;                             }
;                         }
;                         if (__any(lbad | rbad)) {
.LBB0_857:
	s_or_b64 exec, exec, s[80:81]
	v_mov_b32_e32 v151, v150
	v_pk_mul_f32 v[52:53], v[52:53], v[150:151]
	v_pk_mul_f32 v[48:49], v[48:49], v[150:151]
	v_cndmask_b32_e64 v97, 0, v77, s[44:45]
	v_cndmask_b32_e64 v100, 0, v76, s[44:45]
	v_cndmask_b32_e64 v94, 0, v67, s[44:45]
	v_cndmask_b32_e64 v96, 0, v66, s[44:45]
	v_fma_f32 v56, v34, v84, v54
	v_fma_f32 v57, v35, v85, v55
	v_fma_f32 v64, v30, v80, v58
	v_fma_f32 v65, v31, v81, v59
	v_fmac_f32_dpp v56, v34, v76 row_shr:1 row_mask:0xf bank_mask:0xf bound_ctrl:0
	v_fmac_f32_dpp v57, v35, v77 row_shr:1 row_mask:0xf bank_mask:0xf bound_ctrl:0
	v_fmac_f32_dpp v64, v30, v66 row_shr:1 row_mask:0xf bank_mask:0xf bound_ctrl:0
	v_fmac_f32_dpp v65, v31, v67 row_shr:1 row_mask:0xf bank_mask:0xf bound_ctrl:0
	v_cmp_ne_u32_e32 vcc, 0, v166
	v_fmac_f32_dpp v56, v34, v72 row_shl:1 row_mask:0xf bank_mask:0xf bound_ctrl:0
	v_fmac_f32_dpp v57, v35, v73 row_shl:1 row_mask:0xf bank_mask:0xf bound_ctrl:0
	v_fmac_f32_dpp v64, v30, v62 row_shl:1 row_mask:0xf bank_mask:0xf bound_ctrl:0
	v_fmac_f32_dpp v65, v31, v63 row_shl:1 row_mask:0xf bank_mask:0xf bound_ctrl:0
	s_nop 0
	v_fmac_f32_dpp v56, v68, v100 row_ror:1 row_mask:0xf bank_mask:0xf bound_ctrl:0
	v_fmac_f32_dpp v57, v69, v97 row_ror:1 row_mask:0xf bank_mask:0xf bound_ctrl:0
	v_fmac_f32_dpp v64, v60, v96 row_ror:1 row_mask:0xf bank_mask:0xf bound_ctrl:0
	v_fmac_f32_dpp v65, v61, v94 row_ror:1 row_mask:0xf bank_mask:0xf bound_ctrl:0
	s_nop 0
	v_fmac_f32_dpp v56, v52, v102 row_ror:15 row_mask:0xf bank_mask:0xf bound_ctrl:0
	v_fmac_f32_dpp v57, v53, v99 row_ror:15 row_mask:0xf bank_mask:0xf bound_ctrl:0
	v_fmac_f32_dpp v64, v48, v98 row_ror:15 row_mask:0xf bank_mask:0xf bound_ctrl:0
	v_fmac_f32_dpp v65, v49, v95 row_ror:15 row_mask:0xf bank_mask:0xf bound_ctrl:0
	s_cbranch_vccnz .Lconvgate_fix_26

;     __device__ __forceinline__ void operator()(f32x4 (&acc)[2][2][4][2], const Unit& u, int wr, int wc, int fr, int fq) const {
;     ...
;                 for (int ai = 0; ai < 2; ++ai) {
;                     const int tokbase = u.pm * 248 + 62 * (2 * ai + wr) - 1;
; #pragma unroll
;                     for (int m = 0; m < 4; ++m) {
;                         const int rr = 16 * m + fr, tok = tokbase + rr, pos = tok & Tmask;
;                         const bool lbad = pos == 0, rbad = pos == Tmask;
;                         float uu[2][2];
; #pragma unroll
;                         for (int bj = 0; bj < 2; ++bj) {
;                             const f32x4 c = acc[ai][bj][m][n], cm = acc[ai][bj][m > 0 ? m - 1 : m][n], cp = acc[ai][bj][m < 3 ? m + 1 : m][n];
; #pragma unroll
;                             for (int jj = 0; jj < 2; ++jj) {
;                                 const int j = 2 * jh + jj;
;                                 float t = bb[bj][jj] + w1[bj][jj] * c[j];
;                                 fmac_shr1(t, c[j], w0[bj][jj]);
;                                 fmac_shl1(t, c[j], w2[bj][jj]);
;                                 if (m > 0) fmac_ror1(t, cm[j], w0f[bj][jj]);
;                                 if (m < 3) fmac_ror15(t, cp[j], w2l[bj][jj]);
;                                 uu[bj][jj] = t;
;                             }
;                         }
;                         if (__any(lbad | rbad)) {
.LBB0_861:
	s_or_b64 exec, exec, s[40:41]
	v_mov_b32_e32 v143, v142
	v_pk_mul_f32 v[44:45], v[44:45], v[142:143]
	v_pk_mul_f32 v[40:41], v[40:41], v[142:143]
	v_fma_f32 v56, v52, v84, v54
	v_fma_f32 v57, v53, v85, v55
	v_fma_f32 v60, v48, v80, v58
	v_fma_f32 v61, v49, v81, v59
	v_fmac_f32_dpp v56, v52, v76 row_shr:1 row_mask:0xf bank_mask:0xf bound_ctrl:0
	v_fmac_f32_dpp v57, v53, v77 row_shr:1 row_mask:0xf bank_mask:0xf bound_ctrl:0
	v_fmac_f32_dpp v60, v48, v66 row_shr:1 row_mask:0xf bank_mask:0xf bound_ctrl:0
	v_fmac_f32_dpp v61, v49, v67 row_shr:1 row_mask:0xf bank_mask:0xf bound_ctrl:0
	v_readlane_b32 s90, v254, 55
	v_fmac_f32_dpp v56, v52, v72 row_shl:1 row_mask:0xf bank_mask:0xf bound_ctrl:0
	v_fmac_f32_dpp v57, v53, v73 row_shl:1 row_mask:0xf bank_mask:0xf bound_ctrl:0
	v_fmac_f32_dpp v60, v48, v62 row_shl:1 row_mask:0xf bank_mask:0xf bound_ctrl:0
	v_fmac_f32_dpp v61, v49, v63 row_shl:1 row_mask:0xf bank_mask:0xf bound_ctrl:0
	v_cmp_ne_u32_e32 vcc, 0, v160
	v_fmac_f32_dpp v56, v34, v100 row_ror:1 row_mask:0xf bank_mask:0xf bound_ctrl:0
	v_fmac_f32_dpp v57, v35, v97 row_ror:1 row_mask:0xf bank_mask:0xf bound_ctrl:0
	v_fmac_f32_dpp v60, v30, v96 row_ror:1 row_mask:0xf bank_mask:0xf bound_ctrl:0
	v_fmac_f32_dpp v61, v31, v94 row_ror:1 row_mask:0xf bank_mask:0xf bound_ctrl:0
	v_readlane_b32 s91, v254, 56
	v_fmac_f32_dpp v56, v44, v102 row_ror:15 row_mask:0xf bank_mask:0xf bound_ctrl:0
	v_fmac_f32_dpp v57, v45, v99 row_ror:15 row_mask:0xf bank_mask:0xf bound_ctrl:0
	v_fmac_f32_dpp v60, v40, v98 row_ror:15 row_mask:0xf bank_mask:0xf bound_ctrl:0
	v_fmac_f32_dpp v61, v41, v95 row_ror:15 row_mask:0xf bank_mask:0xf bound_ctrl:0
	s_cbranch_vccnz .Lconvgate_fix_27

;     __device__ __forceinline__ void operator()(f32x4 (&acc)[2][2][4][2], const Unit& u, int wr, int wc, int fr, int fq) const {
;     ...
;                 for (int ai = 0; ai < 2; ++ai) {
;                     const int tokbase = u.pm * 248 + 62 * (2 * ai + wr) - 1;
; #pragma unroll
;                     for (int m = 0; m < 4; ++m) {
;                         const int rr = 16 * m + fr, tok = tokbase + rr, pos = tok & Tmask;
;                         const bool lbad = pos == 0, rbad = pos == Tmask;
;                         float uu[2][2];
; #pragma unroll
;                         for (int bj = 0; bj < 2; ++bj) {
;                             const f32x4 c = acc[ai][bj][m][n], cm = acc[ai][bj][m > 0 ? m - 1 : m][n], cp = acc[ai][bj][m < 3 ? m + 1 : m][n];
; #pragma unroll
;                             for (int jj = 0; jj < 2; ++jj) {
;                                 const int j = 2 * jh + jj;
;                                 float t = bb[bj][jj] + w1[bj][jj] * c[j];
;                                 fmac_shr1(t, c[j], w0[bj][jj]);
;                                 fmac_shl1(t, c[j], w2[bj][jj]);
;                                 if (m > 0) fmac_ror1(t, cm[j], w0f[bj][jj]);
;                                 if (m < 3) fmac_ror15(t, cp[j], w2l[bj][jj]);
;                                 uu[bj][jj] = t;
;                             }
;                         }
;                         if (__any(lbad | rbad)) {
.LBB0_865:
	s_or_b64 exec, exec, s[40:41]
	v_fma_f32 v30, v44, v84, v54
	v_fma_f32 v31, v45, v85, v55
	v_fma_f32 v34, v40, v80, v58
	v_fma_f32 v35, v41, v81, v59
	v_fmac_f32_dpp v30, v44, v76 row_shr:1 row_mask:0xf bank_mask:0xf bound_ctrl:0
	v_fmac_f32_dpp v31, v45, v77 row_shr:1 row_mask:0xf bank_mask:0xf bound_ctrl:0
	v_fmac_f32_dpp v34, v40, v66 row_shr:1 row_mask:0xf bank_mask:0xf bound_ctrl:0
	v_fmac_f32_dpp v35, v41, v67 row_shr:1 row_mask:0xf bank_mask:0xf bound_ctrl:0
	v_cmp_ne_u32_e32 vcc, 0, v152
	v_fmac_f32_dpp v30, v44, v72 row_shl:1 row_mask:0xf bank_mask:0xf bound_ctrl:0
	v_fmac_f32_dpp v31, v45, v73 row_shl:1 row_mask:0xf bank_mask:0xf bound_ctrl:0
	v_fmac_f32_dpp v34, v40, v62 row_shl:1 row_mask:0xf bank_mask:0xf bound_ctrl:0
	v_fmac_f32_dpp v35, v41, v63 row_shl:1 row_mask:0xf bank_mask:0xf bound_ctrl:0
	v_readlane_b32 s88, v254, 41
	v_fmac_f32_dpp v30, v52, v100 row_ror:1 row_mask:0xf bank_mask:0xf bound_ctrl:0
	v_fmac_f32_dpp v31, v53, v97 row_ror:1 row_mask:0xf bank_mask:0xf bound_ctrl:0
	v_fmac_f32_dpp v34, v48, v96 row_ror:1 row_mask:0xf bank_mask:0xf bound_ctrl:0
	v_fmac_f32_dpp v35, v49, v94 row_ror:1 row_mask:0xf bank_mask:0xf bound_ctrl:0
	v_readlane_b32 s89, v254, 42
	s_cbranch_vccnz .Lconvgate_fix_28

;     __device__ __forceinline__ void operator()(f32x4 (&acc)[2][2][4][2], const Unit& u, int wr, int wc, int fr, int fq) const {
;     ...
;                 for (int ai = 0; ai < 2; ++ai) {
;                     const int tokbase = u.pm * 248 + 62 * (2 * ai + wr) - 1;
; #pragma unroll
;                     for (int m = 0; m < 4; ++m) {
;                         const int rr = 16 * m + fr, tok = tokbase + rr, pos = tok & Tmask;
;                         const bool lbad = pos == 0, rbad = pos == Tmask;
;                         float uu[2][2];
; #pragma unroll
;                         for (int bj = 0; bj < 2; ++bj) {
;                             const f32x4 c = acc[ai][bj][m][n], cm = acc[ai][bj][m > 0 ? m - 1 : m][n], cp = acc[ai][bj][m < 3 ? m + 1 : m][n];
; #pragma unroll
;                             for (int jj = 0; jj < 2; ++jj) {
;                                 const int j = 2 * jh + jj;
;                                 float t = bb[bj][jj] + w1[bj][jj] * c[j];
;                                 fmac_shr1(t, c[j], w0[bj][jj]);
;                                 fmac_shl1(t, c[j], w2[bj][jj]);
;                                 if (m > 0) fmac_ror1(t, cm[j], w0f[bj][jj]);
;                                 if (m < 3) fmac_ror15(t, cp[j], w2l[bj][jj]);
;                                 uu[bj][jj] = t;
;                             }
;                         }
;                         if (__any(lbad | rbad)) {
.LBB0_869:
	s_or_b64 exec, exec, s[40:41]
	v_mov_b32_e32 v135, v134
	v_mov_b32_e32 v91, v90
	v_pk_mul_f32 v[34:35], v[36:37], v[134:135]
	v_pk_mul_f32 v[30:31], v[28:29], v[134:135]
	v_pk_mul_f32 v[28:29], v[32:33], v[90:91]
	v_pk_mul_f32 v[24:25], v[24:25], v[90:91]
	v_fma_f32 v32, v34, v84, v54
	v_fma_f32 v33, v35, v85, v55
	v_fma_f32 v36, v30, v80, v58
	v_fma_f32 v37, v31, v81, v59
	v_fmac_f32_dpp v32, v34, v76 row_shr:1 row_mask:0xf bank_mask:0xf bound_ctrl:0
	v_fmac_f32_dpp v33, v35, v77 row_shr:1 row_mask:0xf bank_mask:0xf bound_ctrl:0
	v_fmac_f32_dpp v36, v30, v66 row_shr:1 row_mask:0xf bank_mask:0xf bound_ctrl:0
	v_fmac_f32_dpp v37, v31, v67 row_shr:1 row_mask:0xf bank_mask:0xf bound_ctrl:0
	v_cmp_ne_u32_e32 vcc, 0, v137
	v_fmac_f32_dpp v32, v34, v72 row_shl:1 row_mask:0xf bank_mask:0xf bound_ctrl:0
	v_fmac_f32_dpp v33, v35, v73 row_shl:1 row_mask:0xf bank_mask:0xf bound_ctrl:0
	v_fmac_f32_dpp v36, v30, v62 row_shl:1 row_mask:0xf bank_mask:0xf bound_ctrl:0
	v_fmac_f32_dpp v37, v31, v63 row_shl:1 row_mask:0xf bank_mask:0xf bound_ctrl:0
	s_nop 0
	v_fmac_f32_dpp v32, v28, v102 row_ror:15 row_mask:0xf bank_mask:0xf bound_ctrl:0
	v_fmac_f32_dpp v33, v29, v99 row_ror:15 row_mask:0xf bank_mask:0xf bound_ctrl:0
	v_fmac_f32_dpp v36, v24, v98 row_ror:15 row_mask:0xf bank_mask:0xf bound_ctrl:0
	v_fmac_f32_dpp v37, v25, v95 row_ror:15 row_mask:0xf bank_mask:0xf bound_ctrl:0
	s_cbranch_vccnz .Lconvgate_fix_29

;     __device__ __forceinline__ void operator()(f32x4 (&acc)[2][2][4][2], const Unit& u, int wr, int wc, int fr, int fq) const {
;     ...
;                 for (int ai = 0; ai < 2; ++ai) {
;                     const int tokbase = u.pm * 248 + 62 * (2 * ai + wr) - 1;
; #pragma unroll
;                     for (int m = 0; m < 4; ++m) {
;                         const int rr = 16 * m + fr, tok = tokbase + rr, pos = tok & Tmask;
;                         const bool lbad = pos == 0, rbad = pos == Tmask;
;                         float uu[2][2];
; #pragma unroll
;                         for (int bj = 0; bj < 2; ++bj) {
;                             const f32x4 c = acc[ai][bj][m][n], cm = acc[ai][bj][m > 0 ? m - 1 : m][n], cp = acc[ai][bj][m < 3 ? m + 1 : m][n];
; #pragma unroll
;                             for (int jj = 0; jj < 2; ++jj) {
;                                 const int j = 2 * jh + jj;
;                                 float t = bb[bj][jj] + w1[bj][jj] * c[j];
;                                 fmac_shr1(t, c[j], w0[bj][jj]);
;                                 fmac_shl1(t, c[j], w2[bj][jj]);
;                                 if (m > 0) fmac_ror1(t, cm[j], w0f[bj][jj]);
;                                 if (m < 3) fmac_ror15(t, cp[j], w2l[bj][jj]);
;                                 uu[bj][jj] = t;
;                             }
;                         }
;                         if (__any(lbad | rbad)) {
.LBB0_873:
	s_or_b64 exec, exec, s[22:23]
	v_mov_b32_e32 v87, v86
	v_pk_mul_f32 v[20:21], v[20:21], v[86:87]
	v_pk_mul_f32 v[12:13], v[12:13], v[86:87]
	v_fma_f32 v22, v28, v84, v54
	v_fma_f32 v23, v29, v85, v55
	v_fma_f32 v26, v24, v80, v58
	v_fma_f32 v27, v25, v81, v59
	v_fmac_f32_dpp v22, v28, v76 row_shr:1 row_mask:0xf bank_mask:0xf bound_ctrl:0
	v_fmac_f32_dpp v23, v29, v77 row_shr:1 row_mask:0xf bank_mask:0xf bound_ctrl:0
	v_fmac_f32_dpp v26, v24, v66 row_shr:1 row_mask:0xf bank_mask:0xf bound_ctrl:0
	v_fmac_f32_dpp v27, v25, v67 row_shr:1 row_mask:0xf bank_mask:0xf bound_ctrl:0
	v_cmp_ne_u32_e32 vcc, 0, v136
	v_fmac_f32_dpp v22, v28, v72 row_shl:1 row_mask:0xf bank_mask:0xf bound_ctrl:0
	v_fmac_f32_dpp v23, v29, v73 row_shl:1 row_mask:0xf bank_mask:0xf bound_ctrl:0
	v_fmac_f32_dpp v26, v24, v62 row_shl:1 row_mask:0xf bank_mask:0xf bound_ctrl:0
	v_fmac_f32_dpp v27, v25, v63 row_shl:1 row_mask:0xf bank_mask:0xf bound_ctrl:0
	s_nop 0
	v_fmac_f32_dpp v22, v34, v100 row_ror:1 row_mask:0xf bank_mask:0xf bound_ctrl:0
	v_fmac_f32_dpp v23, v35, v97 row_ror:1 row_mask:0xf bank_mask:0xf bound_ctrl:0
	v_fmac_f32_dpp v26, v30, v96 row_ror:1 row_mask:0xf bank_mask:0xf bound_ctrl:0
	v_fmac_f32_dpp v27, v31, v94 row_ror:1 row_mask:0xf bank_mask:0xf bound_ctrl:0
	s_nop 0
	v_fmac_f32_dpp v22, v20, v102 row_ror:15 row_mask:0xf bank_mask:0xf bound_ctrl:0
	v_fmac_f32_dpp v23, v21, v99 row_ror:15 row_mask:0xf bank_mask:0xf bound_ctrl:0
	v_fmac_f32_dpp v26, v12, v98 row_ror:15 row_mask:0xf bank_mask:0xf bound_ctrl:0
	v_fmac_f32_dpp v27, v13, v95 row_ror:15 row_mask:0xf bank_mask:0xf bound_ctrl:0
	s_cbranch_vccnz .Lconvgate_fix_30

;     __device__ __forceinline__ void operator()(f32x4 (&acc)[2][2][4][2], const Unit& u, int wr, int wc, int fr, int fq) const {
;     ...
;                 for (int ai = 0; ai < 2; ++ai) {
;                     const int tokbase = u.pm * 248 + 62 * (2 * ai + wr) - 1;
; #pragma unroll
;                     for (int m = 0; m < 4; ++m) {
;                         const int rr = 16 * m + fr, tok = tokbase + rr, pos = tok & Tmask;
;                         const bool lbad = pos == 0, rbad = pos == Tmask;
;                         float uu[2][2];
; #pragma unroll
;                         for (int bj = 0; bj < 2; ++bj) {
;                             const f32x4 c = acc[ai][bj][m][n], cm = acc[ai][bj][m > 0 ? m - 1 : m][n], cp = acc[ai][bj][m < 3 ? m + 1 : m][n];
; #pragma unroll
;                             for (int jj = 0; jj < 2; ++jj) {
;                                 const int j = 2 * jh + jj;
;                                 float t = bb[bj][jj] + w1[bj][jj] * c[j];
;                                 fmac_shr1(t, c[j], w0[bj][jj]);
;                                 fmac_shl1(t, c[j], w2[bj][jj]);
;                                 if (m > 0) fmac_ror1(t, cm[j], w0f[bj][jj]);
;                                 if (m < 3) fmac_ror15(t, cp[j], w2l[bj][jj]);
;                                 uu[bj][jj] = t;
;                             }
;                         }
;                         if (__any(lbad | rbad)) {
.LBB0_877:
	s_or_b64 exec, exec, s[20:21]
	v_mov_b32_e32 v83, v82
	v_pk_mul_f32 v[8:9], v[8:9], v[82:83]
	v_pk_mul_f32 v[4:5], v[4:5], v[82:83]
	v_fma_f32 v10, v20, v84, v54
	v_fma_f32 v11, v21, v85, v55
	v_fma_f32 v18, v12, v80, v58
	v_fma_f32 v19, v13, v81, v59
	v_fmac_f32_dpp v10, v20, v76 row_shr:1 row_mask:0xf bank_mask:0xf bound_ctrl:0
	v_fmac_f32_dpp v11, v21, v77 row_shr:1 row_mask:0xf bank_mask:0xf bound_ctrl:0
	v_fmac_f32_dpp v18, v12, v66 row_shr:1 row_mask:0xf bank_mask:0xf bound_ctrl:0
	v_fmac_f32_dpp v19, v13, v67 row_shr:1 row_mask:0xf bank_mask:0xf bound_ctrl:0
	v_cmp_ne_u32_e32 vcc, 0, v123
	v_fmac_f32_dpp v10, v20, v72 row_shl:1 row_mask:0xf bank_mask:0xf bound_ctrl:0
	v_fmac_f32_dpp v11, v21, v73 row_shl:1 row_mask:0xf bank_mask:0xf bound_ctrl:0
	v_fmac_f32_dpp v18, v12, v62 row_shl:1 row_mask:0xf bank_mask:0xf bound_ctrl:0
	v_fmac_f32_dpp v19, v13, v63 row_shl:1 row_mask:0xf bank_mask:0xf bound_ctrl:0
	v_readlane_b32 s86, v254, 39
	v_fmac_f32_dpp v10, v28, v100 row_ror:1 row_mask:0xf bank_mask:0xf bound_ctrl:0
	v_fmac_f32_dpp v11, v29, v97 row_ror:1 row_mask:0xf bank_mask:0xf bound_ctrl:0
	v_fmac_f32_dpp v18, v24, v96 row_ror:1 row_mask:0xf bank_mask:0xf bound_ctrl:0
	v_fmac_f32_dpp v19, v25, v94 row_ror:1 row_mask:0xf bank_mask:0xf bound_ctrl:0
	v_readlane_b32 s87, v254, 40
	v_fmac_f32_dpp v10, v8, v102 row_ror:15 row_mask:0xf bank_mask:0xf bound_ctrl:0
	v_fmac_f32_dpp v11, v9, v99 row_ror:15 row_mask:0xf bank_mask:0xf bound_ctrl:0
	v_fmac_f32_dpp v18, v4, v98 row_ror:15 row_mask:0xf bank_mask:0xf bound_ctrl:0
	v_fmac_f32_dpp v19, v5, v95 row_ror:15 row_mask:0xf bank_mask:0xf bound_ctrl:0
	s_cbranch_vccnz .Lconvgate_fix_31

;     __device__ __forceinline__ void operator()(f32x4 (&acc)[2][2][4][2], const Unit& u, int wr, int wc, int fr, int fq) const {
;     ...
;                 for (int ai = 0; ai < 2; ++ai) {
;                     const int tokbase = u.pm * 248 + 62 * (2 * ai + wr) - 1;
; #pragma unroll
;                     for (int m = 0; m < 4; ++m) {
;                         const int rr = 16 * m + fr, tok = tokbase + rr, pos = tok & Tmask;
;                         const bool lbad = pos == 0, rbad = pos == Tmask;
;                         float uu[2][2];
; #pragma unroll
;                         for (int bj = 0; bj < 2; ++bj) {
;                             const f32x4 c = acc[ai][bj][m][n], cm = acc[ai][bj][m > 0 ? m - 1 : m][n], cp = acc[ai][bj][m < 3 ? m + 1 : m][n];
; #pragma unroll
;                             for (int jj = 0; jj < 2; ++jj) {
;                                 const int j = 2 * jh + jj;
;                                 float t = bb[bj][jj] + w1[bj][jj] * c[j];
;                                 fmac_shr1(t, c[j], w0[bj][jj]);
;                                 fmac_shl1(t, c[j], w2[bj][jj]);
;                                 if (m > 0) fmac_ror1(t, cm[j], w0f[bj][jj]);
;                                 if (m < 3) fmac_ror15(t, cp[j], w2l[bj][jj]);
;                                 uu[bj][jj] = t;
;                             }
;                         }
;                         if (__any(lbad | rbad)) {
.LBB0_881:
	s_or_b64 exec, exec, s[20:21]
	v_fma_f32 v54, v8, v84, v54
	v_fmac_f32_e32 v55, v9, v85
	v_fma_f32 v58, v4, v80, v58
	v_fmac_f32_e32 v59, v5, v81
	v_fmac_f32_dpp v54, v8, v76 row_shr:1 row_mask:0xf bank_mask:0xf bound_ctrl:0
	v_fmac_f32_dpp v55, v9, v77 row_shr:1 row_mask:0xf bank_mask:0xf bound_ctrl:0
	v_fmac_f32_dpp v58, v4, v66 row_shr:1 row_mask:0xf bank_mask:0xf bound_ctrl:0
	v_fmac_f32_dpp v59, v5, v67 row_shr:1 row_mask:0xf bank_mask:0xf bound_ctrl:0
	v_readlane_b32 s80, v254, 51
	v_readlane_b32 s84, v254, 53
	v_fmac_f32_dpp v54, v8, v72 row_shl:1 row_mask:0xf bank_mask:0xf bound_ctrl:0
	v_fmac_f32_dpp v55, v9, v73 row_shl:1 row_mask:0xf bank_mask:0xf bound_ctrl:0
	v_fmac_f32_dpp v58, v4, v62 row_shl:1 row_mask:0xf bank_mask:0xf bound_ctrl:0
	v_fmac_f32_dpp v59, v5, v63 row_shl:1 row_mask:0xf bank_mask:0xf bound_ctrl:0
	v_cmp_ne_u32_e32 vcc, 0, v122
	v_readlane_b32 s81, v254, 52
	v_readlane_b32 s85, v254, 54
	v_fmac_f32_dpp v54, v20, v100 row_ror:1 row_mask:0xf bank_mask:0xf bound_ctrl:0
	v_fmac_f32_dpp v55, v21, v97 row_ror:1 row_mask:0xf bank_mask:0xf bound_ctrl:0
	v_fmac_f32_dpp v58, v12, v96 row_ror:1 row_mask:0xf bank_mask:0xf bound_ctrl:0
	v_fmac_f32_dpp v59, v13, v94 row_ror:1 row_mask:0xf bank_mask:0xf bound_ctrl:0
	s_cbranch_vccnz .Lconvgate_fix_32

; __device__ __forceinline__ float dpp_ror1(float v) { return __int_as_float(__builtin_amdgcn_update_dpp(0, __float_as_int(v), 0x121, 0xF, 0xF, false)); }
; __device__ __forceinline__ float dpp_ror15(float v) { return __int_as_float(__builtin_amdgcn_update_dpp(0, __float_as_int(v), 0x12F, 0xF, 0xF, false)); }
;     __device__ __forceinline__ void operator()(f32x4 (&acc)[2][2][4][2], const Unit& u, int wr, int wc, int fr, int fq) const {
;     ...
;                         if (__any(lbad | rbad)) {
; #pragma unroll
;                             for (int bj = 0; bj < 2; ++bj) {
;                                 const f32x4 c = acc[ai][bj][m][n], cm = acc[ai][bj][m > 0 ? m - 1 : m][n], cp = acc[ai][bj][m < 3 ? m + 1 : m][n];
; #pragma unroll
;                                 for (int jj = 0; jj < 2; ++jj) {
;                                     const int j = 2 * jh + jj;
;                                     const float up = dpp_ror1(f15 ? cm[j] : c[j]), dn = dpp_ror15(f0 ? cp[j] : c[j]);
;                                     uu[bj][jj] -= (lbad ? w0[bj][jj] * up : 0.f) + (rbad ? w2[bj][jj] * dn : 0.f);
;                                 }
;                             }
;                         }
.Lconvgate_fix_1:
	v_cndmask_b32_e64 v150, v228, v162, s[44:45]
	v_mov_b32_e32 v216, v1
	v_mov_b32_e32 v208, v1
	v_mov_b32_e32 v209, v1
	v_mov_b32_dpp v216, v150 row_ror:15 row_mask:0xf bank_mask:0xf
	v_cndmask_b32_e64 v150, v229, v163, s[44:45]
	v_mov_b32_e32 v217, v1
	v_mov_b32_dpp v208, v228 row_ror:1 row_mask:0xf bank_mask:0xf
	v_mov_b32_dpp v209, v229 row_ror:1 row_mask:0xf bank_mask:0xf
	v_mov_b32_dpp v217, v150 row_ror:15 row_mask:0xf bank_mask:0xf
	v_pk_mul_f32 v[208:209], v[122:123], v[208:209]
	v_pk_mul_f32 v[216:217], v[114:115], v[216:217]
	v_cndmask_b32_e64 v209, 0, v209, s[82:83]
	v_cndmask_b32_e64 v208, 0, v208, s[82:83]
	v_cndmask_b32_e64 v217, 0, v217, s[80:81]
	v_cndmask_b32_e64 v216, 0, v216, s[80:81]
	v_pk_add_f32 v[208:209], v[208:209], v[216:217]
	v_cndmask_b32_e64 v150, v224, v158, s[44:45]
	v_mov_b32_e32 v216, v1
	v_pk_add_f32 v[220:221], v[220:221], v[208:209] neg_lo:[0,1] neg_hi:[0,1]
	v_mov_b32_e32 v208, v1
	v_mov_b32_dpp v216, v150 row_ror:15 row_mask:0xf bank_mask:0xf
	v_mov_b32_e32 v209, v1
	v_cndmask_b32_e64 v150, v225, v159, s[44:45]
	v_mov_b32_e32 v217, v1
	v_mov_b32_dpp v208, v224 row_ror:1 row_mask:0xf bank_mask:0xf
	v_mov_b32_dpp v209, v225 row_ror:1 row_mask:0xf bank_mask:0xf
	v_mov_b32_dpp v217, v150 row_ror:15 row_mask:0xf bank_mask:0xf
	v_pk_mul_f32 v[208:209], v[118:119], v[208:209]
	v_pk_mul_f32 v[216:217], v[110:111], v[216:217]
	v_cndmask_b32_e64 v209, 0, v209, s[82:83]
	v_cndmask_b32_e64 v208, 0, v208, s[82:83]
	v_cndmask_b32_e64 v217, 0, v217, s[80:81]
	v_cndmask_b32_e64 v216, 0, v216, s[80:81]
	v_pk_add_f32 v[208:209], v[208:209], v[216:217]
	s_nop 0
	v_pk_add_f32 v[222:223], v[222:223], v[208:209] neg_lo:[0,1] neg_hi:[0,1]
	s_branch .LBB0_791
.Lconvgate_fix_2:
	v_cndmask_b32_e64 v142, v162, v228, s[42:43]
	v_mov_b32_e32 v184, v1
	v_mov_b32_e32 v186, v1
	v_mov_b32_e32 v185, v1
	v_mov_b32_dpp v184, v142 row_ror:1 row_mask:0xf bank_mask:0xf
	v_cndmask_b32_e64 v142, v162, v226, s[44:45]
	v_mov_b32_e32 v187, v1
	s_nop 0
	v_mov_b32_dpp v186, v142 row_ror:15 row_mask:0xf bank_mask:0xf
	v_cndmask_b32_e64 v142, v163, v229, s[42:43]
	s_nop 1
	v_mov_b32_dpp v185, v142 row_ror:1 row_mask:0xf bank_mask:0xf
	v_cndmask_b32_e64 v142, v163, v227, s[44:45]
	v_pk_mul_f32 v[184:185], v[122:123], v[184:185]
	s_nop 0
	v_mov_b32_dpp v187, v142 row_ror:15 row_mask:0xf bank_mask:0xf
	v_pk_mul_f32 v[186:187], v[114:115], v[186:187]
	v_cndmask_b32_e64 v185, 0, v185, s[78:79]
	v_cndmask_b32_e64 v184, 0, v184, s[78:79]
	v_cndmask_b32_e64 v187, 0, v187, s[76:77]
	v_cndmask_b32_e64 v186, 0, v186, s[76:77]
	v_pk_add_f32 v[184:185], v[184:185], v[186:187]
	v_cndmask_b32_e64 v142, v158, v224, s[42:43]
	v_pk_add_f32 v[216:217], v[216:217], v[184:185] neg_lo:[0,1] neg_hi:[0,1]
	v_mov_b32_e32 v184, v1
	v_mov_b32_e32 v186, v1
	v_mov_b32_e32 v185, v1
	v_mov_b32_dpp v184, v142 row_ror:1 row_mask:0xf bank_mask:0xf
	v_cndmask_b32_e64 v142, v158, v146, s[44:45]
	v_mov_b32_e32 v187, v1
	s_nop 0
	v_mov_b32_dpp v186, v142 row_ror:15 row_mask:0xf bank_mask:0xf
	v_cndmask_b32_e64 v142, v159, v225, s[42:43]
	s_nop 1
	v_mov_b32_dpp v185, v142 row_ror:1 row_mask:0xf bank_mask:0xf
	v_cndmask_b32_e64 v142, v159, v147, s[44:45]
	v_pk_mul_f32 v[184:185], v[118:119], v[184:185]
	s_nop 0
	v_mov_b32_dpp v187, v142 row_ror:15 row_mask:0xf bank_mask:0xf
	v_pk_mul_f32 v[186:187], v[110:111], v[186:187]
	v_cndmask_b32_e64 v185, 0, v185, s[78:79]
	v_cndmask_b32_e64 v184, 0, v184, s[78:79]
	v_cndmask_b32_e64 v187, 0, v187, s[76:77]
	v_cndmask_b32_e64 v186, 0, v186, s[76:77]
	v_pk_add_f32 v[184:185], v[184:185], v[186:187]
	s_nop 0
	v_pk_add_f32 v[218:219], v[218:219], v[184:185] neg_lo:[0,1] neg_hi:[0,1]
	s_branch .LBB0_793
.Lconvgate_fix_3:
	v_cndmask_b32_e64 v182, v226, v162, s[42:43]
	v_mov_b32_e32 v162, v1
	v_cndmask_b32_e64 v183, v226, v138, s[44:45]
	v_cndmask_b32_e64 v184, v227, v139, s[44:45]
	v_mov_b32_dpp v162, v182 row_ror:1 row_mask:0xf bank_mask:0xf
	v_mov_b32_e32 v182, v1
	s_nop 1
	v_mov_b32_dpp v182, v183 row_ror:15 row_mask:0xf bank_mask:0xf
	v_cndmask_b32_e64 v183, v227, v163, s[42:43]
	v_mov_b32_e32 v163, v1
	s_nop 1
	v_mov_b32_dpp v163, v183 row_ror:1 row_mask:0xf bank_mask:0xf
	v_mov_b32_e32 v183, v1
	v_pk_mul_f32 v[162:163], v[122:123], v[162:163]
	s_nop 0
	v_mov_b32_dpp v183, v184 row_ror:15 row_mask:0xf bank_mask:0xf
	v_pk_mul_f32 v[182:183], v[114:115], v[182:183]
	v_cndmask_b32_e64 v163, 0, v163, s[74:75]
	v_cndmask_b32_e64 v162, 0, v162, s[74:75]
	v_cndmask_b32_e64 v183, 0, v183, s[72:73]
	v_cndmask_b32_e64 v182, 0, v182, s[72:73]
	v_pk_add_f32 v[162:163], v[162:163], v[182:183]
	v_cndmask_b32_e64 v182, v147, v135, s[44:45]
	v_pk_add_f32 v[186:187], v[186:187], v[162:163] neg_lo:[0,1] neg_hi:[0,1]
	v_cndmask_b32_e64 v162, v146, v158, s[42:43]
	v_mov_b32_e32 v158, v1
	v_cndmask_b32_e64 v163, v146, v134, s[44:45]
	s_nop 0
	v_mov_b32_dpp v158, v162 row_ror:1 row_mask:0xf bank_mask:0xf
	v_mov_b32_e32 v162, v1
	s_nop 1
	v_mov_b32_dpp v162, v163 row_ror:15 row_mask:0xf bank_mask:0xf
	v_cndmask_b32_e64 v163, v147, v159, s[42:43]
	v_mov_b32_e32 v159, v1
	s_nop 1
	v_mov_b32_dpp v159, v163 row_ror:1 row_mask:0xf bank_mask:0xf
	v_mov_b32_e32 v163, v1
	v_pk_mul_f32 v[158:159], v[118:119], v[158:159]
	s_nop 0
	v_mov_b32_dpp v163, v182 row_ror:15 row_mask:0xf bank_mask:0xf
	v_pk_mul_f32 v[162:163], v[110:111], v[162:163]
	v_cndmask_b32_e64 v159, 0, v159, s[74:75]
	v_cndmask_b32_e64 v158, 0, v158, s[74:75]
	v_cndmask_b32_e64 v163, 0, v163, s[72:73]
	v_cndmask_b32_e64 v162, 0, v162, s[72:73]
	v_pk_add_f32 v[158:159], v[158:159], v[162:163]
	s_nop 0
	v_pk_add_f32 v[188:189], v[188:189], v[158:159] neg_lo:[0,1] neg_hi:[0,1]
	s_branch .LBB0_795
; __device__ __forceinline__ float dpp_ror1(float v) { return __int_as_float(__builtin_amdgcn_update_dpp(0, __float_as_int(v), 0x121, 0xF, 0xF, false)); }
; __device__ __forceinline__ float dpp_ror15(float v) { return __int_as_float(__builtin_amdgcn_update_dpp(0, __float_as_int(v), 0x12F, 0xF, 0xF, false)); }
;     __device__ __forceinline__ void operator()(f32x4 (&acc)[2][2][4][2], const Unit& u, int wr, int wc, int fr, int fq) const {
;     ...
;                         if (__any(lbad | rbad)) {
; #pragma unroll
;                             for (int bj = 0; bj < 2; ++bj) {
;                                 const f32x4 c = acc[ai][bj][m][n], cm = acc[ai][bj][m > 0 ? m - 1 : m][n], cp = acc[ai][bj][m < 3 ? m + 1 : m][n];
; #pragma unroll
;                                 for (int jj = 0; jj < 2; ++jj) {
;                                     const int j = 2 * jh + jj;
;                                     const float up = dpp_ror1(f15 ? cm[j] : c[j]), dn = dpp_ror15(f0 ? cp[j] : c[j]);
;                                     uu[bj][jj] -= (lbad ? w0[bj][jj] * up : 0.f) + (rbad ? w2[bj][jj] * dn : 0.f);
;                                 }
;                             }
;                         }
.Lconvgate_fix_4:
	v_cndmask_b32_e64 v159, v138, v226, s[42:43]
	v_mov_b32_e32 v158, v1
	v_mov_b32_e32 v162, v1
	v_mov_b32_e32 v163, v1
	v_mov_b32_dpp v158, v159 row_ror:1 row_mask:0xf bank_mask:0xf
	v_mov_b32_dpp v162, v138 row_ror:15 row_mask:0xf bank_mask:0xf
	v_cndmask_b32_e64 v138, v139, v227, s[42:43]
	v_mov_b32_e32 v159, v1
	v_mov_b32_dpp v163, v139 row_ror:15 row_mask:0xf bank_mask:0xf
	s_nop 0
	v_mov_b32_dpp v159, v138 row_ror:1 row_mask:0xf bank_mask:0xf
	v_pk_mul_f32 v[138:139], v[122:123], v[158:159]
	v_pk_mul_f32 v[158:159], v[114:115], v[162:163]
	v_cndmask_b32_e64 v139, 0, v139, s[70:71]
	v_cndmask_b32_e64 v138, 0, v138, s[70:71]
	v_cndmask_b32_e64 v159, 0, v159, s[68:69]
	v_cndmask_b32_e64 v158, 0, v158, s[68:69]
	v_pk_add_f32 v[138:139], v[138:139], v[158:159]
	s_nop 0
	v_pk_add_f32 v[182:183], v[182:183], v[138:139] neg_lo:[0,1] neg_hi:[0,1]
	v_cndmask_b32_e64 v139, v134, v146, s[42:43]
	v_mov_b32_e32 v138, v1
	v_mov_b32_e32 v146, v1
	s_nop 0
	v_mov_b32_dpp v138, v139 row_ror:1 row_mask:0xf bank_mask:0xf
	v_mov_b32_dpp v146, v134 row_ror:15 row_mask:0xf bank_mask:0xf
	v_cndmask_b32_e64 v134, v135, v147, s[42:43]
	v_mov_b32_e32 v139, v1
	v_mov_b32_e32 v147, v1
	s_nop 0
	v_mov_b32_dpp v139, v134 row_ror:1 row_mask:0xf bank_mask:0xf
	v_mov_b32_dpp v147, v135 row_ror:15 row_mask:0xf bank_mask:0xf
	v_pk_mul_f32 v[134:135], v[118:119], v[138:139]
	v_pk_mul_f32 v[138:139], v[110:111], v[146:147]
	v_cndmask_b32_e64 v135, 0, v135, s[70:71]
	v_cndmask_b32_e64 v134, 0, v134, s[70:71]
	v_cndmask_b32_e64 v139, 0, v139, s[68:69]
	v_cndmask_b32_e64 v138, 0, v138, s[68:69]
	v_pk_add_f32 v[134:135], v[134:135], v[138:139]
	s_nop 0
	v_pk_add_f32 v[184:185], v[184:185], v[134:135] neg_lo:[0,1] neg_hi:[0,1]
	s_branch .LBB0_797
.Lconvgate_fix_5:
	v_cndmask_b32_e64 v87, v146, v98, s[44:45]
	v_mov_b32_e32 v158, v1
	v_mov_b32_e32 v86, v1
	v_cndmask_b32_e64 v91, v147, v99, s[44:45]
	v_mov_b32_dpp v158, v87 row_ror:15 row_mask:0xf bank_mask:0xf
	v_mov_b32_e32 v87, v1
	v_mov_b32_e32 v159, v1
	v_mov_b32_dpp v86, v146 row_ror:1 row_mask:0xf bank_mask:0xf
	v_mov_b32_dpp v87, v147 row_ror:1 row_mask:0xf bank_mask:0xf
	v_mov_b32_dpp v159, v91 row_ror:15 row_mask:0xf bank_mask:0xf
	v_pk_mul_f32 v[86:87], v[122:123], v[86:87]
	v_pk_mul_f32 v[158:159], v[114:115], v[158:159]
	v_cndmask_b32_e64 v87, 0, v87, s[66:67]
	v_cndmask_b32_e64 v86, 0, v86, s[66:67]
	v_cndmask_b32_e64 v159, 0, v159, s[64:65]
	v_cndmask_b32_e64 v158, 0, v158, s[64:65]
	v_pk_add_f32 v[86:87], v[86:87], v[158:159]
	v_mov_b32_e32 v158, v1
	v_pk_add_f32 v[174:175], v[174:175], v[86:87] neg_lo:[0,1] neg_hi:[0,1]
	v_cndmask_b32_e64 v87, v138, v94, s[44:45]
	v_mov_b32_e32 v86, v1
	v_cndmask_b32_e64 v91, v139, v95, s[44:45]
	v_mov_b32_dpp v158, v87 row_ror:15 row_mask:0xf bank_mask:0xf
	v_mov_b32_e32 v87, v1
	v_mov_b32_e32 v159, v1
	v_mov_b32_dpp v86, v138 row_ror:1 row_mask:0xf bank_mask:0xf
	v_mov_b32_dpp v87, v139 row_ror:1 row_mask:0xf bank_mask:0xf
	v_mov_b32_dpp v159, v91 row_ror:15 row_mask:0xf bank_mask:0xf
	v_pk_mul_f32 v[86:87], v[118:119], v[86:87]
	v_pk_mul_f32 v[158:159], v[110:111], v[158:159]
	v_cndmask_b32_e64 v87, 0, v87, s[66:67]
	v_cndmask_b32_e64 v86, 0, v86, s[66:67]
	v_cndmask_b32_e64 v159, 0, v159, s[64:65]
	v_cndmask_b32_e64 v158, 0, v158, s[64:65]
	v_pk_add_f32 v[86:87], v[86:87], v[158:159]
	s_nop 0
	v_pk_add_f32 v[176:177], v[176:177], v[86:87] neg_lo:[0,1] neg_hi:[0,1]
	s_branch .LBB0_799
.Lconvgate_fix_6:
	v_cndmask_b32_e64 v83, v98, v146, s[42:43]
	v_mov_b32_e32 v82, v1
	v_mov_b32_e32 v146, v1
	v_cndmask_b32_e64 v87, v99, v147, s[42:43]
	v_mov_b32_dpp v82, v83 row_ror:1 row_mask:0xf bank_mask:0xf
	v_cndmask_b32_e64 v83, v98, v166, s[44:45]
	v_mov_b32_e32 v147, v1
	s_nop 0
	v_mov_b32_dpp v146, v83 row_ror:15 row_mask:0xf bank_mask:0xf
	v_mov_b32_e32 v83, v1
	s_nop 1
	v_mov_b32_dpp v83, v87 row_ror:1 row_mask:0xf bank_mask:0xf
	v_cndmask_b32_e64 v87, v99, v167, s[44:45]
	v_pk_mul_f32 v[82:83], v[122:123], v[82:83]
	s_nop 0
	v_mov_b32_dpp v147, v87 row_ror:15 row_mask:0xf bank_mask:0xf
	v_pk_mul_f32 v[146:147], v[114:115], v[146:147]
	v_cndmask_b32_e64 v83, 0, v83, s[62:63]
	v_cndmask_b32_e64 v82, 0, v82, s[62:63]
	v_cndmask_b32_e64 v147, 0, v147, s[60:61]
	v_cndmask_b32_e64 v146, 0, v146, s[60:61]
	v_pk_add_f32 v[82:83], v[82:83], v[146:147]
	v_cndmask_b32_e64 v87, v95, v139, s[42:43]
	v_pk_add_f32 v[158:159], v[158:159], v[82:83] neg_lo:[0,1] neg_hi:[0,1]
	v_cndmask_b32_e64 v83, v94, v138, s[42:43]
	v_mov_b32_e32 v82, v1
	v_mov_b32_e32 v138, v1
	v_mov_b32_e32 v139, v1
	v_mov_b32_dpp v82, v83 row_ror:1 row_mask:0xf bank_mask:0xf
	v_cndmask_b32_e64 v83, v94, v78, s[44:45]
	s_nop 1
	v_mov_b32_dpp v138, v83 row_ror:15 row_mask:0xf bank_mask:0xf
	v_mov_b32_e32 v83, v1
	s_nop 1
	v_mov_b32_dpp v83, v87 row_ror:1 row_mask:0xf bank_mask:0xf
	v_cndmask_b32_e64 v87, v95, v79, s[44:45]
	v_pk_mul_f32 v[82:83], v[118:119], v[82:83]
	s_nop 0
	v_mov_b32_dpp v139, v87 row_ror:15 row_mask:0xf bank_mask:0xf
	v_pk_mul_f32 v[138:139], v[110:111], v[138:139]
	v_cndmask_b32_e64 v83, 0, v83, s[62:63]
	v_cndmask_b32_e64 v82, 0, v82, s[62:63]
	v_cndmask_b32_e64 v139, 0, v139, s[60:61]
	v_cndmask_b32_e64 v138, 0, v138, s[60:61]
	v_pk_add_f32 v[82:83], v[82:83], v[138:139]
	s_nop 0
	v_pk_add_f32 v[162:163], v[162:163], v[82:83] neg_lo:[0,1] neg_hi:[0,1]
	s_branch .LBB0_801
; __device__ __forceinline__ float dpp_ror1(float v) { return __int_as_float(__builtin_amdgcn_update_dpp(0, __float_as_int(v), 0x121, 0xF, 0xF, false)); }
; __device__ __forceinline__ float dpp_ror15(float v) { return __int_as_float(__builtin_amdgcn_update_dpp(0, __float_as_int(v), 0x12F, 0xF, 0xF, false)); }
;     __device__ __forceinline__ void operator()(f32x4 (&acc)[2][2][4][2], const Unit& u, int wr, int wc, int fr, int fq) const {
;     ...
;                         if (__any(lbad | rbad)) {
; #pragma unroll
;                             for (int bj = 0; bj < 2; ++bj) {
;                                 const f32x4 c = acc[ai][bj][m][n], cm = acc[ai][bj][m > 0 ? m - 1 : m][n], cp = acc[ai][bj][m < 3 ? m + 1 : m][n];
; #pragma unroll
;                                 for (int jj = 0; jj < 2; ++jj) {
;                                     const int j = 2 * jh + jj;
;                                     const float up = dpp_ror1(f15 ? cm[j] : c[j]), dn = dpp_ror15(f0 ? cp[j] : c[j]);
;                                     uu[bj][jj] -= (lbad ? w0[bj][jj] * up : 0.f) + (rbad ? w2[bj][jj] * dn : 0.f);
;                                 }
;                             }
.Lconvgate_fix_7:
	v_cndmask_b32_e64 v83, v166, v98, s[42:43]
	v_mov_b32_e32 v98, v1
	v_mov_b32_e32 v172, v1
	v_mov_b32_e32 v173, v1
	v_mov_b32_dpp v98, v83 row_ror:1 row_mask:0xf bank_mask:0xf
	v_cndmask_b32_e64 v83, v166, v74, s[44:45]
	s_nop 1
	v_mov_b32_dpp v172, v83 row_ror:15 row_mask:0xf bank_mask:0xf
	v_cndmask_b32_e64 v83, v167, v99, s[42:43]
	v_mov_b32_e32 v99, v1
	s_nop 1
	v_mov_b32_dpp v99, v83 row_ror:1 row_mask:0xf bank_mask:0xf
	v_cndmask_b32_e64 v83, v167, v75, s[44:45]
	v_pk_mul_f32 v[98:99], v[122:123], v[98:99]
	s_nop 0
	v_mov_b32_dpp v173, v83 row_ror:15 row_mask:0xf bank_mask:0xf
	v_pk_mul_f32 v[172:173], v[114:115], v[172:173]
	v_cndmask_b32_e64 v99, 0, v99, s[58:59]
	v_cndmask_b32_e64 v98, 0, v98, s[58:59]
	v_cndmask_b32_e64 v173, 0, v173, s[56:57]
	v_cndmask_b32_e64 v172, 0, v172, s[56:57]
	v_pk_add_f32 v[98:99], v[98:99], v[172:173]
	v_cndmask_b32_e64 v83, v78, v94, s[42:43]
	v_mov_b32_e32 v94, v1
	v_pk_add_f32 v[138:139], v[138:139], v[98:99] neg_lo:[0,1] neg_hi:[0,1]
	v_mov_b32_e32 v98, v1
	v_mov_b32_dpp v94, v83 row_ror:1 row_mask:0xf bank_mask:0xf
	v_cndmask_b32_e64 v83, v78, v70, s[44:45]
	v_mov_b32_e32 v99, v1
	s_nop 0
	v_mov_b32_dpp v98, v83 row_ror:15 row_mask:0xf bank_mask:0xf
	v_cndmask_b32_e64 v83, v79, v95, s[42:43]
	v_mov_b32_e32 v95, v1
	s_nop 1
	v_mov_b32_dpp v95, v83 row_ror:1 row_mask:0xf bank_mask:0xf
	v_cndmask_b32_e64 v83, v79, v71, s[44:45]
	v_pk_mul_f32 v[94:95], v[118:119], v[94:95]
	s_nop 0
	v_mov_b32_dpp v99, v83 row_ror:15 row_mask:0xf bank_mask:0xf
	v_pk_mul_f32 v[98:99], v[110:111], v[98:99]
	v_cndmask_b32_e64 v95, 0, v95, s[58:59]
	v_cndmask_b32_e64 v94, 0, v94, s[58:59]
	v_cndmask_b32_e64 v99, 0, v99, s[56:57]
	v_cndmask_b32_e64 v98, 0, v98, s[56:57]
	v_pk_add_f32 v[94:95], v[94:95], v[98:99]
	s_nop 0
	v_pk_add_f32 v[146:147], v[146:147], v[94:95] neg_lo:[0,1] neg_hi:[0,1]
	s_branch .LBB0_803
.Lconvgate_fix_8:
	v_mov_b32_e32 v98, v1
	v_cndmask_b32_e64 v83, v74, v166, s[42:43]
	v_mov_b32_e32 v94, v1
	v_mov_b32_dpp v98, v74 row_ror:15 row_mask:0xf bank_mask:0xf
	v_cndmask_b32_e64 v74, v75, v167, s[42:43]
	v_mov_b32_e32 v95, v1
	v_mov_b32_e32 v99, v1
	v_mov_b32_dpp v94, v83 row_ror:1 row_mask:0xf bank_mask:0xf
	v_mov_b32_dpp v95, v74 row_ror:1 row_mask:0xf bank_mask:0xf
	v_mov_b32_dpp v99, v75 row_ror:15 row_mask:0xf bank_mask:0xf
	v_pk_mul_f32 v[74:75], v[122:123], v[94:95]
	v_pk_mul_f32 v[94:95], v[114:115], v[98:99]
	v_cndmask_b32_e64 v75, 0, v75, s[54:55]
	v_cndmask_b32_e64 v74, 0, v74, s[54:55]
	v_cndmask_b32_e64 v95, 0, v95, s[52:53]
	v_cndmask_b32_e64 v94, 0, v94, s[52:53]
	v_pk_add_f32 v[74:75], v[74:75], v[94:95]
	s_nop 0
	v_pk_add_f32 v[130:131], v[130:131], v[74:75] neg_lo:[0,1] neg_hi:[0,1]
	v_cndmask_b32_e64 v75, v70, v78, s[42:43]
	v_mov_b32_e32 v74, v1
	v_mov_b32_e32 v78, v1
	s_nop 0
	v_mov_b32_dpp v74, v75 row_ror:1 row_mask:0xf bank_mask:0xf
	v_mov_b32_dpp v78, v70 row_ror:15 row_mask:0xf bank_mask:0xf
	v_cndmask_b32_e64 v70, v71, v79, s[42:43]
	v_mov_b32_e32 v75, v1
	v_mov_b32_e32 v79, v1
	s_nop 0
	v_mov_b32_dpp v75, v70 row_ror:1 row_mask:0xf bank_mask:0xf
	v_mov_b32_dpp v79, v71 row_ror:15 row_mask:0xf bank_mask:0xf
	v_pk_mul_f32 v[70:71], v[118:119], v[74:75]
	v_pk_mul_f32 v[74:75], v[110:111], v[78:79]
	v_cndmask_b32_e64 v71, 0, v71, s[54:55]
	v_cndmask_b32_e64 v70, 0, v70, s[54:55]
	v_cndmask_b32_e64 v75, 0, v75, s[52:53]
	v_cndmask_b32_e64 v74, 0, v74, s[52:53]
	v_pk_add_f32 v[70:71], v[70:71], v[74:75]
	s_nop 0
	v_pk_add_f32 v[126:127], v[126:127], v[70:71] neg_lo:[0,1] neg_hi:[0,1]
	s_branch .LBB0_805
.Lconvgate_fix_9:
	v_cndmask_b32_e64 v79, v164, v122, s[44:45]
	v_mov_b32_e32 v172, v1
	v_mov_b32_e32 v78, v1
	v_cndmask_b32_e64 v87, v165, v123, s[44:45]
	v_mov_b32_dpp v172, v79 row_ror:15 row_mask:0xf bank_mask:0xf
	v_mov_b32_e32 v79, v1
	v_mov_b32_e32 v173, v1
	v_mov_b32_dpp v78, v164 row_ror:1 row_mask:0xf bank_mask:0xf
	v_mov_b32_dpp v79, v165 row_ror:1 row_mask:0xf bank_mask:0xf
	v_mov_b32_dpp v173, v87 row_ror:15 row_mask:0xf bank_mask:0xf
	v_cndmask_b32_e64 v87, v156, v118, s[44:45]
	v_mov_b32_e32 v208, v1
	v_pk_mul_f32 v[78:79], v[124:125], v[78:79]
	v_pk_mul_f32 v[172:173], v[116:117], v[172:173]
	v_mov_b32_e32 v180, v1
	v_mov_b32_dpp v208, v87 row_ror:15 row_mask:0xf bank_mask:0xf
	v_mov_b32_e32 v181, v1
	v_cndmask_b32_e64 v87, v157, v119, s[44:45]
	v_mov_b32_e32 v209, v1
	v_cndmask_b32_e64 v79, 0, v79, s[82:83]
	v_cndmask_b32_e64 v78, 0, v78, s[82:83]
	v_cndmask_b32_e64 v173, 0, v173, s[80:81]
	v_cndmask_b32_e64 v172, 0, v172, s[80:81]
	v_mov_b32_dpp v180, v156 row_ror:1 row_mask:0xf bank_mask:0xf
	v_mov_b32_dpp v181, v157 row_ror:1 row_mask:0xf bank_mask:0xf
	v_mov_b32_dpp v209, v87 row_ror:15 row_mask:0xf bank_mask:0xf
	v_pk_add_f32 v[78:79], v[78:79], v[172:173]
	v_pk_mul_f32 v[172:173], v[112:113], v[208:209]
	v_pk_add_f32 v[152:153], v[152:153], v[78:79] neg_lo:[0,1] neg_hi:[0,1]
	v_pk_mul_f32 v[78:79], v[120:121], v[180:181]
	v_cndmask_b32_e64 v173, 0, v173, s[80:81]
	v_cndmask_b32_e64 v79, 0, v79, s[82:83]
	v_cndmask_b32_e64 v78, 0, v78, s[82:83]
	v_cndmask_b32_e64 v172, 0, v172, s[80:81]
	v_pk_add_f32 v[78:79], v[78:79], v[172:173]
	s_nop 0
	v_pk_add_f32 v[160:161], v[160:161], v[78:79] neg_lo:[0,1] neg_hi:[0,1]
	s_branch .LBB0_807
; __device__ __forceinline__ float dpp_ror1(float v) { return __int_as_float(__builtin_amdgcn_update_dpp(0, __float_as_int(v), 0x121, 0xF, 0xF, false)); }
; __device__ __forceinline__ float dpp_ror15(float v) { return __int_as_float(__builtin_amdgcn_update_dpp(0, __float_as_int(v), 0x12F, 0xF, 0xF, false)); }
;     __device__ __forceinline__ void operator()(f32x4 (&acc)[2][2][4][2], const Unit& u, int wr, int wc, int fr, int fq) const {
;     ...
;                         if (__any(lbad | rbad)) {
; #pragma unroll
;                             for (int bj = 0; bj < 2; ++bj) {
;                                 const f32x4 c = acc[ai][bj][m][n], cm = acc[ai][bj][m > 0 ? m - 1 : m][n], cp = acc[ai][bj][m < 3 ? m + 1 : m][n];
; #pragma unroll
;                                 for (int jj = 0; jj < 2; ++jj) {
;                                     const int j = 2 * jh + jj;
;                                     const float up = dpp_ror1(f15 ? cm[j] : c[j]), dn = dpp_ror15(f0 ? cp[j] : c[j]);
;                                     uu[bj][jj] -= (lbad ? w0[bj][jj] * up : 0.f) + (rbad ? w2[bj][jj] * dn : 0.f);
;                                 }
;                             }
.Lconvgate_fix_10:
	v_cndmask_b32_e64 v172, v122, v164, s[42:43]
	v_mov_b32_e32 v164, v1
	v_cndmask_b32_e64 v173, v122, v148, s[44:45]
	v_cndmask_b32_e64 v179, v123, v149, s[44:45]
	v_mov_b32_dpp v164, v172 row_ror:1 row_mask:0xf bank_mask:0xf
	v_mov_b32_e32 v172, v1
	v_mov_b32_e32 v180, v1
	v_mov_b32_e32 v181, v1
	v_mov_b32_dpp v172, v173 row_ror:15 row_mask:0xf bank_mask:0xf
	v_cndmask_b32_e64 v173, v123, v165, s[42:43]
	v_mov_b32_e32 v165, v1
	s_nop 1
	v_mov_b32_dpp v165, v173 row_ror:1 row_mask:0xf bank_mask:0xf
	v_mov_b32_e32 v173, v1
	v_pk_mul_f32 v[164:165], v[124:125], v[164:165]
	s_nop 0
	v_mov_b32_dpp v173, v179 row_ror:15 row_mask:0xf bank_mask:0xf
	v_cndmask_b32_e64 v179, v118, v156, s[42:43]
	v_mov_b32_e32 v156, v1
	v_pk_mul_f32 v[172:173], v[116:117], v[172:173]
	v_cndmask_b32_e64 v165, 0, v165, s[78:79]
	v_mov_b32_dpp v156, v179 row_ror:1 row_mask:0xf bank_mask:0xf
	v_cndmask_b32_e64 v179, v118, v144, s[44:45]
	v_cndmask_b32_e64 v164, 0, v164, s[78:79]
	v_cndmask_b32_e64 v173, 0, v173, s[76:77]
	v_mov_b32_dpp v180, v179 row_ror:15 row_mask:0xf bank_mask:0xf
	v_cndmask_b32_e64 v179, v119, v157, s[42:43]
	v_mov_b32_e32 v157, v1
	v_cndmask_b32_e64 v172, 0, v172, s[76:77]
	v_pk_add_f32 v[164:165], v[164:165], v[172:173]
	v_mov_b32_dpp v157, v179 row_ror:1 row_mask:0xf bank_mask:0xf
	v_cndmask_b32_e64 v179, v119, v145, s[44:45]
	v_pk_add_f32 v[152:153], v[152:153], v[164:165] neg_lo:[0,1] neg_hi:[0,1]
	v_pk_mul_f32 v[156:157], v[120:121], v[156:157]
	v_mov_b32_dpp v181, v179 row_ror:15 row_mask:0xf bank_mask:0xf
	v_pk_mul_f32 v[164:165], v[112:113], v[180:181]
	v_cndmask_b32_e64 v157, 0, v157, s[78:79]
	v_cndmask_b32_e64 v156, 0, v156, s[78:79]
	v_cndmask_b32_e64 v165, 0, v165, s[76:77]
	v_cndmask_b32_e64 v164, 0, v164, s[76:77]
	v_pk_add_f32 v[156:157], v[156:157], v[164:165]
	s_nop 0
	v_pk_add_f32 v[160:161], v[160:161], v[156:157] neg_lo:[0,1] neg_hi:[0,1]
	s_branch .LBB0_811
.Lconvgate_fix_11:
	v_cndmask_b32_e64 v161, v148, v122, s[42:43]
	v_mov_b32_e32 v122, v1
	v_mov_b32_e32 v164, v1
	v_mov_b32_e32 v165, v1
	v_mov_b32_dpp v122, v161 row_ror:1 row_mask:0xf bank_mask:0xf
	v_cndmask_b32_e64 v161, v148, v140, s[44:45]
	v_mov_b32_e32 v172, v1
	v_mov_b32_e32 v173, v1
	v_mov_b32_dpp v164, v161 row_ror:15 row_mask:0xf bank_mask:0xf
	v_cndmask_b32_e64 v161, v149, v123, s[42:43]
	v_mov_b32_e32 v123, v1
	s_nop 1
	v_mov_b32_dpp v123, v161 row_ror:1 row_mask:0xf bank_mask:0xf
	v_cndmask_b32_e64 v161, v149, v141, s[44:45]
	v_pk_mul_f32 v[122:123], v[124:125], v[122:123]
	s_nop 0
	v_mov_b32_dpp v165, v161 row_ror:15 row_mask:0xf bank_mask:0xf
	v_cndmask_b32_e64 v161, v144, v118, s[42:43]
	v_mov_b32_e32 v118, v1
	v_pk_mul_f32 v[164:165], v[116:117], v[164:165]
	v_cndmask_b32_e64 v123, 0, v123, s[74:75]
	v_mov_b32_dpp v118, v161 row_ror:1 row_mask:0xf bank_mask:0xf
	v_cndmask_b32_e64 v161, v144, v136, s[44:45]
	v_cndmask_b32_e64 v122, 0, v122, s[74:75]
	v_cndmask_b32_e64 v165, 0, v165, s[72:73]
	v_mov_b32_dpp v172, v161 row_ror:15 row_mask:0xf bank_mask:0xf
	v_cndmask_b32_e64 v161, v145, v119, s[42:43]
	v_mov_b32_e32 v119, v1
	v_cndmask_b32_e64 v164, 0, v164, s[72:73]
	v_pk_add_f32 v[122:123], v[122:123], v[164:165]
	v_mov_b32_dpp v119, v161 row_ror:1 row_mask:0xf bank_mask:0xf
	v_cndmask_b32_e64 v161, v145, v137, s[44:45]
	v_pk_add_f32 v[152:153], v[152:153], v[122:123] neg_lo:[0,1] neg_hi:[0,1]
	v_pk_mul_f32 v[118:119], v[120:121], v[118:119]
	v_mov_b32_dpp v173, v161 row_ror:15 row_mask:0xf bank_mask:0xf
	v_pk_mul_f32 v[122:123], v[112:113], v[172:173]
	v_cndmask_b32_e64 v119, 0, v119, s[74:75]
	v_cndmask_b32_e64 v118, 0, v118, s[74:75]
	v_cndmask_b32_e64 v123, 0, v123, s[72:73]
	v_cndmask_b32_e64 v122, 0, v122, s[72:73]
	v_pk_add_f32 v[118:119], v[118:119], v[122:123]
	s_nop 0
	v_pk_add_f32 v[156:157], v[156:157], v[118:119] neg_lo:[0,1] neg_hi:[0,1]
	s_branch .LBB0_815
.Lconvgate_fix_12:
	v_mov_b32_e32 v156, v1
	v_cndmask_b32_e64 v153, v140, v148, s[42:43]
	v_mov_b32_e32 v157, v1
	v_mov_b32_dpp v156, v140 row_ror:15 row_mask:0xf bank_mask:0xf
	v_cndmask_b32_e64 v140, v141, v149, s[42:43]
	v_mov_b32_e32 v149, v1
	v_mov_b32_e32 v148, v1
	v_mov_b32_dpp v157, v141 row_ror:15 row_mask:0xf bank_mask:0xf
	v_mov_b32_dpp v149, v140 row_ror:1 row_mask:0xf bank_mask:0xf
	v_cndmask_b32_e64 v141, v136, v144, s[42:43]
	v_mov_b32_e32 v140, v1
	v_mov_b32_e32 v144, v1
	v_mov_b32_dpp v148, v153 row_ror:1 row_mask:0xf bank_mask:0xf
	v_mov_b32_dpp v140, v141 row_ror:1 row_mask:0xf bank_mask:0xf
	v_mov_b32_dpp v144, v136 row_ror:15 row_mask:0xf bank_mask:0xf
	v_cndmask_b32_e64 v136, v137, v145, s[42:43]
	v_mov_b32_e32 v141, v1
	v_mov_b32_e32 v145, v1
	s_nop 0
	v_mov_b32_dpp v141, v136 row_ror:1 row_mask:0xf bank_mask:0xf
	v_mov_b32_dpp v145, v137 row_ror:15 row_mask:0xf bank_mask:0xf
	v_pk_mul_f32 v[136:137], v[124:125], v[148:149]
	v_pk_mul_f32 v[148:149], v[116:117], v[156:157]
	v_cndmask_b32_e64 v137, 0, v137, s[70:71]
	v_cndmask_b32_e64 v136, 0, v136, s[70:71]
	v_cndmask_b32_e64 v149, 0, v149, s[68:69]
	v_cndmask_b32_e64 v148, 0, v148, s[68:69]
	v_pk_add_f32 v[136:137], v[136:137], v[148:149]
	s_nop 0
	v_pk_add_f32 v[118:119], v[118:119], v[136:137] neg_lo:[0,1] neg_hi:[0,1]
	v_pk_mul_f32 v[136:137], v[120:121], v[140:141]
	v_pk_mul_f32 v[140:141], v[112:113], v[144:145]
	v_cndmask_b32_e64 v137, 0, v137, s[70:71]
	v_cndmask_b32_e64 v136, 0, v136, s[70:71]
	v_cndmask_b32_e64 v141, 0, v141, s[68:69]
	v_cndmask_b32_e64 v140, 0, v140, s[68:69]
	v_pk_add_f32 v[136:137], v[136:137], v[140:141]
	s_nop 0
	v_pk_add_f32 v[122:123], v[122:123], v[136:137] neg_lo:[0,1] neg_hi:[0,1]
	s_branch .LBB0_819
; __device__ __forceinline__ float dpp_ror1(float v) { return __int_as_float(__builtin_amdgcn_update_dpp(0, __float_as_int(v), 0x121, 0xF, 0xF, false)); }
; __device__ __forceinline__ float dpp_ror15(float v) { return __int_as_float(__builtin_amdgcn_update_dpp(0, __float_as_int(v), 0x12F, 0xF, 0xF, false)); }
;     __device__ __forceinline__ void operator()(f32x4 (&acc)[2][2][4][2], const Unit& u, int wr, int wc, int fr, int fq) const {
;     ...
;                         if (__any(lbad | rbad)) {
; #pragma unroll
;                             for (int bj = 0; bj < 2; ++bj) {
;                                 const f32x4 c = acc[ai][bj][m][n], cm = acc[ai][bj][m > 0 ? m - 1 : m][n], cp = acc[ai][bj][m < 3 ? m + 1 : m][n];
; #pragma unroll
;                                 for (int jj = 0; jj < 2; ++jj) {
;                                     const int j = 2 * jh + jj;
;                                     const float up = dpp_ror1(f15 ? cm[j] : c[j]), dn = dpp_ror15(f0 ? cp[j] : c[j]);
;                                     uu[bj][jj] -= (lbad ? w0[bj][jj] * up : 0.f) + (rbad ? w2[bj][jj] * dn : 0.f);
;                                 }
;                             }
.Lconvgate_fix_13:
	v_cndmask_b32_e64 v136, v118, v92, s[44:45]
	v_mov_b32_e32 v144, v1
	v_mov_b32_e32 v140, v1
	v_mov_b32_e32 v141, v1
	v_mov_b32_dpp v144, v136 row_ror:15 row_mask:0xf bank_mask:0xf
	v_cndmask_b32_e64 v136, v119, v93, s[44:45]
	v_mov_b32_e32 v145, v1
	v_mov_b32_dpp v140, v118 row_ror:1 row_mask:0xf bank_mask:0xf
	v_mov_b32_dpp v141, v119 row_ror:1 row_mask:0xf bank_mask:0xf
	v_mov_b32_dpp v145, v136 row_ror:15 row_mask:0xf bank_mask:0xf
	v_cndmask_b32_e64 v136, v100, v88, s[44:45]
	v_mov_b32_e32 v156, v1
	v_pk_mul_f32 v[140:141], v[124:125], v[140:141]
	v_pk_mul_f32 v[144:145], v[116:117], v[144:145]
	v_mov_b32_e32 v148, v1
	v_mov_b32_dpp v156, v136 row_ror:15 row_mask:0xf bank_mask:0xf
	v_mov_b32_e32 v149, v1
	v_cndmask_b32_e64 v136, v101, v89, s[44:45]
	v_mov_b32_e32 v157, v1
	v_cndmask_b32_e64 v141, 0, v141, s[66:67]
	v_cndmask_b32_e64 v140, 0, v140, s[66:67]
	v_cndmask_b32_e64 v145, 0, v145, s[64:65]
	v_cndmask_b32_e64 v144, 0, v144, s[64:65]
	v_mov_b32_dpp v148, v100 row_ror:1 row_mask:0xf bank_mask:0xf
	v_mov_b32_dpp v149, v101 row_ror:1 row_mask:0xf bank_mask:0xf
	v_mov_b32_dpp v157, v136 row_ror:15 row_mask:0xf bank_mask:0xf
	v_pk_add_f32 v[140:141], v[140:141], v[144:145]
	v_pk_mul_f32 v[144:145], v[112:113], v[156:157]
	v_pk_add_f32 v[96:97], v[96:97], v[140:141] neg_lo:[0,1] neg_hi:[0,1]
	v_pk_mul_f32 v[140:141], v[120:121], v[148:149]
	v_cndmask_b32_e64 v145, 0, v145, s[64:65]
	v_cndmask_b32_e64 v141, 0, v141, s[66:67]
	v_cndmask_b32_e64 v140, 0, v140, s[66:67]
	v_cndmask_b32_e64 v144, 0, v144, s[64:65]
	v_pk_add_f32 v[140:141], v[140:141], v[144:145]
	s_nop 0
	v_pk_add_f32 v[122:123], v[122:123], v[140:141] neg_lo:[0,1] neg_hi:[0,1]
	s_branch .LBB0_823
.Lconvgate_fix_14:
	v_cndmask_b32_e64 v140, v92, v118, s[42:43]
	v_mov_b32_e32 v118, v1
	v_cndmask_b32_e64 v141, v92, v84, s[44:45]
	v_cndmask_b32_e64 v144, v93, v85, s[44:45]
	v_mov_b32_dpp v118, v140 row_ror:1 row_mask:0xf bank_mask:0xf
	v_mov_b32_e32 v140, v1
	v_cndmask_b32_e64 v145, v88, v80, s[44:45]
	v_cndmask_b32_e64 v148, v89, v81, s[44:45]
	v_mov_b32_dpp v140, v141 row_ror:15 row_mask:0xf bank_mask:0xf
	v_cndmask_b32_e64 v141, v93, v119, s[42:43]
	v_mov_b32_e32 v119, v1
	s_nop 1
	v_mov_b32_dpp v119, v141 row_ror:1 row_mask:0xf bank_mask:0xf
	v_mov_b32_e32 v141, v1
	v_pk_mul_f32 v[118:119], v[124:125], v[118:119]
	s_nop 0
	v_mov_b32_dpp v141, v144 row_ror:15 row_mask:0xf bank_mask:0xf
	v_cndmask_b32_e64 v144, v88, v100, s[42:43]
	v_mov_b32_e32 v100, v1
	v_pk_mul_f32 v[140:141], v[116:117], v[140:141]
	v_cndmask_b32_e64 v119, 0, v119, s[62:63]
	v_mov_b32_dpp v100, v144 row_ror:1 row_mask:0xf bank_mask:0xf
	v_mov_b32_e32 v144, v1
	v_cndmask_b32_e64 v118, 0, v118, s[62:63]
	v_cndmask_b32_e64 v141, 0, v141, s[60:61]
	v_mov_b32_dpp v144, v145 row_ror:15 row_mask:0xf bank_mask:0xf
	v_cndmask_b32_e64 v145, v89, v101, s[42:43]
	v_mov_b32_e32 v101, v1
	v_cndmask_b32_e64 v140, 0, v140, s[60:61]
	v_pk_add_f32 v[118:119], v[118:119], v[140:141]
	v_mov_b32_dpp v101, v145 row_ror:1 row_mask:0xf bank_mask:0xf
	v_mov_b32_e32 v145, v1
	v_pk_add_f32 v[96:97], v[96:97], v[118:119] neg_lo:[0,1] neg_hi:[0,1]
	v_pk_mul_f32 v[100:101], v[120:121], v[100:101]
	v_mov_b32_dpp v145, v148 row_ror:15 row_mask:0xf bank_mask:0xf
	v_pk_mul_f32 v[118:119], v[112:113], v[144:145]
	v_cndmask_b32_e64 v101, 0, v101, s[62:63]
	v_cndmask_b32_e64 v100, 0, v100, s[62:63]
	v_cndmask_b32_e64 v119, 0, v119, s[60:61]
	v_cndmask_b32_e64 v118, 0, v118, s[60:61]
	v_pk_add_f32 v[100:101], v[100:101], v[118:119]
	s_nop 0
	v_pk_add_f32 v[122:123], v[122:123], v[100:101] neg_lo:[0,1] neg_hi:[0,1]
	s_branch .LBB0_827
.Lconvgate_fix_15:
	v_cndmask_b32_e64 v83, v84, v92, s[42:43]
	v_mov_b32_e32 v92, v1
	v_mov_b32_e32 v118, v1
	v_mov_b32_e32 v119, v1
	v_mov_b32_dpp v92, v83 row_ror:1 row_mask:0xf bank_mask:0xf
	v_cndmask_b32_e64 v83, v84, v76, s[44:45]
	v_mov_b32_e32 v140, v1
	v_mov_b32_e32 v141, v1
	v_mov_b32_dpp v118, v83 row_ror:15 row_mask:0xf bank_mask:0xf
	v_cndmask_b32_e64 v83, v85, v93, s[42:43]
	v_mov_b32_e32 v93, v1
	s_nop 1
	v_mov_b32_dpp v93, v83 row_ror:1 row_mask:0xf bank_mask:0xf
	v_cndmask_b32_e64 v83, v85, v77, s[44:45]
	v_pk_mul_f32 v[92:93], v[124:125], v[92:93]
	s_nop 0
	v_mov_b32_dpp v119, v83 row_ror:15 row_mask:0xf bank_mask:0xf
	v_cndmask_b32_e64 v83, v80, v88, s[42:43]
	v_mov_b32_e32 v88, v1
	v_pk_mul_f32 v[118:119], v[116:117], v[118:119]
	v_cndmask_b32_e64 v93, 0, v93, s[58:59]
	v_mov_b32_dpp v88, v83 row_ror:1 row_mask:0xf bank_mask:0xf
	v_cndmask_b32_e64 v83, v80, v72, s[44:45]
	v_cndmask_b32_e64 v92, 0, v92, s[58:59]
	v_cndmask_b32_e64 v119, 0, v119, s[56:57]
	v_mov_b32_dpp v140, v83 row_ror:15 row_mask:0xf bank_mask:0xf
	v_cndmask_b32_e64 v83, v81, v89, s[42:43]
	v_mov_b32_e32 v89, v1
	v_cndmask_b32_e64 v118, 0, v118, s[56:57]
	v_pk_add_f32 v[92:93], v[92:93], v[118:119]
	v_mov_b32_dpp v89, v83 row_ror:1 row_mask:0xf bank_mask:0xf
	v_cndmask_b32_e64 v83, v81, v73, s[44:45]
	v_pk_add_f32 v[96:97], v[96:97], v[92:93] neg_lo:[0,1] neg_hi:[0,1]
	v_pk_mul_f32 v[88:89], v[120:121], v[88:89]
	v_mov_b32_dpp v141, v83 row_ror:15 row_mask:0xf bank_mask:0xf
	v_pk_mul_f32 v[92:93], v[112:113], v[140:141]
	v_cndmask_b32_e64 v89, 0, v89, s[58:59]
	v_cndmask_b32_e64 v88, 0, v88, s[58:59]
	v_cndmask_b32_e64 v93, 0, v93, s[56:57]
	v_cndmask_b32_e64 v92, 0, v92, s[56:57]
	v_pk_add_f32 v[88:89], v[88:89], v[92:93]
	s_nop 0
	v_pk_add_f32 v[100:101], v[100:101], v[88:89] neg_lo:[0,1] neg_hi:[0,1]
	s_branch .LBB0_831
; __device__ __forceinline__ float dpp_ror1(float v) { return __int_as_float(__builtin_amdgcn_update_dpp(0, __float_as_int(v), 0x121, 0xF, 0xF, false)); }
; __device__ __forceinline__ float dpp_ror15(float v) { return __int_as_float(__builtin_amdgcn_update_dpp(0, __float_as_int(v), 0x12F, 0xF, 0xF, false)); }
;     __device__ __forceinline__ void operator()(f32x4 (&acc)[2][2][4][2], const Unit& u, int wr, int wc, int fr, int fq) const {
;     ...
;                         if (__any(lbad | rbad)) {
; #pragma unroll
;                             for (int bj = 0; bj < 2; ++bj) {
;                                 const f32x4 c = acc[ai][bj][m][n], cm = acc[ai][bj][m > 0 ? m - 1 : m][n], cp = acc[ai][bj][m < 3 ? m + 1 : m][n];
; #pragma unroll
;                                 for (int jj = 0; jj < 2; ++jj) {
;                                     const int j = 2 * jh + jj;
;                                     const float up = dpp_ror1(f15 ? cm[j] : c[j]), dn = dpp_ror15(f0 ? cp[j] : c[j]);
;                                     uu[bj][jj] -= (lbad ? w0[bj][jj] * up : 0.f) + (rbad ? w2[bj][jj] * dn : 0.f);
;                                 }
;                             }
.Lconvgate_fix_16:
	v_mov_b32_e32 v88, v1
	v_cndmask_b32_e64 v83, v76, v84, s[42:43]
	v_mov_b32_e32 v89, v1
	v_mov_b32_dpp v88, v76 row_ror:15 row_mask:0xf bank_mask:0xf
	v_cndmask_b32_e64 v76, v77, v85, s[42:43]
	v_mov_b32_e32 v85, v1
	v_mov_b32_e32 v84, v1
	v_mov_b32_dpp v89, v77 row_ror:15 row_mask:0xf bank_mask:0xf
	v_mov_b32_dpp v85, v76 row_ror:1 row_mask:0xf bank_mask:0xf
	v_cndmask_b32_e64 v77, v72, v80, s[42:43]
	v_mov_b32_e32 v76, v1
	v_mov_b32_e32 v80, v1
	v_mov_b32_dpp v84, v83 row_ror:1 row_mask:0xf bank_mask:0xf
	v_mov_b32_dpp v76, v77 row_ror:1 row_mask:0xf bank_mask:0xf
	v_mov_b32_dpp v80, v72 row_ror:15 row_mask:0xf bank_mask:0xf
	v_cndmask_b32_e64 v72, v73, v81, s[42:43]
	v_mov_b32_e32 v77, v1
	v_mov_b32_e32 v81, v1
	s_nop 0
	v_mov_b32_dpp v77, v72 row_ror:1 row_mask:0xf bank_mask:0xf
	v_mov_b32_dpp v81, v73 row_ror:15 row_mask:0xf bank_mask:0xf
	v_pk_mul_f32 v[72:73], v[124:125], v[84:85]
	v_pk_mul_f32 v[84:85], v[116:117], v[88:89]
	v_cndmask_b32_e64 v73, 0, v73, s[54:55]
	v_cndmask_b32_e64 v72, 0, v72, s[54:55]
	v_cndmask_b32_e64 v85, 0, v85, s[52:53]
	v_cndmask_b32_e64 v84, 0, v84, s[52:53]
	v_pk_add_f32 v[72:73], v[72:73], v[84:85]
	s_nop 0
	v_pk_add_f32 v[104:105], v[104:105], v[72:73] neg_lo:[0,1] neg_hi:[0,1]
	v_pk_mul_f32 v[72:73], v[120:121], v[76:77]
	v_pk_mul_f32 v[76:77], v[112:113], v[80:81]
	v_cndmask_b32_e64 v73, 0, v73, s[54:55]
	v_cndmask_b32_e64 v72, 0, v72, s[54:55]
	v_cndmask_b32_e64 v77, 0, v77, s[52:53]
	v_cndmask_b32_e64 v76, 0, v76, s[52:53]
	v_pk_add_f32 v[72:73], v[72:73], v[76:77]
	s_nop 0
	v_pk_add_f32 v[108:109], v[108:109], v[72:73] neg_lo:[0,1] neg_hi:[0,1]
	s_branch .LBB0_835
.Lconvgate_fix_17:
	v_cndmask_b32_e64 v83, v120, v112, s[44:45]
	v_mov_b32_e32 v89, v1
	v_mov_b32_e32 v108, v1
	v_mov_b32_e32 v109, v1
	v_mov_b32_dpp v89, v83 row_ror:15 row_mask:0xf bank_mask:0xf
	v_cndmask_b32_e64 v83, v121, v113, s[44:45]
	v_mov_b32_e32 v88, v1
	v_mov_b32_dpp v108, v121 row_ror:1 row_mask:0xf bank_mask:0xf
	v_mov_b32_dpp v109, v83 row_ror:15 row_mask:0xf bank_mask:0xf
	v_mov_b32_e32 v116, v103
	v_mov_b32_e32 v117, v107
	v_mov_b32_dpp v88, v120 row_ror:1 row_mask:0xf bank_mask:0xf
	v_mov_b32_e32 v92, v102
	v_mov_b32_e32 v93, v106
	v_pk_mul_f32 v[108:109], v[116:117], v[108:109]
	v_pk_mul_f32 v[88:89], v[92:93], v[88:89]
	v_cndmask_b32_e64 v93, 0, v109, s[80:81]
	v_cndmask_b32_e64 v83, v118, v104, s[44:45]
	v_mov_b32_e32 v109, v1
	v_cndmask_b32_e64 v92, 0, v89, s[80:81]
	v_cndmask_b32_e64 v89, 0, v108, s[82:83]
	v_mov_b32_e32 v108, v1
	v_mov_b32_dpp v109, v83 row_ror:15 row_mask:0xf bank_mask:0xf
	v_mov_b32_e32 v126, v1
	v_cndmask_b32_e64 v83, v119, v105, s[44:45]
	v_mov_b32_e32 v127, v1
	v_mov_b32_dpp v108, v118 row_ror:1 row_mask:0xf bank_mask:0xf
	v_mov_b32_e32 v116, v94
	v_mov_b32_e32 v117, v98
	v_mov_b32_dpp v126, v119 row_ror:1 row_mask:0xf bank_mask:0xf
	v_mov_b32_dpp v127, v83 row_ror:15 row_mask:0xf bank_mask:0xf
	v_mov_b32_e32 v132, v95
	v_mov_b32_e32 v133, v99
	v_cndmask_b32_e64 v88, 0, v88, s[82:83]
	v_pk_mul_f32 v[108:109], v[116:117], v[108:109]
	v_pk_mul_f32 v[126:127], v[132:133], v[126:127]
	v_cndmask_b32_e64 v116, 0, v109, s[80:81]
	v_cndmask_b32_e64 v108, 0, v108, s[82:83]
	v_cndmask_b32_e64 v117, 0, v127, s[80:81]
	v_cndmask_b32_e64 v109, 0, v126, s[82:83]
	v_pk_add_f32 v[88:89], v[88:89], v[92:93]
	s_nop 0
	v_pk_add_f32 v[96:97], v[96:97], v[88:89] neg_lo:[0,1] neg_hi:[0,1]
	v_pk_add_f32 v[88:89], v[108:109], v[116:117]
	s_nop 0
	v_pk_add_f32 v[100:101], v[100:101], v[88:89] neg_lo:[0,1] neg_hi:[0,1]
	s_branch .LBB0_839
.Lconvgate_fix_18:
	v_cndmask_b32_e64 v47, v112, v120, s[42:43]
	v_mov_b32_e32 v46, v1
	v_cndmask_b32_e64 v50, v112, v116, s[44:45]
	v_mov_b32_e32 v51, v106
	v_mov_b32_dpp v46, v47 row_ror:1 row_mask:0xf bank_mask:0xf
	v_mov_b32_e32 v47, v1
	v_mov_b32_e32 v120, v1
	v_mov_b32_e32 v132, v103
	v_mov_b32_dpp v47, v50 row_ror:15 row_mask:0xf bank_mask:0xf
	v_mov_b32_e32 v50, v102
	v_pk_mul_f32 v[46:47], v[50:51], v[46:47]
	v_mov_b32_e32 v133, v107
	v_cndmask_b32_e64 v50, 0, v47, s[76:77]
	v_cndmask_b32_e64 v47, v113, v121, s[42:43]
	v_mov_b32_e32 v121, v1
	v_cndmask_b32_e64 v83, v104, v118, s[42:43]
	v_mov_b32_dpp v120, v47 row_ror:1 row_mask:0xf bank_mask:0xf
	v_cndmask_b32_e64 v47, v113, v117, s[44:45]
	v_mov_b32_e32 v138, v95
	v_mov_b32_e32 v139, v99
	v_mov_b32_dpp v121, v47 row_ror:15 row_mask:0xf bank_mask:0xf
	v_pk_mul_f32 v[120:121], v[132:133], v[120:121]
	v_mov_b32_e32 v132, v94
	v_cndmask_b32_e64 v47, 0, v120, s[78:79]
	v_mov_b32_e32 v120, v1
	v_cndmask_b32_e64 v51, 0, v121, s[76:77]
	v_mov_b32_e32 v121, v1
	v_mov_b32_dpp v120, v83 row_ror:1 row_mask:0xf bank_mask:0xf
	v_cndmask_b32_e64 v83, v104, v108, s[44:45]
	v_mov_b32_e32 v133, v98
	v_cndmask_b32_e64 v46, 0, v46, s[78:79]
	v_mov_b32_dpp v121, v83 row_ror:15 row_mask:0xf bank_mask:0xf
	v_pk_mul_f32 v[120:121], v[132:133], v[120:121]
	v_cndmask_b32_e64 v83, v105, v119, s[42:43]
	v_mov_b32_e32 v132, v1
	v_mov_b32_e32 v133, v1
	v_cndmask_b32_e64 v118, 0, v121, s[76:77]
	v_mov_b32_dpp v132, v83 row_ror:1 row_mask:0xf bank_mask:0xf
	v_cndmask_b32_e64 v83, v105, v109, s[44:45]
	v_cndmask_b32_e64 v120, 0, v120, s[78:79]
	v_pk_add_f32 v[46:47], v[46:47], v[50:51]
	v_mov_b32_dpp v133, v83 row_ror:15 row_mask:0xf bank_mask:0xf
	v_pk_mul_f32 v[132:133], v[138:139], v[132:133]
	v_pk_add_f32 v[88:89], v[88:89], v[46:47] neg_lo:[0,1] neg_hi:[0,1]
	v_cndmask_b32_e64 v119, 0, v133, s[76:77]
	v_cndmask_b32_e64 v121, 0, v132, s[78:79]
	v_pk_add_f32 v[46:47], v[120:121], v[118:119]
	s_nop 0
	v_pk_add_f32 v[92:93], v[92:93], v[46:47] neg_lo:[0,1] neg_hi:[0,1]
	s_branch .LBB0_841
; __device__ __forceinline__ float dpp_ror1(float v) { return __int_as_float(__builtin_amdgcn_update_dpp(0, __float_as_int(v), 0x121, 0xF, 0xF, false)); }
; __device__ __forceinline__ float dpp_ror15(float v) { return __int_as_float(__builtin_amdgcn_update_dpp(0, __float_as_int(v), 0x12F, 0xF, 0xF, false)); }
;     __device__ __forceinline__ void operator()(f32x4 (&acc)[2][2][4][2], const Unit& u, int wr, int wc, int fr, int fq) const {
;     ...
;                         if (__any(lbad | rbad)) {
; #pragma unroll
;                             for (int bj = 0; bj < 2; ++bj) {
;                                 const f32x4 c = acc[ai][bj][m][n], cm = acc[ai][bj][m > 0 ? m - 1 : m][n], cp = acc[ai][bj][m < 3 ? m + 1 : m][n];
; #pragma unroll
;                                 for (int jj = 0; jj < 2; ++jj) {
;                                     const int j = 2 * jh + jj;
;                                     const float up = dpp_ror1(f15 ? cm[j] : c[j]), dn = dpp_ror15(f0 ? cp[j] : c[j]);
;                                     uu[bj][jj] -= (lbad ? w0[bj][jj] * up : 0.f) + (rbad ? w2[bj][jj] * dn : 0.f);
;                                 }
;                             }
.Lconvgate_fix_19:
	v_cndmask_b32_e64 v39, v116, v112, s[42:43]
	v_mov_b32_e32 v38, v1
	v_cndmask_b32_e64 v42, v116, v120, s[44:45]
	v_mov_b32_e32 v43, v106
	v_mov_b32_dpp v38, v39 row_ror:1 row_mask:0xf bank_mask:0xf
	v_mov_b32_e32 v39, v1
	v_mov_b32_e32 v112, v1
	v_mov_b32_e32 v132, v103
	v_mov_b32_dpp v39, v42 row_ror:15 row_mask:0xf bank_mask:0xf
	v_mov_b32_e32 v42, v102
	v_pk_mul_f32 v[38:39], v[42:43], v[38:39]
	v_mov_b32_e32 v133, v107
	v_cndmask_b32_e64 v42, 0, v39, s[72:73]
	v_cndmask_b32_e64 v39, v117, v113, s[42:43]
	v_mov_b32_e32 v113, v1
	v_cndmask_b32_e64 v83, v108, v104, s[42:43]
	v_mov_b32_dpp v112, v39 row_ror:1 row_mask:0xf bank_mask:0xf
	v_cndmask_b32_e64 v39, v117, v121, s[44:45]
	v_mov_b32_e32 v138, v95
	v_mov_b32_e32 v139, v99
	v_mov_b32_dpp v113, v39 row_ror:15 row_mask:0xf bank_mask:0xf
	v_pk_mul_f32 v[112:113], v[132:133], v[112:113]
	v_mov_b32_e32 v132, v94
	v_cndmask_b32_e64 v39, 0, v112, s[74:75]
	v_mov_b32_e32 v112, v1
	v_cndmask_b32_e64 v43, 0, v113, s[72:73]
	v_mov_b32_e32 v113, v1
	v_mov_b32_dpp v112, v83 row_ror:1 row_mask:0xf bank_mask:0xf
	v_cndmask_b32_e64 v83, v108, v118, s[44:45]
	v_mov_b32_e32 v133, v98
	v_cndmask_b32_e64 v38, 0, v38, s[74:75]
	v_mov_b32_dpp v113, v83 row_ror:15 row_mask:0xf bank_mask:0xf
	v_pk_mul_f32 v[112:113], v[132:133], v[112:113]
	v_cndmask_b32_e64 v83, v109, v105, s[42:43]
	v_mov_b32_e32 v132, v1
	v_mov_b32_e32 v133, v1
	v_cndmask_b32_e64 v104, 0, v113, s[72:73]
	v_mov_b32_dpp v132, v83 row_ror:1 row_mask:0xf bank_mask:0xf
	v_cndmask_b32_e64 v83, v109, v119, s[44:45]
	v_cndmask_b32_e64 v112, 0, v112, s[74:75]
	v_pk_add_f32 v[38:39], v[38:39], v[42:43]
	v_mov_b32_dpp v133, v83 row_ror:15 row_mask:0xf bank_mask:0xf
	v_pk_mul_f32 v[132:133], v[138:139], v[132:133]
	v_pk_add_f32 v[46:47], v[46:47], v[38:39] neg_lo:[0,1] neg_hi:[0,1]
	v_cndmask_b32_e64 v105, 0, v133, s[72:73]
	v_cndmask_b32_e64 v113, 0, v132, s[74:75]
	v_pk_add_f32 v[38:39], v[112:113], v[104:105]
	s_nop 0
	v_pk_add_f32 v[50:51], v[50:51], v[38:39] neg_lo:[0,1] neg_hi:[0,1]
	s_branch .LBB0_843
.Lconvgate_fix_20:
	v_cndmask_b32_e64 v83, v120, v116, s[42:43]
	v_mov_b32_e32 v104, v1
	v_mov_b32_e32 v105, v1
	v_mov_b32_e32 v116, v1
	v_mov_b32_dpp v104, v83 row_ror:1 row_mask:0xf bank_mask:0xf
	v_cndmask_b32_e64 v83, v121, v117, s[42:43]
	v_mov_b32_e32 v117, v1
	v_mov_b32_dpp v105, v120 row_ror:15 row_mask:0xf bank_mask:0xf
	v_mov_b32_e32 v112, v102
	v_mov_b32_e32 v113, v106
	v_mov_b32_dpp v116, v83 row_ror:1 row_mask:0xf bank_mask:0xf
	v_mov_b32_dpp v117, v121 row_ror:15 row_mask:0xf bank_mask:0xf
	v_mov_b32_e32 v120, v103
	v_mov_b32_e32 v121, v107
	v_pk_mul_f32 v[104:105], v[112:113], v[104:105]
	v_pk_mul_f32 v[116:117], v[120:121], v[116:117]
	v_cndmask_b32_e64 v112, 0, v105, s[68:69]
	v_cndmask_b32_e64 v113, 0, v117, s[68:69]
	v_cndmask_b32_e64 v105, 0, v116, s[70:71]
	v_cndmask_b32_e64 v83, v118, v108, s[42:43]
	v_mov_b32_e32 v116, v1
	v_mov_b32_e32 v117, v1
	v_mov_b32_e32 v120, v94
	v_mov_b32_dpp v116, v83 row_ror:1 row_mask:0xf bank_mask:0xf
	v_mov_b32_dpp v117, v118 row_ror:15 row_mask:0xf bank_mask:0xf
	v_mov_b32_e32 v121, v98
	v_pk_mul_f32 v[116:117], v[120:121], v[116:117]
	v_cndmask_b32_e64 v83, v119, v109, s[42:43]
	v_mov_b32_e32 v120, v1
	v_mov_b32_e32 v121, v1
	v_mov_b32_e32 v118, v95
	v_mov_b32_dpp v120, v83 row_ror:1 row_mask:0xf bank_mask:0xf
	v_mov_b32_dpp v121, v119 row_ror:15 row_mask:0xf bank_mask:0xf
	v_mov_b32_e32 v119, v99
	v_cndmask_b32_e64 v104, 0, v104, s[70:71]
	v_pk_mul_f32 v[118:119], v[118:119], v[120:121]
	v_cndmask_b32_e64 v108, 0, v117, s[68:69]
	v_cndmask_b32_e64 v116, 0, v116, s[70:71]
	v_cndmask_b32_e64 v109, 0, v119, s[68:69]
	v_cndmask_b32_e64 v117, 0, v118, s[70:71]
	v_pk_add_f32 v[104:105], v[104:105], v[112:113]
	s_nop 0
	v_pk_add_f32 v[38:39], v[38:39], v[104:105] neg_lo:[0,1] neg_hi:[0,1]
	v_pk_add_f32 v[104:105], v[116:117], v[108:109]
	s_nop 0
	v_pk_add_f32 v[42:43], v[42:43], v[104:105] neg_lo:[0,1] neg_hi:[0,1]
	s_branch .LBB0_845
.Lconvgate_fix_21:
	v_mov_b32_e32 v30, v1
	v_cndmask_b32_e64 v83, v116, v108, s[44:45]
	v_mov_b32_e32 v31, v1
	v_mov_b32_dpp v30, v116 row_ror:1 row_mask:0xf bank_mask:0xf
	v_mov_b32_e32 v104, v102
	v_mov_b32_dpp v31, v83 row_ror:15 row_mask:0xf bank_mask:0xf
	v_mov_b32_e32 v105, v106
	v_pk_mul_f32 v[30:31], v[104:105], v[30:31]
	v_mov_b32_e32 v118, v1
	v_cndmask_b32_e64 v104, 0, v31, s[64:65]
	v_cndmask_b32_e64 v31, v117, v109, s[44:45]
	v_mov_b32_e32 v119, v1
	v_mov_b32_dpp v118, v117 row_ror:1 row_mask:0xf bank_mask:0xf
	v_mov_b32_e32 v120, v103
	v_mov_b32_dpp v119, v31 row_ror:15 row_mask:0xf bank_mask:0xf
	v_mov_b32_e32 v121, v107
	v_pk_mul_f32 v[118:119], v[120:121], v[118:119]
	v_cndmask_b32_e64 v83, v112, v34, s[44:45]
	v_cndmask_b32_e64 v105, 0, v119, s[64:65]
	v_mov_b32_e32 v119, v1
	v_cndmask_b32_e64 v31, 0, v118, s[66:67]
	v_mov_b32_e32 v118, v1
	v_mov_b32_dpp v119, v83 row_ror:15 row_mask:0xf bank_mask:0xf
	v_mov_b32_e32 v132, v1
	v_cndmask_b32_e64 v83, v113, v35, s[44:45]
	v_mov_b32_e32 v133, v1
	v_mov_b32_dpp v118, v112 row_ror:1 row_mask:0xf bank_mask:0xf
	v_mov_b32_e32 v120, v94
	v_mov_b32_e32 v121, v98
	v_mov_b32_dpp v132, v113 row_ror:1 row_mask:0xf bank_mask:0xf
	v_mov_b32_dpp v133, v83 row_ror:15 row_mask:0xf bank_mask:0xf
	v_mov_b32_e32 v138, v95
	v_mov_b32_e32 v139, v99
	v_cndmask_b32_e64 v30, 0, v30, s[66:67]
	v_pk_mul_f32 v[118:119], v[120:121], v[118:119]
	v_pk_mul_f32 v[132:133], v[138:139], v[132:133]
	v_cndmask_b32_e64 v120, 0, v119, s[64:65]
	v_cndmask_b32_e64 v118, 0, v118, s[66:67]
	v_cndmask_b32_e64 v121, 0, v133, s[64:65]
	v_cndmask_b32_e64 v119, 0, v132, s[66:67]
	v_pk_add_f32 v[30:31], v[30:31], v[104:105]
	s_nop 0
	v_pk_add_f32 v[22:23], v[22:23], v[30:31] neg_lo:[0,1] neg_hi:[0,1]
	v_pk_add_f32 v[30:31], v[118:119], v[120:121]
	s_nop 0
	v_pk_add_f32 v[26:27], v[26:27], v[30:31] neg_lo:[0,1] neg_hi:[0,1]
	s_branch .LBB0_847
; __device__ __forceinline__ float dpp_ror1(float v) { return __int_as_float(__builtin_amdgcn_update_dpp(0, __float_as_int(v), 0x121, 0xF, 0xF, false)); }
; __device__ __forceinline__ float dpp_ror15(float v) { return __int_as_float(__builtin_amdgcn_update_dpp(0, __float_as_int(v), 0x12F, 0xF, 0xF, false)); }
;     __device__ __forceinline__ void operator()(f32x4 (&acc)[2][2][4][2], const Unit& u, int wr, int wc, int fr, int fq) const {
;     ...
;                         if (__any(lbad | rbad)) {
; #pragma unroll
;                             for (int bj = 0; bj < 2; ++bj) {
;                                 const f32x4 c = acc[ai][bj][m][n], cm = acc[ai][bj][m > 0 ? m - 1 : m][n], cp = acc[ai][bj][m < 3 ? m + 1 : m][n];
; #pragma unroll
;                                 for (int jj = 0; jj < 2; ++jj) {
;                                     const int j = 2 * jh + jj;
;                                     const float up = dpp_ror1(f15 ? cm[j] : c[j]), dn = dpp_ror15(f0 ? cp[j] : c[j]);
;                                     uu[bj][jj] -= (lbad ? w0[bj][jj] * up : 0.f) + (rbad ? w2[bj][jj] * dn : 0.f);
;                                 }
;                             }
.Lconvgate_fix_22:
	v_cndmask_b32_e64 v83, v108, v116, s[42:43]
	v_mov_b32_e32 v118, v1
	v_mov_b32_e32 v119, v1
	v_mov_b32_e32 v120, v102
	v_mov_b32_dpp v118, v83 row_ror:1 row_mask:0xf bank_mask:0xf
	v_cndmask_b32_e64 v83, v108, v104, s[44:45]
	v_mov_b32_e32 v121, v106
	v_mov_b32_e32 v132, v103
	v_mov_b32_dpp v119, v83 row_ror:15 row_mask:0xf bank_mask:0xf
	v_pk_mul_f32 v[118:119], v[120:121], v[118:119]
	v_cndmask_b32_e64 v83, v109, v117, s[42:43]
	v_mov_b32_e32 v120, v1
	v_mov_b32_e32 v121, v1
	v_mov_b32_e32 v133, v107
	v_mov_b32_dpp v120, v83 row_ror:1 row_mask:0xf bank_mask:0xf
	v_cndmask_b32_e64 v83, v109, v105, s[44:45]
	v_cndmask_b32_e64 v116, 0, v119, s[60:61]
	v_mov_b32_e32 v138, v95
	v_mov_b32_dpp v121, v83 row_ror:15 row_mask:0xf bank_mask:0xf
	v_pk_mul_f32 v[120:121], v[132:133], v[120:121]
	v_cndmask_b32_e64 v83, v34, v112, s[42:43]
	v_cndmask_b32_e64 v119, 0, v120, s[62:63]
	v_mov_b32_e32 v120, v1
	v_cndmask_b32_e64 v117, 0, v121, s[60:61]
	v_mov_b32_e32 v121, v1
	v_mov_b32_dpp v120, v83 row_ror:1 row_mask:0xf bank_mask:0xf
	v_cndmask_b32_e64 v83, v34, v30, s[44:45]
	v_mov_b32_e32 v132, v94
	v_mov_b32_e32 v133, v98
	v_mov_b32_dpp v121, v83 row_ror:15 row_mask:0xf bank_mask:0xf
	v_pk_mul_f32 v[120:121], v[132:133], v[120:121]
	v_cndmask_b32_e64 v83, v35, v113, s[42:43]
	v_mov_b32_e32 v132, v1
	v_mov_b32_e32 v133, v1
	v_mov_b32_e32 v139, v99
	v_mov_b32_dpp v132, v83 row_ror:1 row_mask:0xf bank_mask:0xf
	v_cndmask_b32_e64 v83, v35, v31, s[44:45]
	v_cndmask_b32_e64 v118, 0, v118, s[62:63]
	v_cndmask_b32_e64 v112, 0, v121, s[60:61]
	v_mov_b32_dpp v133, v83 row_ror:15 row_mask:0xf bank_mask:0xf
	v_pk_mul_f32 v[132:133], v[138:139], v[132:133]
	v_cndmask_b32_e64 v120, 0, v120, s[62:63]
	v_cndmask_b32_e64 v113, 0, v133, s[60:61]
	v_cndmask_b32_e64 v121, 0, v132, s[62:63]
	v_pk_add_f32 v[116:117], v[118:119], v[116:117]
	v_pk_add_f32 v[112:113], v[120:121], v[112:113]
	v_pk_add_f32 v[10:11], v[10:11], v[116:117] neg_lo:[0,1] neg_hi:[0,1]
	v_pk_add_f32 v[18:19], v[18:19], v[112:113] neg_lo:[0,1] neg_hi:[0,1]
	s_branch .LBB0_849
.Lconvgate_fix_23:
	v_cndmask_b32_e64 v83, v104, v108, s[42:43]
	v_mov_b32_e32 v118, v1
	v_mov_b32_e32 v119, v1
	v_mov_b32_e32 v120, v102
	v_mov_b32_dpp v118, v83 row_ror:1 row_mask:0xf bank_mask:0xf
	v_cndmask_b32_e64 v83, v104, v116, s[44:45]
	v_mov_b32_e32 v121, v106
	v_mov_b32_e32 v128, v103
	v_mov_b32_dpp v119, v83 row_ror:15 row_mask:0xf bank_mask:0xf
	v_pk_mul_f32 v[118:119], v[120:121], v[118:119]
	v_cndmask_b32_e64 v83, v105, v109, s[42:43]
	v_mov_b32_e32 v120, v1
	v_mov_b32_e32 v121, v1
	v_mov_b32_e32 v129, v107
	v_mov_b32_dpp v120, v83 row_ror:1 row_mask:0xf bank_mask:0xf
	v_cndmask_b32_e64 v83, v105, v117, s[44:45]
	v_cndmask_b32_e64 v108, 0, v119, s[56:57]
	v_cndmask_b32_e64 v34, v30, v34, s[42:43]
	v_mov_b32_dpp v121, v83 row_ror:15 row_mask:0xf bank_mask:0xf
	v_pk_mul_f32 v[120:121], v[128:129], v[120:121]
	v_mov_b32_e32 v128, v94
	v_cndmask_b32_e64 v119, 0, v120, s[58:59]
	v_mov_b32_e32 v120, v1
	v_cndmask_b32_e64 v109, 0, v121, s[56:57]
	v_mov_b32_e32 v121, v1
	v_mov_b32_dpp v120, v34 row_ror:1 row_mask:0xf bank_mask:0xf
	v_cndmask_b32_e64 v34, v30, v112, s[44:45]
	v_mov_b32_e32 v129, v98
	v_cndmask_b32_e64 v35, v31, v35, s[42:43]
	v_mov_b32_dpp v121, v34 row_ror:15 row_mask:0xf bank_mask:0xf
	v_pk_mul_f32 v[120:121], v[128:129], v[120:121]
	v_mov_b32_e32 v128, v1
	v_mov_b32_e32 v129, v1
	v_mov_b32_e32 v132, v95
	v_mov_b32_dpp v128, v35 row_ror:1 row_mask:0xf bank_mask:0xf
	v_cndmask_b32_e64 v35, v31, v113, s[44:45]
	v_mov_b32_e32 v133, v99
	v_cndmask_b32_e64 v118, 0, v118, s[58:59]
	v_mov_b32_dpp v129, v35 row_ror:15 row_mask:0xf bank_mask:0xf
	v_pk_mul_f32 v[128:129], v[132:133], v[128:129]
	v_cndmask_b32_e64 v34, 0, v121, s[56:57]
	v_cndmask_b32_e64 v120, 0, v120, s[58:59]
	v_cndmask_b32_e64 v35, 0, v129, s[56:57]
	v_cndmask_b32_e64 v121, 0, v128, s[58:59]
	v_pk_add_f32 v[108:109], v[118:119], v[108:109]
	v_pk_add_f32 v[34:35], v[120:121], v[34:35]
	v_pk_add_f32 v[2:3], v[2:3], v[108:109] neg_lo:[0,1] neg_hi:[0,1]
	v_pk_add_f32 v[6:7], v[6:7], v[34:35] neg_lo:[0,1] neg_hi:[0,1]
	s_branch .LBB0_851
.Lconvgate_fix_24:
	v_cndmask_b32_e64 v35, v116, v104, s[42:43]
	v_mov_b32_e32 v34, v1
	v_mov_b32_e32 v108, v102
	v_mov_b32_e32 v109, v106
	v_mov_b32_dpp v34, v35 row_ror:1 row_mask:0xf bank_mask:0xf
	v_mov_b32_e32 v35, v1
	v_mov_b32_e32 v104, v1
	v_mov_b32_e32 v106, v103
	v_mov_b32_dpp v35, v116 row_ror:15 row_mask:0xf bank_mask:0xf
	v_pk_mul_f32 v[34:35], v[108:109], v[34:35]
	v_cndmask_b32_e64 v30, v112, v30, s[42:43]
	v_cndmask_b32_e64 v102, 0, v35, s[52:53]
	v_cndmask_b32_e64 v35, v117, v105, s[42:43]
	v_mov_b32_e32 v105, v1
	v_cndmask_b32_e64 v31, v113, v31, s[42:43]
	v_mov_b32_dpp v104, v35 row_ror:1 row_mask:0xf bank_mask:0xf
	v_mov_b32_dpp v105, v117 row_ror:15 row_mask:0xf bank_mask:0xf
	v_pk_mul_f32 v[104:105], v[106:107], v[104:105]
	v_mov_b32_e32 v106, v94
	v_cndmask_b32_e64 v103, 0, v105, s[52:53]
	v_cndmask_b32_e64 v35, 0, v104, s[54:55]
	v_mov_b32_e32 v104, v1
	v_mov_b32_e32 v105, v1
	v_mov_b32_e32 v107, v98
	v_mov_b32_dpp v104, v30 row_ror:1 row_mask:0xf bank_mask:0xf
	v_mov_b32_dpp v105, v112 row_ror:15 row_mask:0xf bank_mask:0xf
	v_pk_mul_f32 v[104:105], v[106:107], v[104:105]
	v_mov_b32_e32 v98, v95
	v_cndmask_b32_e64 v30, 0, v105, s[52:53]
	v_cndmask_b32_e64 v94, 0, v104, s[54:55]
	v_mov_b32_e32 v104, v1
	v_mov_b32_e32 v105, v1
	v_cndmask_b32_e64 v34, 0, v34, s[54:55]
	v_mov_b32_dpp v104, v31 row_ror:1 row_mask:0xf bank_mask:0xf
	v_mov_b32_dpp v105, v113 row_ror:15 row_mask:0xf bank_mask:0xf
	v_pk_mul_f32 v[98:99], v[98:99], v[104:105]
	v_pk_add_f32 v[34:35], v[34:35], v[102:103]
	v_cndmask_b32_e64 v31, 0, v99, s[52:53]
	v_cndmask_b32_e64 v95, 0, v98, s[54:55]
	v_pk_add_f32 v[30:31], v[94:95], v[30:31]
	v_pk_add_f32 v[70:71], v[70:71], v[34:35] neg_lo:[0,1] neg_hi:[0,1]
	v_pk_add_f32 v[74:75], v[74:75], v[30:31] neg_lo:[0,1] neg_hi:[0,1]
	s_branch .LBB0_853
; __device__ __forceinline__ float dpp_ror1(float v) { return __int_as_float(__builtin_amdgcn_update_dpp(0, __float_as_int(v), 0x121, 0xF, 0xF, false)); }
; __device__ __forceinline__ float dpp_ror15(float v) { return __int_as_float(__builtin_amdgcn_update_dpp(0, __float_as_int(v), 0x12F, 0xF, 0xF, false)); }
;     __device__ __forceinline__ void operator()(f32x4 (&acc)[2][2][4][2], const Unit& u, int wr, int wc, int fr, int fq) const {
;     ...
;                         if (__any(lbad | rbad)) {
; #pragma unroll
;                             for (int bj = 0; bj < 2; ++bj) {
;                                 const f32x4 c = acc[ai][bj][m][n], cm = acc[ai][bj][m > 0 ? m - 1 : m][n], cp = acc[ai][bj][m < 3 ? m + 1 : m][n];
; #pragma unroll
;                                 for (int jj = 0; jj < 2; ++jj) {
;                                     const int j = 2 * jh + jj;
;                                     const float up = dpp_ror1(f15 ? cm[j] : c[j]), dn = dpp_ror15(f0 ? cp[j] : c[j]);
;                                     uu[bj][jj] -= (lbad ? w0[bj][jj] * up : 0.f) + (rbad ? w2[bj][jj] * dn : 0.f);
;                                 }
;                             }
.Lconvgate_fix_25:
	v_cndmask_b32_e64 v83, v68, v34, s[44:45]
	v_mov_b32_e32 v106, v1
	v_mov_b32_e32 v104, v1
	v_mov_b32_e32 v105, v1
	v_mov_b32_dpp v106, v83 row_ror:15 row_mask:0xf bank_mask:0xf
	v_cndmask_b32_e64 v83, v69, v35, s[44:45]
	v_mov_b32_e32 v107, v1
	v_mov_b32_dpp v104, v68 row_ror:1 row_mask:0xf bank_mask:0xf
	v_mov_b32_dpp v105, v69 row_ror:1 row_mask:0xf bank_mask:0xf
	v_mov_b32_dpp v107, v83 row_ror:15 row_mask:0xf bank_mask:0xf
	v_cndmask_b32_e64 v83, v60, v30, s[44:45]
	v_mov_b32_e32 v110, v1
	v_pk_mul_f32 v[104:105], v[76:77], v[104:105]
	v_pk_mul_f32 v[106:107], v[72:73], v[106:107]
	v_mov_b32_e32 v108, v1
	v_mov_b32_dpp v110, v83 row_ror:15 row_mask:0xf bank_mask:0xf
	v_mov_b32_e32 v109, v1
	v_cndmask_b32_e64 v83, v61, v31, s[44:45]
	v_mov_b32_e32 v111, v1
	v_cndmask_b32_e64 v105, 0, v105, s[82:83]
	v_cndmask_b32_e64 v104, 0, v104, s[82:83]
	v_cndmask_b32_e64 v107, 0, v107, s[80:81]
	v_cndmask_b32_e64 v106, 0, v106, s[80:81]
	v_mov_b32_dpp v108, v60 row_ror:1 row_mask:0xf bank_mask:0xf
	v_mov_b32_dpp v109, v61 row_ror:1 row_mask:0xf bank_mask:0xf
	v_mov_b32_dpp v111, v83 row_ror:15 row_mask:0xf bank_mask:0xf
	v_pk_add_f32 v[104:105], v[104:105], v[106:107]
	v_pk_mul_f32 v[106:107], v[62:63], v[110:111]
	v_pk_add_f32 v[56:57], v[56:57], v[104:105] neg_lo:[0,1] neg_hi:[0,1]
	v_pk_mul_f32 v[104:105], v[66:67], v[108:109]
	v_cndmask_b32_e64 v107, 0, v107, s[80:81]
	v_cndmask_b32_e64 v105, 0, v105, s[82:83]
	v_cndmask_b32_e64 v104, 0, v104, s[82:83]
	v_cndmask_b32_e64 v106, 0, v106, s[80:81]
	v_pk_add_f32 v[104:105], v[104:105], v[106:107]
	s_nop 0
	v_pk_add_f32 v[64:65], v[64:65], v[104:105] neg_lo:[0,1] neg_hi:[0,1]
	s_branch .LBB0_855
.Lconvgate_fix_26:
	v_cndmask_b32_e64 v83, v34, v68, s[42:43]
	v_mov_b32_e32 v68, v1
	v_mov_b32_e32 v104, v1
	v_mov_b32_e32 v105, v1
	v_mov_b32_dpp v68, v83 row_ror:1 row_mask:0xf bank_mask:0xf
	v_cndmask_b32_e64 v83, v34, v52, s[44:45]
	v_mov_b32_e32 v106, v1
	v_mov_b32_e32 v107, v1
	v_mov_b32_dpp v104, v83 row_ror:15 row_mask:0xf bank_mask:0xf
	v_cndmask_b32_e64 v83, v35, v69, s[42:43]
	v_mov_b32_e32 v69, v1
	s_nop 1
	v_mov_b32_dpp v69, v83 row_ror:1 row_mask:0xf bank_mask:0xf
	v_cndmask_b32_e64 v83, v35, v53, s[44:45]
	v_pk_mul_f32 v[68:69], v[76:77], v[68:69]
	s_nop 0
	v_mov_b32_dpp v105, v83 row_ror:15 row_mask:0xf bank_mask:0xf
	v_cndmask_b32_e64 v83, v30, v60, s[42:43]
	v_mov_b32_e32 v60, v1
	v_pk_mul_f32 v[104:105], v[72:73], v[104:105]
	v_cndmask_b32_e64 v69, 0, v69, s[78:79]
	v_mov_b32_dpp v60, v83 row_ror:1 row_mask:0xf bank_mask:0xf
	v_cndmask_b32_e64 v83, v30, v48, s[44:45]
	v_cndmask_b32_e64 v68, 0, v68, s[78:79]
	v_cndmask_b32_e64 v105, 0, v105, s[76:77]
	v_mov_b32_dpp v106, v83 row_ror:15 row_mask:0xf bank_mask:0xf
	v_cndmask_b32_e64 v83, v31, v61, s[42:43]
	v_mov_b32_e32 v61, v1
	v_cndmask_b32_e64 v104, 0, v104, s[76:77]
	v_pk_add_f32 v[68:69], v[68:69], v[104:105]
	v_mov_b32_dpp v61, v83 row_ror:1 row_mask:0xf bank_mask:0xf
	v_cndmask_b32_e64 v83, v31, v49, s[44:45]
	v_pk_add_f32 v[56:57], v[56:57], v[68:69] neg_lo:[0,1] neg_hi:[0,1]
	v_pk_mul_f32 v[60:61], v[66:67], v[60:61]
	v_mov_b32_dpp v107, v83 row_ror:15 row_mask:0xf bank_mask:0xf
	v_pk_mul_f32 v[68:69], v[62:63], v[106:107]
	v_cndmask_b32_e64 v61, 0, v61, s[78:79]
	v_cndmask_b32_e64 v60, 0, v60, s[78:79]
	v_cndmask_b32_e64 v69, 0, v69, s[76:77]
	v_cndmask_b32_e64 v68, 0, v68, s[76:77]
	v_pk_add_f32 v[60:61], v[60:61], v[68:69]
	s_nop 0
	v_pk_add_f32 v[64:65], v[64:65], v[60:61] neg_lo:[0,1] neg_hi:[0,1]
	s_branch .LBB0_859
.Lconvgate_fix_27:
	v_cndmask_b32_e64 v64, v52, v34, s[42:43]
	v_mov_b32_e32 v34, v1
	v_cndmask_b32_e64 v65, v52, v44, s[44:45]
	v_cndmask_b32_e64 v68, v53, v45, s[44:45]
	v_mov_b32_dpp v34, v64 row_ror:1 row_mask:0xf bank_mask:0xf
	v_mov_b32_e32 v64, v1
	v_cndmask_b32_e64 v69, v48, v40, s[44:45]
	v_cndmask_b32_e64 v83, v49, v41, s[44:45]
	v_mov_b32_dpp v64, v65 row_ror:15 row_mask:0xf bank_mask:0xf
	v_cndmask_b32_e64 v65, v53, v35, s[42:43]
	v_mov_b32_e32 v35, v1
	s_nop 1
	v_mov_b32_dpp v35, v65 row_ror:1 row_mask:0xf bank_mask:0xf
	v_mov_b32_e32 v65, v1
	v_pk_mul_f32 v[34:35], v[76:77], v[34:35]
	s_nop 0
	v_mov_b32_dpp v65, v68 row_ror:15 row_mask:0xf bank_mask:0xf
	v_cndmask_b32_e64 v68, v48, v30, s[42:43]
	v_mov_b32_e32 v30, v1
	v_pk_mul_f32 v[64:65], v[72:73], v[64:65]
	v_cndmask_b32_e64 v35, 0, v35, s[74:75]
	v_mov_b32_dpp v30, v68 row_ror:1 row_mask:0xf bank_mask:0xf
	v_mov_b32_e32 v68, v1
	v_cndmask_b32_e64 v34, 0, v34, s[74:75]
	v_cndmask_b32_e64 v65, 0, v65, s[72:73]
	v_mov_b32_dpp v68, v69 row_ror:15 row_mask:0xf bank_mask:0xf
	v_cndmask_b32_e64 v69, v49, v31, s[42:43]
	v_mov_b32_e32 v31, v1
	v_cndmask_b32_e64 v64, 0, v64, s[72:73]
	v_pk_add_f32 v[34:35], v[34:35], v[64:65]
	v_mov_b32_dpp v31, v69 row_ror:1 row_mask:0xf bank_mask:0xf
	v_mov_b32_e32 v69, v1
	v_pk_add_f32 v[56:57], v[56:57], v[34:35] neg_lo:[0,1] neg_hi:[0,1]
	v_pk_mul_f32 v[30:31], v[66:67], v[30:31]
	v_mov_b32_dpp v69, v83 row_ror:15 row_mask:0xf bank_mask:0xf
	v_pk_mul_f32 v[34:35], v[62:63], v[68:69]
	v_cndmask_b32_e64 v31, 0, v31, s[74:75]
	v_cndmask_b32_e64 v30, 0, v30, s[74:75]
	v_cndmask_b32_e64 v35, 0, v35, s[72:73]
	v_cndmask_b32_e64 v34, 0, v34, s[72:73]
	v_pk_add_f32 v[30:31], v[30:31], v[34:35]
	s_nop 0
	v_pk_add_f32 v[60:61], v[60:61], v[30:31] neg_lo:[0,1] neg_hi:[0,1]
	s_branch .LBB0_863
; __device__ __forceinline__ float dpp_ror1(float v) { return __int_as_float(__builtin_amdgcn_update_dpp(0, __float_as_int(v), 0x121, 0xF, 0xF, false)); }
; __device__ __forceinline__ float dpp_ror15(float v) { return __int_as_float(__builtin_amdgcn_update_dpp(0, __float_as_int(v), 0x12F, 0xF, 0xF, false)); }
;     __device__ __forceinline__ void operator()(f32x4 (&acc)[2][2][4][2], const Unit& u, int wr, int wc, int fr, int fq) const {
;     ...
;                         if (__any(lbad | rbad)) {
; #pragma unroll
;                             for (int bj = 0; bj < 2; ++bj) {
;                                 const f32x4 c = acc[ai][bj][m][n], cm = acc[ai][bj][m > 0 ? m - 1 : m][n], cp = acc[ai][bj][m < 3 ? m + 1 : m][n];
; #pragma unroll
;                                 for (int jj = 0; jj < 2; ++jj) {
;                                     const int j = 2 * jh + jj;
;                                     const float up = dpp_ror1(f15 ? cm[j] : c[j]), dn = dpp_ror15(f0 ? cp[j] : c[j]);
;                                     uu[bj][jj] -= (lbad ? w0[bj][jj] * up : 0.f) + (rbad ? w2[bj][jj] * dn : 0.f);
;                                 }
;                             }
.Lconvgate_fix_28:
	v_cndmask_b32_e64 v47, v44, v52, s[42:43]
	v_mov_b32_e32 v46, v1
	v_mov_b32_e32 v50, v1
	v_mov_b32_e32 v51, v1
	v_mov_b32_dpp v46, v47 row_ror:1 row_mask:0xf bank_mask:0xf
	v_mov_b32_dpp v50, v44 row_ror:15 row_mask:0xf bank_mask:0xf
	v_cndmask_b32_e64 v44, v45, v53, s[42:43]
	v_mov_b32_e32 v47, v1
	v_mov_b32_dpp v51, v45 row_ror:15 row_mask:0xf bank_mask:0xf
	v_cndmask_b32_e64 v45, v40, v48, s[42:43]
	v_mov_b32_dpp v47, v44 row_ror:1 row_mask:0xf bank_mask:0xf
	v_mov_b32_e32 v44, v1
	v_mov_b32_e32 v48, v1
	s_nop 0
	v_mov_b32_dpp v44, v45 row_ror:1 row_mask:0xf bank_mask:0xf
	v_mov_b32_dpp v48, v40 row_ror:15 row_mask:0xf bank_mask:0xf
	v_cndmask_b32_e64 v40, v41, v49, s[42:43]
	v_mov_b32_e32 v45, v1
	v_mov_b32_e32 v49, v1
	s_nop 0
	v_mov_b32_dpp v45, v40 row_ror:1 row_mask:0xf bank_mask:0xf
	v_mov_b32_dpp v49, v41 row_ror:15 row_mask:0xf bank_mask:0xf
	v_pk_mul_f32 v[40:41], v[76:77], v[46:47]
	v_pk_mul_f32 v[46:47], v[72:73], v[50:51]
	v_cndmask_b32_e64 v41, 0, v41, s[70:71]
	v_cndmask_b32_e64 v40, 0, v40, s[70:71]
	v_cndmask_b32_e64 v47, 0, v47, s[68:69]
	v_cndmask_b32_e64 v46, 0, v46, s[68:69]
	v_pk_add_f32 v[40:41], v[40:41], v[46:47]
	s_nop 0
	v_pk_add_f32 v[30:31], v[30:31], v[40:41] neg_lo:[0,1] neg_hi:[0,1]
	v_pk_mul_f32 v[40:41], v[66:67], v[44:45]
	v_pk_mul_f32 v[44:45], v[62:63], v[48:49]
	v_cndmask_b32_e64 v41, 0, v41, s[70:71]
	v_cndmask_b32_e64 v40, 0, v40, s[70:71]
	v_cndmask_b32_e64 v45, 0, v45, s[68:69]
	v_cndmask_b32_e64 v44, 0, v44, s[68:69]
	v_pk_add_f32 v[40:41], v[40:41], v[44:45]
	s_nop 0
	v_pk_add_f32 v[34:35], v[34:35], v[40:41] neg_lo:[0,1] neg_hi:[0,1]
	s_branch .LBB0_867
.Lconvgate_fix_29:
	v_cndmask_b32_e64 v39, v34, v28, s[44:45]
	v_mov_b32_e32 v40, v1
	v_mov_b32_e32 v38, v1
	v_cndmask_b32_e64 v42, v35, v29, s[44:45]
	v_mov_b32_dpp v40, v39 row_ror:15 row_mask:0xf bank_mask:0xf
	v_mov_b32_e32 v39, v1
	v_mov_b32_e32 v41, v1
	v_mov_b32_dpp v38, v34 row_ror:1 row_mask:0xf bank_mask:0xf
	v_mov_b32_dpp v39, v35 row_ror:1 row_mask:0xf bank_mask:0xf
	v_mov_b32_dpp v41, v42 row_ror:15 row_mask:0xf bank_mask:0xf
	v_cndmask_b32_e64 v43, v30, v24, s[44:45]
	v_mov_b32_e32 v44, v1
	v_pk_mul_f32 v[38:39], v[76:77], v[38:39]
	v_pk_mul_f32 v[40:41], v[72:73], v[40:41]
	v_mov_b32_e32 v42, v1
	v_mov_b32_dpp v44, v43 row_ror:15 row_mask:0xf bank_mask:0xf
	v_mov_b32_e32 v43, v1
	v_cndmask_b32_e64 v46, v31, v25, s[44:45]
	v_mov_b32_e32 v45, v1
	v_cndmask_b32_e64 v39, 0, v39, s[66:67]
	v_cndmask_b32_e64 v38, 0, v38, s[66:67]
	v_cndmask_b32_e64 v41, 0, v41, s[64:65]
	v_cndmask_b32_e64 v40, 0, v40, s[64:65]
	v_mov_b32_dpp v42, v30 row_ror:1 row_mask:0xf bank_mask:0xf
	v_mov_b32_dpp v43, v31 row_ror:1 row_mask:0xf bank_mask:0xf
	v_mov_b32_dpp v45, v46 row_ror:15 row_mask:0xf bank_mask:0xf
	v_pk_add_f32 v[38:39], v[38:39], v[40:41]
	v_pk_mul_f32 v[40:41], v[62:63], v[44:45]
	v_pk_add_f32 v[32:33], v[32:33], v[38:39] neg_lo:[0,1] neg_hi:[0,1]
	v_pk_mul_f32 v[38:39], v[66:67], v[42:43]
	v_cndmask_b32_e64 v41, 0, v41, s[64:65]
	v_cndmask_b32_e64 v39, 0, v39, s[66:67]
	v_cndmask_b32_e64 v38, 0, v38, s[66:67]
	v_cndmask_b32_e64 v40, 0, v40, s[64:65]
	v_pk_add_f32 v[38:39], v[38:39], v[40:41]
	s_nop 0
	v_pk_add_f32 v[36:37], v[36:37], v[38:39] neg_lo:[0,1] neg_hi:[0,1]
	s_branch .LBB0_871
.Lconvgate_fix_30:
	v_cndmask_b32_e64 v33, v28, v34, s[42:43]
	v_mov_b32_e32 v32, v1
	v_mov_b32_e32 v34, v1
	v_cndmask_b32_e64 v35, v29, v35, s[42:43]
	v_mov_b32_dpp v32, v33 row_ror:1 row_mask:0xf bank_mask:0xf
	v_cndmask_b32_e64 v33, v28, v20, s[44:45]
	v_cndmask_b32_e64 v36, v29, v21, s[44:45]
	v_cndmask_b32_e64 v37, v24, v12, s[44:45]
	v_mov_b32_dpp v34, v33 row_ror:15 row_mask:0xf bank_mask:0xf
	v_mov_b32_e32 v33, v1
	v_cndmask_b32_e64 v38, v25, v13, s[44:45]
	s_nop 0
	v_mov_b32_dpp v33, v35 row_ror:1 row_mask:0xf bank_mask:0xf
	v_mov_b32_e32 v35, v1
	v_pk_mul_f32 v[32:33], v[76:77], v[32:33]
	s_nop 0
	v_mov_b32_dpp v35, v36 row_ror:15 row_mask:0xf bank_mask:0xf
	v_cndmask_b32_e64 v36, v24, v30, s[42:43]
	v_mov_b32_e32 v30, v1
	v_pk_mul_f32 v[34:35], v[72:73], v[34:35]
	v_cndmask_b32_e64 v33, 0, v33, s[62:63]
	v_mov_b32_dpp v30, v36 row_ror:1 row_mask:0xf bank_mask:0xf
	v_mov_b32_e32 v36, v1
	v_cndmask_b32_e64 v32, 0, v32, s[62:63]
	v_cndmask_b32_e64 v35, 0, v35, s[60:61]
	v_mov_b32_dpp v36, v37 row_ror:15 row_mask:0xf bank_mask:0xf
	v_cndmask_b32_e64 v37, v25, v31, s[42:43]
	v_mov_b32_e32 v31, v1
	v_cndmask_b32_e64 v34, 0, v34, s[60:61]
	v_pk_add_f32 v[32:33], v[32:33], v[34:35]
	v_mov_b32_dpp v31, v37 row_ror:1 row_mask:0xf bank_mask:0xf
	v_mov_b32_e32 v37, v1
	v_pk_add_f32 v[22:23], v[22:23], v[32:33] neg_lo:[0,1] neg_hi:[0,1]
	v_pk_mul_f32 v[30:31], v[66:67], v[30:31]
	v_mov_b32_dpp v37, v38 row_ror:15 row_mask:0xf bank_mask:0xf
	v_pk_mul_f32 v[32:33], v[62:63], v[36:37]
	v_cndmask_b32_e64 v31, 0, v31, s[62:63]
	v_cndmask_b32_e64 v30, 0, v30, s[62:63]
	v_cndmask_b32_e64 v33, 0, v33, s[60:61]
	v_cndmask_b32_e64 v32, 0, v32, s[60:61]
	v_pk_add_f32 v[30:31], v[30:31], v[32:33]
	s_nop 0
	v_pk_add_f32 v[26:27], v[26:27], v[30:31] neg_lo:[0,1] neg_hi:[0,1]
	s_branch .LBB0_875
; __device__ __forceinline__ float dpp_ror1(float v) { return __int_as_float(__builtin_amdgcn_update_dpp(0, __float_as_int(v), 0x121, 0xF, 0xF, false)); }
; __device__ __forceinline__ float dpp_ror15(float v) { return __int_as_float(__builtin_amdgcn_update_dpp(0, __float_as_int(v), 0x12F, 0xF, 0xF, false)); }
;     __device__ __forceinline__ void operator()(f32x4 (&acc)[2][2][4][2], const Unit& u, int wr, int wc, int fr, int fq) const {
;     ...
;                         if (__any(lbad | rbad)) {
; #pragma unroll
;                             for (int bj = 0; bj < 2; ++bj) {
;                                 const f32x4 c = acc[ai][bj][m][n], cm = acc[ai][bj][m > 0 ? m - 1 : m][n], cp = acc[ai][bj][m < 3 ? m + 1 : m][n];
; #pragma unroll
;                                 for (int jj = 0; jj < 2; ++jj) {
;                                     const int j = 2 * jh + jj;
;                                     const float up = dpp_ror1(f15 ? cm[j] : c[j]), dn = dpp_ror15(f0 ? cp[j] : c[j]);
;                                     uu[bj][jj] -= (lbad ? w0[bj][jj] * up : 0.f) + (rbad ? w2[bj][jj] * dn : 0.f);
;                                 }
;                             }
.Lconvgate_fix_31:
	v_cndmask_b32_e64 v23, v20, v28, s[42:43]
	v_mov_b32_e32 v22, v1
	v_mov_b32_e32 v26, v1
	v_cndmask_b32_e64 v27, v21, v29, s[42:43]
	v_mov_b32_dpp v22, v23 row_ror:1 row_mask:0xf bank_mask:0xf
	v_cndmask_b32_e64 v23, v20, v8, s[44:45]
	v_cndmask_b32_e64 v28, v21, v9, s[44:45]
	v_cndmask_b32_e64 v29, v12, v4, s[44:45]
	v_mov_b32_dpp v26, v23 row_ror:15 row_mask:0xf bank_mask:0xf
	v_mov_b32_e32 v23, v1
	v_cndmask_b32_e64 v30, v13, v5, s[44:45]
	s_nop 0
	v_mov_b32_dpp v23, v27 row_ror:1 row_mask:0xf bank_mask:0xf
	v_mov_b32_e32 v27, v1
	v_pk_mul_f32 v[22:23], v[76:77], v[22:23]
	s_nop 0
	v_mov_b32_dpp v27, v28 row_ror:15 row_mask:0xf bank_mask:0xf
	v_cndmask_b32_e64 v28, v12, v24, s[42:43]
	v_mov_b32_e32 v24, v1
	v_pk_mul_f32 v[26:27], v[72:73], v[26:27]
	v_cndmask_b32_e64 v23, 0, v23, s[58:59]
	v_mov_b32_dpp v24, v28 row_ror:1 row_mask:0xf bank_mask:0xf
	v_mov_b32_e32 v28, v1
	v_cndmask_b32_e64 v22, 0, v22, s[58:59]
	v_cndmask_b32_e64 v27, 0, v27, s[56:57]
	v_mov_b32_dpp v28, v29 row_ror:15 row_mask:0xf bank_mask:0xf
	v_cndmask_b32_e64 v29, v13, v25, s[42:43]
	v_mov_b32_e32 v25, v1
	v_cndmask_b32_e64 v26, 0, v26, s[56:57]
	v_pk_add_f32 v[22:23], v[22:23], v[26:27]
	v_mov_b32_dpp v25, v29 row_ror:1 row_mask:0xf bank_mask:0xf
	v_mov_b32_e32 v29, v1
	v_pk_add_f32 v[10:11], v[10:11], v[22:23] neg_lo:[0,1] neg_hi:[0,1]
	v_pk_mul_f32 v[22:23], v[66:67], v[24:25]
	v_mov_b32_dpp v29, v30 row_ror:15 row_mask:0xf bank_mask:0xf
	v_pk_mul_f32 v[24:25], v[62:63], v[28:29]
	v_cndmask_b32_e64 v23, 0, v23, s[58:59]
	v_cndmask_b32_e64 v22, 0, v22, s[58:59]
	v_cndmask_b32_e64 v25, 0, v25, s[56:57]
	v_cndmask_b32_e64 v24, 0, v24, s[56:57]
	v_pk_add_f32 v[22:23], v[22:23], v[24:25]
	s_nop 0
	v_pk_add_f32 v[18:19], v[18:19], v[22:23] neg_lo:[0,1] neg_hi:[0,1]
	s_branch .LBB0_879
.Lconvgate_fix_32:
	v_cndmask_b32_e64 v3, v8, v20, s[42:43]
	v_mov_b32_e32 v2, v1
	v_cndmask_b32_e64 v7, v9, v21, s[42:43]
	v_mov_b32_e32 v6, v1
	v_mov_b32_dpp v2, v3 row_ror:1 row_mask:0xf bank_mask:0xf
	v_mov_b32_e32 v3, v1
	v_mov_b32_dpp v6, v8 row_ror:15 row_mask:0xf bank_mask:0xf
	v_mov_b32_e32 v8, v1
	v_mov_b32_dpp v3, v7 row_ror:1 row_mask:0xf bank_mask:0xf
	v_mov_b32_e32 v7, v1
	v_mov_b32_e32 v10, v1
	v_mov_b32_e32 v11, v1
	v_mov_b32_dpp v7, v9 row_ror:15 row_mask:0xf bank_mask:0xf
	v_cndmask_b32_e64 v9, v4, v12, s[42:43]
	v_mov_b32_dpp v10, v4 row_ror:15 row_mask:0xf bank_mask:0xf
	v_cndmask_b32_e64 v4, v5, v13, s[42:43]
	v_mov_b32_dpp v8, v9 row_ror:1 row_mask:0xf bank_mask:0xf
	v_mov_b32_e32 v9, v1
	v_mov_b32_dpp v11, v5 row_ror:15 row_mask:0xf bank_mask:0xf
	v_pk_mul_f32 v[2:3], v[76:77], v[2:3]
	v_mov_b32_dpp v9, v4 row_ror:1 row_mask:0xf bank_mask:0xf
	v_pk_mul_f32 v[4:5], v[72:73], v[6:7]
	v_cndmask_b32_e64 v3, 0, v3, s[54:55]
	v_cndmask_b32_e64 v2, 0, v2, s[54:55]
	v_cndmask_b32_e64 v5, 0, v5, s[52:53]
	v_cndmask_b32_e64 v4, 0, v4, s[52:53]
	v_pk_add_f32 v[2:3], v[2:3], v[4:5]
	v_pk_mul_f32 v[4:5], v[62:63], v[10:11]
	v_pk_add_f32 v[54:55], v[54:55], v[2:3] neg_lo:[0,1] neg_hi:[0,1]
	v_pk_mul_f32 v[2:3], v[66:67], v[8:9]
	v_cndmask_b32_e64 v5, 0, v5, s[52:53]
	v_cndmask_b32_e64 v3, 0, v3, s[54:55]
	v_cndmask_b32_e64 v2, 0, v2, s[54:55]
	v_cndmask_b32_e64 v4, 0, v4, s[52:53]
	v_pk_add_f32 v[2:3], v[2:3], v[4:5]
	s_nop 0
	v_pk_add_f32 v[58:59], v[58:59], v[2:3] neg_lo:[0,1] neg_hi:[0,1]
	s_branch .LBB0_883
